# v12 + spatial epilogue stores widened to dwordx4 (permlane swaps) + K-loop back-edge rotation + attention O stores write-through
# speedup vs baseline: 1.0214x; 1.0073x over previous
; #define PG8_STAGE(bufoff, gbase, voff) do { _Pragma("unroll") for (int _i = 0; _i < 2; ++_i) \
;         __builtin_amdgcn_global_load_lds((const unsigned*)((const char*)(gbase) + (voff)[_i]), (PG8_LAS unsigned*)(lds + (bufoff) + ldsw + _i * 8192), 16, 0, 0); } while (0)
; #define PG8_LDA(dst, b, h) do { _Pragma("unroll") for (int m = 0; m < 4; ++m) _Pragma("unroll") for (int k = 0; k < 2; ++k) dst[m][k] = *(const PG8_LAS bf16x8*)(lds + PG8_SA(b, h) + aoff + m * 2048 + k * 1024); } while (0)
; #define PG8_LDB(dst, b, h) do { _Pragma("unroll") for (int n = 0; n < 2; ++n) _Pragma("unroll") for (int k = 0; k < 2; ++k) dst[n][k] = *(const PG8_LAS bf16x8*)(lds + PG8_SB(b, h) + boff + n * 2048 + k * 1024); } while (0)
; #define PG8_MMA(ai, bj, At, Bt) do { __builtin_amdgcn_s_setprio(1); _Pragma("unroll") for (int m = 0; m < 4; ++m) _Pragma("unroll") for (int n = 0; n < 2; ++n) _Pragma("unroll") for (int k = 0; k < 2; ++k) \
;         acc[ai][bj][m][n] = __builtin_amdgcn_mfma_f32_16x16x32_bf16(Bt[n][k], At[m][k], acc[ai][bj][m][n], 0, 0, 0); __builtin_amdgcn_s_setprio(0); } while (0)
; #define PG8_WAIT_V(n) asm volatile("s_waitcnt vmcnt(" #n ")" ::: "memory")
; #define PG8_WAIT_L(n) asm volatile("s_waitcnt lgkmcnt(" #n ")" ::: "memory")
; template <class Epi, class Sched, bool ALIGN_EPI = false, bool SP2 = false>
; __device__ __forceinline__ void gemm_phase(PG8_LAS unsigned char* lds, const Gemm g, const Sched& S, const Epi& E, const int tid_in) {
;     ...
;             const bool last = (t == nt - 2);
;             const char* a1 = cA + (size_t)(t + 1) * kstep;
;             const char* a2 = last ? nA : cA + (size_t)(t + 2) * kstep; const char* b2 = last ? nB : cB + (size_t)(t + 2) * kstep;
;             const char* a3 = a2 + kstep; const char* b3 = b2 + kstep;
;             if (last && has_next) S.a_ready(nxt);
;             if constexpr (SP2) {
;             PG8_LDB(B0, 0, 0); PG8_LDB(B1, 0, 1); PG8_SCHED; PG8_LDA(At, 0, 0); PG8_STAGE(PG8_SA(1, 1), a1 + hstepA, voffA);
;             PG8_WAIT_V(8); PG8_WAIT_L(0); PG8_BAR; PG8_MMA(0, 0, At, B0); PG8_MMA(0, 1, At, B1); PG8_BAR; PG8_SCHED;
;             PG8_LDA(At, 0, 1); PG8_STAGE(PG8_SB(0, 0), b2, voffB); PG8_STAGE(PG8_SB(0, 1), b2 + hstepB, voffB); PG8_STAGE(PG8_SA(0, 0), a2, voffA);
;             PG8_WAIT_V(8); PG8_WAIT_L(0); PG8_BAR; PG8_MMA(1, 0, At, B0); PG8_MMA(1, 1, At, B1); PG8_BAR; PG8_SCHED;
.LBB0_224:
	s_add_u32 s4, s0, 0xfffc0080
	s_addc_u32 s5, s1, -1
	s_add_i32 s76, 0, 0x10000
	s_cmp_eq_u32 s75, 12
	s_cselect_b32 s21, s57, s5
	s_cselect_b32 s20, s71, s4
	v_add_u32_e32 v114, s76, v171
	s_cselect_b32 s5, s55, s74
	s_cselect_b32 s4, s72, s73
	s_add_i32 s78, 0, 0x14000
	ds_read_b128 v[132:135], v114
	ds_read_b128 v[136:139], v114 offset:1024
	ds_read_b128 v[140:143], v114 offset:2048
	s_waitcnt lgkmcnt(0)
	ds_read_b128 v[154:157], v114 offset:3072
	v_add_u32_e32 v114, s78, v171
	ds_read_b128 v[158:161], v114
	ds_read_b128 v[162:165], v114 offset:1024
	ds_read_b128 v[166:169], v114 offset:2048
	ds_read_b128 v[200:203], v114 offset:3072
	v_lshl_add_u64 v[230:231], s[0:1], 0, v[150:151]
	s_add_i32 m0, s28, 0xc000
	ds_read_b128 v[204:207], v197
	ds_read_b128 v[208:211], v197 offset:1024
	ds_read_b128 v[212:215], v197 offset:2048
	ds_read_b128 v[216:219], v197 offset:3072
	ds_read_b128 v[220:223], v197 offset:4096
	ds_read_b128 v[224:227], v197 offset:5120
	ds_read_b128 v[238:241], v197 offset:6144
	ds_read_b128 v[242:245], v197 offset:7168
	global_load_lds_dwordx4 v[230:231], off
	v_lshl_add_u64 v[230:231], s[0:1], 0, v[152:153]
	s_add_i32 m0, s28, 0xe000
	s_nop 0
	global_load_lds_dwordx4 v[230:231], off
	s_waitcnt vmcnt(8)
	s_waitcnt lgkmcnt(0)
	s_barrier
	s_setprio 1
	s_waitcnt lgkmcnt(0)
	v_mfma_f32_16x16x32_bf16 v[128:131], v[132:135], v[204:207], v[128:131]
	v_mfma_f32_16x16x32_bf16 v[124:127], v[140:143], v[204:207], v[124:127]
	v_mfma_f32_16x16x32_bf16 v[108:111], v[132:135], v[212:215], v[108:111]
	v_mfma_f32_16x16x32_bf16 v[104:107], v[140:143], v[212:215], v[104:107]
	v_mfma_f32_16x16x32_bf16 v[92:95], v[132:135], v[220:223], v[92:95]
	v_mfma_f32_16x16x32_bf16 v[88:91], v[140:143], v[220:223], v[88:91]
	v_mfma_f32_16x16x32_bf16 v[76:79], v[132:135], v[238:241], v[76:79]
	v_mfma_f32_16x16x32_bf16 v[72:75], v[140:143], v[238:241], v[72:75]
	v_mfma_f32_16x16x32_bf16 v[128:131], v[136:139], v[208:211], v[128:131]
	v_mfma_f32_16x16x32_bf16 v[124:127], v[154:157], v[208:211], v[124:127]
	v_mfma_f32_16x16x32_bf16 v[108:111], v[136:139], v[216:219], v[108:111]
	v_mfma_f32_16x16x32_bf16 v[104:107], v[154:157], v[216:219], v[104:107]
	v_mfma_f32_16x16x32_bf16 v[92:95], v[136:139], v[224:227], v[92:95]
	v_mfma_f32_16x16x32_bf16 v[88:91], v[154:157], v[224:227], v[88:91]
	v_mfma_f32_16x16x32_bf16 v[76:79], v[136:139], v[242:245], v[76:79]
	v_mfma_f32_16x16x32_bf16 v[72:75], v[154:157], v[242:245], v[72:75]
	s_setprio 0
	s_setprio 1
	v_mfma_f32_16x16x32_bf16 v[120:123], v[158:161], v[204:207], v[120:123]
	v_mfma_f32_16x16x32_bf16 v[116:119], v[166:169], v[204:207], v[116:119]
	v_mfma_f32_16x16x32_bf16 v[100:103], v[158:161], v[212:215], v[100:103]
	v_mfma_f32_16x16x32_bf16 v[96:99], v[166:169], v[212:215], v[96:99]
	v_mfma_f32_16x16x32_bf16 v[84:87], v[158:161], v[220:223], v[84:87]
	v_mfma_f32_16x16x32_bf16 v[80:83], v[166:169], v[220:223], v[80:83]
	v_mfma_f32_16x16x32_bf16 v[68:71], v[158:161], v[238:241], v[68:71]
	v_mfma_f32_16x16x32_bf16 v[64:67], v[166:169], v[238:241], v[64:67]
	v_mfma_f32_16x16x32_bf16 v[120:123], v[162:165], v[208:211], v[120:123]
	v_mfma_f32_16x16x32_bf16 v[116:119], v[200:203], v[208:211], v[116:119]
	v_mfma_f32_16x16x32_bf16 v[100:103], v[162:165], v[216:219], v[100:103]
	v_mfma_f32_16x16x32_bf16 v[96:99], v[200:203], v[216:219], v[96:99]
	v_mfma_f32_16x16x32_bf16 v[84:87], v[162:165], v[224:227], v[84:87]
	v_mfma_f32_16x16x32_bf16 v[80:83], v[200:203], v[224:227], v[80:83]
	v_mfma_f32_16x16x32_bf16 v[68:71], v[162:165], v[242:245], v[68:71]
	v_mfma_f32_16x16x32_bf16 v[64:67], v[200:203], v[242:245], v[64:67]
	s_setprio 0
	s_barrier
	s_add_i32 s76, s76, s19
	v_lshl_add_u64 v[230:231], s[4:5], 0, v[144:145]
	s_mov_b32 m0, s76
	ds_read_b128 v[204:207], v197 offset:16384
	ds_read_b128 v[208:211], v197 offset:17408
	ds_read_b128 v[212:215], v197 offset:18432
	ds_read_b128 v[216:219], v197 offset:19456
	ds_read_b128 v[220:223], v197 offset:20480
	ds_read_b128 v[224:227], v197 offset:21504
	ds_read_b128 v[238:241], v197 offset:22528
	ds_read_b128 v[242:245], v197 offset:23552
	global_load_lds_dwordx4 v[230:231], off
	s_add_i32 m0, s76, 0x2000
	s_add_u32 s76, s4, 0x40000
	v_lshl_add_u64 v[234:235], s[4:5], 0, v[148:149]
	s_addc_u32 s77, s5, 0
	s_add_i32 s78, s78, s19
	global_load_lds_dwordx4 v[234:235], off
	v_lshl_add_u64 v[246:247], s[76:77], 0, v[144:145]
	s_mov_b32 m0, s78
	v_lshl_add_u64 v[248:249], s[20:21], 0, v[146:147]
	global_load_lds_dwordx4 v[246:247], off
	v_lshl_add_u64 v[246:247], s[76:77], 0, v[148:149]
	s_add_i32 m0, s78, 0x2000
	s_nop 0
	global_load_lds_dwordx4 v[246:247], off
	v_lshl_add_u64 v[246:247], s[20:21], 0, v[112:113]
	s_mov_b32 m0, s28
	s_nop 0
	global_load_lds_dwordx4 v[246:247], off
	s_mov_b32 m0, s29
	s_nop 0
	global_load_lds_dwordx4 v[248:249], off
	s_waitcnt vmcnt(8)
	s_waitcnt lgkmcnt(0)
	s_barrier
; #define PG8_STAGE(bufoff, gbase, voff) do { _Pragma("unroll") for (int _i = 0; _i < 2; ++_i) \
;         __builtin_amdgcn_global_load_lds((const unsigned*)((const char*)(gbase) + (voff)[_i]), (PG8_LAS unsigned*)(lds + (bufoff) + ldsw + _i * 8192), 16, 0, 0); } while (0)
; #define PG8_LDA(dst, b, h) do { _Pragma("unroll") for (int m = 0; m < 4; ++m) _Pragma("unroll") for (int k = 0; k < 2; ++k) dst[m][k] = *(const PG8_LAS bf16x8*)(lds + PG8_SA(b, h) + aoff + m * 2048 + k * 1024); } while (0)
; #define PG8_LDB(dst, b, h) do { _Pragma("unroll") for (int n = 0; n < 2; ++n) _Pragma("unroll") for (int k = 0; k < 2; ++k) dst[n][k] = *(const PG8_LAS bf16x8*)(lds + PG8_SB(b, h) + boff + n * 2048 + k * 1024); } while (0)
; #define PG8_MMA(ai, bj, At, Bt) do { __builtin_amdgcn_s_setprio(1); _Pragma("unroll") for (int m = 0; m < 4; ++m) _Pragma("unroll") for (int n = 0; n < 2; ++n) _Pragma("unroll") for (int k = 0; k < 2; ++k) \
;         acc[ai][bj][m][n] = __builtin_amdgcn_mfma_f32_16x16x32_bf16(Bt[n][k], At[m][k], acc[ai][bj][m][n], 0, 0, 0); __builtin_amdgcn_s_setprio(0); } while (0)
; #define PG8_WAIT_V(n) asm volatile("s_waitcnt vmcnt(" #n ")" ::: "memory")
; #define PG8_WAIT_L(n) asm volatile("s_waitcnt lgkmcnt(" #n ")" ::: "memory")
; #define PG8_BAR __builtin_amdgcn_s_barrier()
; #define PG8_SCHED __builtin_amdgcn_sched_barrier(0)
; template <class Epi, class Sched, bool ALIGN_EPI = false, bool SP2 = false>
; __device__ __forceinline__ void gemm_phase(PG8_LAS unsigned char* lds, const Gemm g, const Sched& S, const Epi& E, const int tid_in) {
;     ...
;             PG8_WAIT_V(8); PG8_WAIT_L(0); PG8_BAR; PG8_MMA(1, 0, At, B0); PG8_MMA(1, 1, At, B1); PG8_BAR; PG8_SCHED;
;             PG8_LDB(B0, 1, 0); PG8_LDB(B1, 1, 1); PG8_SCHED; PG8_LDA(At, 1, 0); PG8_STAGE(PG8_SA(0, 1), a2 + hstepA, voffA);
;             PG8_WAIT_V(8); PG8_WAIT_L(0); PG8_BAR; PG8_MMA(0, 0, At, B0); PG8_MMA(0, 1, At, B1); PG8_BAR; PG8_SCHED;
	s_setprio 1
	s_waitcnt lgkmcnt(0)
	v_mfma_f32_16x16x32_bf16 v[60:63], v[132:135], v[204:207], v[60:63]
	v_mfma_f32_16x16x32_bf16 v[56:59], v[140:143], v[204:207], v[56:59]
	v_mfma_f32_16x16x32_bf16 v[44:47], v[132:135], v[212:215], v[44:47]
	v_mfma_f32_16x16x32_bf16 v[40:43], v[140:143], v[212:215], v[40:43]
	v_mfma_f32_16x16x32_bf16 v[28:31], v[132:135], v[220:223], v[28:31]
	v_mfma_f32_16x16x32_bf16 v[24:27], v[140:143], v[220:223], v[24:27]
	v_mfma_f32_16x16x32_bf16 v[12:15], v[132:135], v[238:241], v[12:15]
	v_mfma_f32_16x16x32_bf16 v[8:11], v[140:143], v[238:241], v[8:11]
	v_mfma_f32_16x16x32_bf16 v[60:63], v[136:139], v[208:211], v[60:63]
	v_mfma_f32_16x16x32_bf16 v[56:59], v[154:157], v[208:211], v[56:59]
	v_mfma_f32_16x16x32_bf16 v[44:47], v[136:139], v[216:219], v[44:47]
	v_mfma_f32_16x16x32_bf16 v[40:43], v[154:157], v[216:219], v[40:43]
	v_mfma_f32_16x16x32_bf16 v[28:31], v[136:139], v[224:227], v[28:31]
	v_mfma_f32_16x16x32_bf16 v[24:27], v[154:157], v[224:227], v[24:27]
	v_mfma_f32_16x16x32_bf16 v[12:15], v[136:139], v[242:245], v[12:15]
	v_mfma_f32_16x16x32_bf16 v[8:11], v[154:157], v[242:245], v[8:11]
	s_setprio 0
	s_setprio 1
	v_mfma_f32_16x16x32_bf16 v[52:55], v[158:161], v[204:207], v[52:55]
	v_mfma_f32_16x16x32_bf16 v[48:51], v[166:169], v[204:207], v[48:51]
	v_mfma_f32_16x16x32_bf16 v[36:39], v[158:161], v[212:215], v[36:39]
	v_mfma_f32_16x16x32_bf16 v[32:35], v[166:169], v[212:215], v[32:35]
	v_mfma_f32_16x16x32_bf16 v[20:23], v[158:161], v[220:223], v[20:23]
	v_mfma_f32_16x16x32_bf16 v[16:19], v[166:169], v[220:223], v[16:19]
	v_mfma_f32_16x16x32_bf16 v[4:7], v[158:161], v[238:241], v[4:7]
	v_mfma_f32_16x16x32_bf16 v[0:3], v[166:169], v[238:241], v[0:3]
	v_mfma_f32_16x16x32_bf16 v[52:55], v[162:165], v[208:211], v[52:55]
	v_mfma_f32_16x16x32_bf16 v[48:51], v[200:203], v[208:211], v[48:51]
	v_mfma_f32_16x16x32_bf16 v[36:39], v[162:165], v[216:219], v[36:39]
	v_mfma_f32_16x16x32_bf16 v[32:35], v[200:203], v[216:219], v[32:35]
	v_mfma_f32_16x16x32_bf16 v[20:23], v[162:165], v[224:227], v[20:23]
	v_mfma_f32_16x16x32_bf16 v[16:19], v[200:203], v[224:227], v[16:19]
	v_mfma_f32_16x16x32_bf16 v[4:7], v[162:165], v[242:245], v[4:7]
	v_mfma_f32_16x16x32_bf16 v[0:3], v[200:203], v[242:245], v[0:3]
	s_setprio 0
	s_barrier
	s_add_i32 s76, 0, 0x18000
	v_add_u32_e32 v114, s76, v171
	s_add_i32 s77, 0, 0x1c000
	ds_read_b128 v[132:135], v114
	ds_read_b128 v[136:139], v114 offset:1024
	ds_read_b128 v[140:143], v114 offset:2048
	ds_read_b128 v[154:157], v114 offset:3072
	v_add_u32_e32 v114, s77, v171
	ds_read_b128 v[158:161], v114
	ds_read_b128 v[162:165], v114 offset:1024
	ds_read_b128 v[166:169], v114 offset:2048
	ds_read_b128 v[200:203], v114 offset:3072
	s_add_u32 s20, s20, 0x40000
	s_addc_u32 s21, s21, 0
	s_mov_b32 m0, s62
	v_lshl_add_u64 v[250:251], s[20:21], 0, v[112:113]
	ds_read_b128 v[204:207], v197 offset:32768
	ds_read_b128 v[208:211], v197 offset:33792
	ds_read_b128 v[212:215], v197 offset:34816
	ds_read_b128 v[216:219], v197 offset:35840
	ds_read_b128 v[220:223], v197 offset:36864
	ds_read_b128 v[224:227], v197 offset:37888
	ds_read_b128 v[238:241], v197 offset:38912
	ds_read_b128 v[242:245], v197 offset:39936
	global_load_lds_dwordx4 v[250:251], off
	v_lshl_add_u64 v[250:251], s[20:21], 0, v[146:147]
	s_mov_b32 m0, s63
	s_nop 0
	global_load_lds_dwordx4 v[250:251], off
	s_waitcnt vmcnt(8)
	s_waitcnt lgkmcnt(0)
	s_barrier
	s_setprio 1
	s_waitcnt lgkmcnt(0)
	v_mfma_f32_16x16x32_bf16 v[128:131], v[132:135], v[204:207], v[128:131]
	v_mfma_f32_16x16x32_bf16 v[124:127], v[140:143], v[204:207], v[124:127]
	v_mfma_f32_16x16x32_bf16 v[108:111], v[132:135], v[212:215], v[108:111]
	v_mfma_f32_16x16x32_bf16 v[104:107], v[140:143], v[212:215], v[104:107]
	v_mfma_f32_16x16x32_bf16 v[92:95], v[132:135], v[220:223], v[92:95]
	v_mfma_f32_16x16x32_bf16 v[88:91], v[140:143], v[220:223], v[88:91]
	v_mfma_f32_16x16x32_bf16 v[76:79], v[132:135], v[238:241], v[76:79]
	v_mfma_f32_16x16x32_bf16 v[72:75], v[140:143], v[238:241], v[72:75]
	v_mfma_f32_16x16x32_bf16 v[128:131], v[136:139], v[208:211], v[128:131]
	v_mfma_f32_16x16x32_bf16 v[124:127], v[154:157], v[208:211], v[124:127]
	v_mfma_f32_16x16x32_bf16 v[108:111], v[136:139], v[216:219], v[108:111]
	v_mfma_f32_16x16x32_bf16 v[104:107], v[154:157], v[216:219], v[104:107]
	v_mfma_f32_16x16x32_bf16 v[92:95], v[136:139], v[224:227], v[92:95]
	v_mfma_f32_16x16x32_bf16 v[88:91], v[154:157], v[224:227], v[88:91]
	v_mfma_f32_16x16x32_bf16 v[76:79], v[136:139], v[242:245], v[76:79]
	v_mfma_f32_16x16x32_bf16 v[72:75], v[154:157], v[242:245], v[72:75]
	s_setprio 0
	s_setprio 1
	v_mfma_f32_16x16x32_bf16 v[120:123], v[158:161], v[204:207], v[120:123]
	v_mfma_f32_16x16x32_bf16 v[116:119], v[166:169], v[204:207], v[116:119]
	v_mfma_f32_16x16x32_bf16 v[100:103], v[158:161], v[212:215], v[100:103]
	v_mfma_f32_16x16x32_bf16 v[96:99], v[166:169], v[212:215], v[96:99]
	v_mfma_f32_16x16x32_bf16 v[84:87], v[158:161], v[220:223], v[84:87]
	v_mfma_f32_16x16x32_bf16 v[80:83], v[166:169], v[220:223], v[80:83]
	v_mfma_f32_16x16x32_bf16 v[68:71], v[158:161], v[238:241], v[68:71]
	v_mfma_f32_16x16x32_bf16 v[64:67], v[166:169], v[238:241], v[64:67]
	v_mfma_f32_16x16x32_bf16 v[120:123], v[162:165], v[208:211], v[120:123]
	v_mfma_f32_16x16x32_bf16 v[116:119], v[200:203], v[208:211], v[116:119]
	v_mfma_f32_16x16x32_bf16 v[100:103], v[162:165], v[216:219], v[100:103]
	v_mfma_f32_16x16x32_bf16 v[96:99], v[200:203], v[216:219], v[96:99]
	v_mfma_f32_16x16x32_bf16 v[84:87], v[162:165], v[224:227], v[84:87]
	v_mfma_f32_16x16x32_bf16 v[80:83], v[200:203], v[224:227], v[80:83]
	v_mfma_f32_16x16x32_bf16 v[68:71], v[162:165], v[242:245], v[68:71]
	v_mfma_f32_16x16x32_bf16 v[64:67], v[200:203], v[242:245], v[64:67]
	s_setprio 0
	s_barrier
; #define PG8_STAGE(bufoff, gbase, voff) do { _Pragma("unroll") for (int _i = 0; _i < 2; ++_i) \
;         __builtin_amdgcn_global_load_lds((const unsigned*)((const char*)(gbase) + (voff)[_i]), (PG8_LAS unsigned*)(lds + (bufoff) + ldsw + _i * 8192), 16, 0, 0); } while (0)
; #define PG8_LDA(dst, b, h) do { _Pragma("unroll") for (int m = 0; m < 4; ++m) _Pragma("unroll") for (int k = 0; k < 2; ++k) dst[m][k] = *(const PG8_LAS bf16x8*)(lds + PG8_SA(b, h) + aoff + m * 2048 + k * 1024); } while (0)
; #define PG8_MMA(ai, bj, At, Bt) do { __builtin_amdgcn_s_setprio(1); _Pragma("unroll") for (int m = 0; m < 4; ++m) _Pragma("unroll") for (int n = 0; n < 2; ++n) _Pragma("unroll") for (int k = 0; k < 2; ++k) \
;         acc[ai][bj][m][n] = __builtin_amdgcn_mfma_f32_16x16x32_bf16(Bt[n][k], At[m][k], acc[ai][bj][m][n], 0, 0, 0); __builtin_amdgcn_s_setprio(0); } while (0)
; #define PG8_WAIT_V(n) asm volatile("s_waitcnt vmcnt(" #n ")" ::: "memory")
; #define PG8_WAIT_L(n) asm volatile("s_waitcnt lgkmcnt(" #n ")" ::: "memory")
; #define PG8_BAR __builtin_amdgcn_s_barrier()
; #define PG8_SCHED __builtin_amdgcn_sched_barrier(0)
; template <class Epi, class Sched, bool ALIGN_EPI = false, bool SP2 = false>
; __device__ __forceinline__ void gemm_phase(PG8_LAS unsigned char* lds, const Gemm g, const Sched& S, const Epi& E, const int tid_in) {
;     ...
;             PG8_LDA(At, 1, 1); PG8_STAGE(PG8_SB(1, 0), b3, voffB); PG8_STAGE(PG8_SB(1, 1), b3 + hstepB, voffB); PG8_STAGE(PG8_SA(1, 0), a3, voffA);
;             PG8_WAIT_V(8); PG8_WAIT_L(0); PG8_BAR; PG8_MMA(1, 0, At, B0); PG8_MMA(1, 1, At, B1); PG8_BAR; PG8_SCHED;
	s_add_i32 s20, s76, s19
	v_lshl_add_u64 v[230:231], v[230:231], 0, s[10:11]
	s_mov_b32 m0, s20
	ds_read_b128 v[204:207], v197 offset:49152
	ds_read_b128 v[208:211], v197 offset:50176
	ds_read_b128 v[212:215], v197 offset:51200
	ds_read_b128 v[216:219], v197 offset:52224
	ds_read_b128 v[220:223], v197 offset:53248
	ds_read_b128 v[224:227], v197 offset:54272
	ds_read_b128 v[238:241], v197 offset:55296
	ds_read_b128 v[242:245], v197 offset:56320
	global_load_lds_dwordx4 v[230:231], off
	s_add_i32 m0, s20, 0x2000
	s_add_u32 s4, s4, 0x40080
	v_lshl_add_u64 v[230:231], v[234:235], 0, s[10:11]
	s_addc_u32 s5, s5, 0
	s_add_i32 s20, s77, s19
	global_load_lds_dwordx4 v[230:231], off
	v_lshl_add_u64 v[230:231], s[4:5], 0, v[144:145]
	s_mov_b32 m0, s20
	s_nop 0
	global_load_lds_dwordx4 v[230:231], off
	v_lshl_add_u64 v[230:231], s[4:5], 0, v[148:149]
	s_add_i32 m0, s20, 0x2000
	s_nop 0
	global_load_lds_dwordx4 v[230:231], off
	v_lshl_add_u64 v[230:231], v[246:247], 0, s[10:11]
	s_mov_b32 m0, s64
	s_nop 0
	global_load_lds_dwordx4 v[230:231], off
	v_lshl_add_u64 v[230:231], v[248:249], 0, s[10:11]
	s_mov_b32 m0, s65
	s_nop 0
	global_load_lds_dwordx4 v[230:231], off
	s_waitcnt vmcnt(8)
	s_waitcnt lgkmcnt(0)
	s_barrier
	s_setprio 1
	s_waitcnt lgkmcnt(0)
	v_mfma_f32_16x16x32_bf16 v[60:63], v[132:135], v[204:207], v[60:63]
	v_mfma_f32_16x16x32_bf16 v[56:59], v[140:143], v[204:207], v[56:59]
	v_mfma_f32_16x16x32_bf16 v[44:47], v[132:135], v[212:215], v[44:47]
	v_mfma_f32_16x16x32_bf16 v[40:43], v[140:143], v[212:215], v[40:43]
	v_mfma_f32_16x16x32_bf16 v[28:31], v[132:135], v[220:223], v[28:31]
	v_mfma_f32_16x16x32_bf16 v[24:27], v[140:143], v[220:223], v[24:27]
	v_mfma_f32_16x16x32_bf16 v[12:15], v[132:135], v[238:241], v[12:15]
	v_mfma_f32_16x16x32_bf16 v[8:11], v[140:143], v[238:241], v[8:11]
	v_mfma_f32_16x16x32_bf16 v[60:63], v[136:139], v[208:211], v[60:63]
	v_mfma_f32_16x16x32_bf16 v[56:59], v[154:157], v[208:211], v[56:59]
	v_mfma_f32_16x16x32_bf16 v[44:47], v[136:139], v[216:219], v[44:47]
	v_mfma_f32_16x16x32_bf16 v[40:43], v[154:157], v[216:219], v[40:43]
	v_mfma_f32_16x16x32_bf16 v[28:31], v[136:139], v[224:227], v[28:31]
	v_mfma_f32_16x16x32_bf16 v[24:27], v[154:157], v[224:227], v[24:27]
	v_mfma_f32_16x16x32_bf16 v[12:15], v[136:139], v[242:245], v[12:15]
	v_mfma_f32_16x16x32_bf16 v[8:11], v[154:157], v[242:245], v[8:11]
	s_setprio 0
	s_setprio 1
	v_mfma_f32_16x16x32_bf16 v[52:55], v[158:161], v[204:207], v[52:55]
	v_mfma_f32_16x16x32_bf16 v[48:51], v[166:169], v[204:207], v[48:51]
	v_mfma_f32_16x16x32_bf16 v[36:39], v[158:161], v[212:215], v[36:39]
	v_mfma_f32_16x16x32_bf16 v[32:35], v[166:169], v[212:215], v[32:35]
	v_mfma_f32_16x16x32_bf16 v[20:23], v[158:161], v[220:223], v[20:23]
	v_mfma_f32_16x16x32_bf16 v[16:19], v[166:169], v[220:223], v[16:19]
	v_mfma_f32_16x16x32_bf16 v[4:7], v[158:161], v[238:241], v[4:7]
	v_mfma_f32_16x16x32_bf16 v[0:3], v[166:169], v[238:241], v[0:3]
	v_mfma_f32_16x16x32_bf16 v[52:55], v[162:165], v[208:211], v[52:55]
	v_mfma_f32_16x16x32_bf16 v[48:51], v[200:203], v[208:211], v[48:51]
	v_mfma_f32_16x16x32_bf16 v[36:39], v[162:165], v[216:219], v[36:39]
	v_mfma_f32_16x16x32_bf16 v[32:35], v[200:203], v[216:219], v[32:35]
	v_mfma_f32_16x16x32_bf16 v[20:23], v[162:165], v[224:227], v[20:23]
	v_mfma_f32_16x16x32_bf16 v[16:19], v[200:203], v[224:227], v[16:19]
	v_mfma_f32_16x16x32_bf16 v[4:7], v[162:165], v[242:245], v[4:7]
	v_mfma_f32_16x16x32_bf16 v[0:3], v[200:203], v[242:245], v[0:3]
	s_setprio 0
	s_add_i32 s75, s75, 2
	s_add_u32 s0, s0, 0x100
	s_addc_u32 s1, s1, 0
	s_add_u32 s73, s73, 0x100
	s_addc_u32 s74, s74, 0
	s_cmp_gt_u32 s75, 13
	s_barrier
	s_cbranch_scc0 .LBB0_224
	s_and_b64 vcc, exec, s[50:51]
	s_cbranch_vccz .LBB0_227
	s_barrier

; #define PG8_STAGE(bufoff, gbase, voff) do { _Pragma("unroll") for (int _i = 0; _i < 2; ++_i) \
;         __builtin_amdgcn_global_load_lds((const unsigned*)((const char*)(gbase) + (voff)[_i]), (PG8_LAS unsigned*)(lds + (bufoff) + ldsw + _i * 8192), 16, 0, 0); } while (0)
; #define PG8_LDA(dst, b, h) do { _Pragma("unroll") for (int m = 0; m < 4; ++m) _Pragma("unroll") for (int k = 0; k < 2; ++k) dst[m][k] = *(const PG8_LAS bf16x8*)(lds + PG8_SA(b, h) + aoff + m * 2048 + k * 1024); } while (0)
; #define PG8_MMA(ai, bj, At, Bt) do { __builtin_amdgcn_s_setprio(1); _Pragma("unroll") for (int m = 0; m < 4; ++m) _Pragma("unroll") for (int n = 0; n < 2; ++n) _Pragma("unroll") for (int k = 0; k < 2; ++k) \
;         acc[ai][bj][m][n] = __builtin_amdgcn_mfma_f32_16x16x32_bf16(Bt[n][k], At[m][k], acc[ai][bj][m][n], 0, 0, 0); __builtin_amdgcn_s_setprio(0); } while (0)
; #define PG8_WAIT_V(n) asm volatile("s_waitcnt vmcnt(" #n ")" ::: "memory")
; #define PG8_WAIT_L(n) asm volatile("s_waitcnt lgkmcnt(" #n ")" ::: "memory")
; #define PG8_BAR __builtin_amdgcn_s_barrier()
; #define PG8_SCHED __builtin_amdgcn_sched_barrier(0)
; template <class Epi, class Sched, bool ALIGN_EPI = false, bool SP2 = false>
; __device__ __forceinline__ void gemm_phase(PG8_LAS unsigned char* lds, const Gemm g, const Sched& S, const Epi& E, const int tid_in) {
;     ...
;             PG8_WAIT_V(8); PG8_WAIT_L(0); PG8_BAR; PG8_MMA(0, 0, At, B0); PG8_MMA(0, 1, At, B1); PG8_BAR; PG8_SCHED;
;             PG8_LDA(At, 1, 1); PG8_STAGE(PG8_SB(1, 0), b3, voffB); PG8_STAGE(PG8_SB(1, 1), b3 + hstepB, voffB); PG8_STAGE(PG8_SA(1, 0), a3, voffA);
;             PG8_WAIT_V(8); PG8_WAIT_L(0); PG8_BAR; PG8_MMA(1, 0, At, B0); PG8_MMA(1, 1, At, B1); PG8_BAR; PG8_SCHED;
.Ltl_foxout_15_j:
	s_waitcnt vmcnt(8)
	s_waitcnt lgkmcnt(0)
	s_barrier
	s_setprio 1
	s_waitcnt lgkmcnt(0)
	v_mfma_f32_16x16x32_bf16 v[64:67], v[152:155], v[184:187], v[64:67]
	v_mfma_f32_16x16x32_bf16 v[68:71], v[160:163], v[184:187], v[68:71]
	v_mfma_f32_16x16x32_bf16 v[80:83], v[152:155], v[192:195], v[80:83]
	v_mfma_f32_16x16x32_bf16 v[84:87], v[160:163], v[192:195], v[84:87]
	v_mfma_f32_16x16x32_bf16 v[96:99], v[152:155], v[200:203], v[96:99]
	v_mfma_f32_16x16x32_bf16 v[100:103], v[160:163], v[200:203], v[100:103]
	v_mfma_f32_16x16x32_bf16 v[116:119], v[152:155], v[208:211], v[116:119]
	v_mfma_f32_16x16x32_bf16 v[120:123], v[160:163], v[208:211], v[120:123]
	v_mfma_f32_16x16x32_bf16 v[64:67], v[156:159], v[188:191], v[64:67]
	v_mfma_f32_16x16x32_bf16 v[68:71], v[164:167], v[188:191], v[68:71]
	v_mfma_f32_16x16x32_bf16 v[80:83], v[156:159], v[196:199], v[80:83]
	v_mfma_f32_16x16x32_bf16 v[84:87], v[164:167], v[196:199], v[84:87]
	v_mfma_f32_16x16x32_bf16 v[96:99], v[156:159], v[204:207], v[96:99]
	v_mfma_f32_16x16x32_bf16 v[100:103], v[164:167], v[204:207], v[100:103]
	v_mfma_f32_16x16x32_bf16 v[116:119], v[156:159], v[212:215], v[116:119]
	v_mfma_f32_16x16x32_bf16 v[120:123], v[164:167], v[212:215], v[120:123]
	s_setprio 0
	s_setprio 1
	v_mfma_f32_16x16x32_bf16 v[72:75], v[168:171], v[184:187], v[72:75]
	v_mfma_f32_16x16x32_bf16 v[76:79], v[176:179], v[184:187], v[76:79]
	v_mfma_f32_16x16x32_bf16 v[88:91], v[168:171], v[192:195], v[88:91]
	v_mfma_f32_16x16x32_bf16 v[92:95], v[176:179], v[192:195], v[92:95]
	v_mfma_f32_16x16x32_bf16 v[104:107], v[168:171], v[200:203], v[104:107]
	v_mfma_f32_16x16x32_bf16 v[108:111], v[176:179], v[200:203], v[108:111]
	v_mfma_f32_16x16x32_bf16 v[124:127], v[168:171], v[208:211], v[124:127]
	v_mfma_f32_16x16x32_bf16 v[128:131], v[176:179], v[208:211], v[128:131]
	v_mfma_f32_16x16x32_bf16 v[72:75], v[172:175], v[188:191], v[72:75]
	v_mfma_f32_16x16x32_bf16 v[76:79], v[180:183], v[188:191], v[76:79]
	v_mfma_f32_16x16x32_bf16 v[88:91], v[172:175], v[196:199], v[88:91]
	v_mfma_f32_16x16x32_bf16 v[92:95], v[180:183], v[196:199], v[92:95]
	v_mfma_f32_16x16x32_bf16 v[104:107], v[172:175], v[204:207], v[104:107]
	v_mfma_f32_16x16x32_bf16 v[108:111], v[180:183], v[204:207], v[108:111]
	v_mfma_f32_16x16x32_bf16 v[124:127], v[172:175], v[212:215], v[124:127]
	v_mfma_f32_16x16x32_bf16 v[128:131], v[180:183], v[212:215], v[128:131]
	s_setprio 0
	s_add_i32 s29, s29, 2
	s_add_u32 s40, s40, 0x100
	s_addc_u32 s41, s41, 0
	s_cmp_gt_u32 s29, 13
	s_barrier
	s_cbranch_scc0 .LBB0_508
	s_and_b64 vcc, exec, s[26:27]
	s_cbranch_vccz .LBB0_511
	s_barrier

; #define PG8_STAGE(bufoff, gbase, voff) do { _Pragma("unroll") for (int _i = 0; _i < 2; ++_i) \
;         __builtin_amdgcn_global_load_lds((const unsigned*)((const char*)(gbase) + (voff)[_i]), (PG8_LAS unsigned*)(lds + (bufoff) + ldsw + _i * 8192), 16, 0, 0); } while (0)
; #define PG8_LDA(dst, b, h) do { _Pragma("unroll") for (int m = 0; m < 4; ++m) _Pragma("unroll") for (int k = 0; k < 2; ++k) dst[m][k] = *(const PG8_LAS bf16x8*)(lds + PG8_SA(b, h) + aoff + m * 2048 + k * 1024); } while (0)
; #define PG8_LDB(dst, b, h) do { _Pragma("unroll") for (int n = 0; n < 2; ++n) _Pragma("unroll") for (int k = 0; k < 2; ++k) dst[n][k] = *(const PG8_LAS bf16x8*)(lds + PG8_SB(b, h) + boff + n * 2048 + k * 1024); } while (0)
; #define PG8_MMA(ai, bj, At, Bt) do { __builtin_amdgcn_s_setprio(1); _Pragma("unroll") for (int m = 0; m < 4; ++m) _Pragma("unroll") for (int n = 0; n < 2; ++n) _Pragma("unroll") for (int k = 0; k < 2; ++k) \
;         acc[ai][bj][m][n] = __builtin_amdgcn_mfma_f32_16x16x32_bf16(Bt[n][k], At[m][k], acc[ai][bj][m][n], 0, 0, 0); __builtin_amdgcn_s_setprio(0); } while (0)
; #define PG8_WAIT_V(n) asm volatile("s_waitcnt vmcnt(" #n ")" ::: "memory")
; #define PG8_WAIT_L(n) asm volatile("s_waitcnt lgkmcnt(" #n ")" ::: "memory")
; template <class Epi, class Sched, bool ALIGN_EPI = false, bool SP2 = false>
; __device__ __forceinline__ void gemm_phase(PG8_LAS unsigned char* lds, const Gemm g, const Sched& S, const Epi& E, const int tid_in) {
;     ...
;             const bool last = (t == nt - 2);
;             const char* a1 = cA + (size_t)(t + 1) * kstep;
;             const char* a2 = last ? nA : cA + (size_t)(t + 2) * kstep; const char* b2 = last ? nB : cB + (size_t)(t + 2) * kstep;
;             const char* a3 = a2 + kstep; const char* b3 = b2 + kstep;
;             if (last && has_next) S.a_ready(nxt);
;             if constexpr (SP2) {
;             PG8_LDB(B0, 0, 0); PG8_LDB(B1, 0, 1); PG8_SCHED; PG8_LDA(At, 0, 0); PG8_STAGE(PG8_SA(1, 1), a1 + hstepA, voffA);
;             PG8_WAIT_V(8); PG8_WAIT_L(0); PG8_BAR; PG8_MMA(0, 0, At, B0); PG8_MMA(0, 1, At, B1); PG8_BAR; PG8_SCHED;
;             PG8_LDA(At, 0, 1); PG8_STAGE(PG8_SB(0, 0), b2, voffB); PG8_STAGE(PG8_SB(0, 1), b2 + hstepB, voffB); PG8_STAGE(PG8_SA(0, 0), a2, voffA);
;             PG8_WAIT_V(8); PG8_WAIT_L(0); PG8_BAR; PG8_MMA(1, 0, At, B0); PG8_MMA(1, 1, At, B1); PG8_BAR; PG8_SCHED;
.LBB0_613:
	s_add_u32 s4, s0, 0xfffc0080
	s_addc_u32 s5, s1, -1
	s_add_i32 s66, 0, 0x10000
	s_cmp_eq_u32 s65, 12
	s_cselect_b32 s21, s53, s5
	s_cselect_b32 s20, s61, s4
	s_cselect_b32 s5, s51, s64
	s_cselect_b32 s4, s62, s63
	s_add_i32 s70, 0, 0x14000
	v_add_u32_e32 v144, s66, v176
	v_add_u32_e32 v168, s70, v176
	ds_read_b128 v[132:135], v144
	ds_read_b128 v[136:139], v144 offset:1024
	ds_read_b128 v[140:143], v144 offset:2048
	ds_read_b128 v[144:147], v144 offset:3072
	ds_read_b128 v[148:151], v168
	ds_read_b128 v[152:155], v168 offset:1024
	ds_read_b128 v[164:167], v168 offset:2048
	ds_read_b128 v[168:171], v168 offset:3072
	v_lshl_add_u64 v[174:175], s[0:1], 0, v[160:161]
	s_add_i32 m0, s26, 0xc000
	ds_read_b128 v[180:183], v179
	ds_read_b128 v[184:187], v179 offset:1024
	ds_read_b128 v[188:191], v179 offset:2048
	ds_read_b128 v[192:195], v179 offset:3072
	ds_read_b128 v[196:199], v179 offset:4096
	ds_read_b128 v[204:207], v179 offset:5120
	ds_read_b128 v[208:211], v179 offset:6144
	ds_read_b128 v[212:215], v179 offset:7168
	global_load_lds_dwordx4 v[174:175], off
	v_lshl_add_u64 v[174:175], s[0:1], 0, v[162:163]
	s_add_i32 m0, s26, 0xe000
	s_nop 0
	global_load_lds_dwordx4 v[174:175], off
	s_waitcnt vmcnt(8)
	s_waitcnt lgkmcnt(0)
	s_barrier
	s_setprio 1
	s_waitcnt lgkmcnt(0)
	v_mfma_f32_16x16x32_bf16 v[128:131], v[132:135], v[180:183], v[128:131]
	v_mfma_f32_16x16x32_bf16 v[124:127], v[140:143], v[180:183], v[124:127]
	v_mfma_f32_16x16x32_bf16 v[108:111], v[132:135], v[188:191], v[108:111]
	v_mfma_f32_16x16x32_bf16 v[104:107], v[140:143], v[188:191], v[104:107]
	v_mfma_f32_16x16x32_bf16 v[92:95], v[132:135], v[196:199], v[92:95]
	v_mfma_f32_16x16x32_bf16 v[88:91], v[140:143], v[196:199], v[88:91]
	v_mfma_f32_16x16x32_bf16 v[76:79], v[132:135], v[208:211], v[76:79]
	v_mfma_f32_16x16x32_bf16 v[72:75], v[140:143], v[208:211], v[72:75]
	v_mfma_f32_16x16x32_bf16 v[128:131], v[136:139], v[184:187], v[128:131]
	v_mfma_f32_16x16x32_bf16 v[124:127], v[144:147], v[184:187], v[124:127]
	v_mfma_f32_16x16x32_bf16 v[108:111], v[136:139], v[192:195], v[108:111]
	v_mfma_f32_16x16x32_bf16 v[104:107], v[144:147], v[192:195], v[104:107]
	v_mfma_f32_16x16x32_bf16 v[92:95], v[136:139], v[204:207], v[92:95]
	v_mfma_f32_16x16x32_bf16 v[88:91], v[144:147], v[204:207], v[88:91]
	v_mfma_f32_16x16x32_bf16 v[76:79], v[136:139], v[212:215], v[76:79]
	v_mfma_f32_16x16x32_bf16 v[72:75], v[144:147], v[212:215], v[72:75]
	s_setprio 0
	s_setprio 1
	v_mfma_f32_16x16x32_bf16 v[120:123], v[148:151], v[180:183], v[120:123]
	v_mfma_f32_16x16x32_bf16 v[116:119], v[164:167], v[180:183], v[116:119]
	v_mfma_f32_16x16x32_bf16 v[100:103], v[148:151], v[188:191], v[100:103]
	v_mfma_f32_16x16x32_bf16 v[96:99], v[164:167], v[188:191], v[96:99]
	v_mfma_f32_16x16x32_bf16 v[84:87], v[148:151], v[196:199], v[84:87]
	v_mfma_f32_16x16x32_bf16 v[80:83], v[164:167], v[196:199], v[80:83]
	v_mfma_f32_16x16x32_bf16 v[68:71], v[148:151], v[208:211], v[68:71]
	v_mfma_f32_16x16x32_bf16 v[64:67], v[164:167], v[208:211], v[64:67]
	v_mfma_f32_16x16x32_bf16 v[120:123], v[152:155], v[184:187], v[120:123]
	v_mfma_f32_16x16x32_bf16 v[116:119], v[168:171], v[184:187], v[116:119]
	v_mfma_f32_16x16x32_bf16 v[100:103], v[152:155], v[192:195], v[100:103]
	v_mfma_f32_16x16x32_bf16 v[96:99], v[168:171], v[192:195], v[96:99]
	v_mfma_f32_16x16x32_bf16 v[84:87], v[152:155], v[204:207], v[84:87]
	v_mfma_f32_16x16x32_bf16 v[80:83], v[168:171], v[204:207], v[80:83]
	v_mfma_f32_16x16x32_bf16 v[68:71], v[152:155], v[212:215], v[68:71]
	v_mfma_f32_16x16x32_bf16 v[64:67], v[168:171], v[212:215], v[64:67]
	s_setprio 0
	s_barrier
	s_add_i32 s66, s66, s13
	v_lshl_add_u64 v[174:175], s[4:5], 0, v[114:115]
	s_mov_b32 m0, s66
	ds_read_b128 v[180:183], v179 offset:16384
	ds_read_b128 v[184:187], v179 offset:17408
	ds_read_b128 v[188:191], v179 offset:18432
	ds_read_b128 v[192:195], v179 offset:19456
	ds_read_b128 v[196:199], v179 offset:20480
	ds_read_b128 v[204:207], v179 offset:21504
	ds_read_b128 v[208:211], v179 offset:22528
	ds_read_b128 v[212:215], v179 offset:23552
	global_load_lds_dwordx4 v[174:175], off
	s_add_i32 m0, s66, 0x2000
	s_add_u32 s66, s4, 0x40000
	v_lshl_add_u64 v[200:201], s[4:5], 0, v[158:159]
	s_addc_u32 s67, s5, 0
	s_add_i32 s70, s70, s13
	global_load_lds_dwordx4 v[200:201], off
	v_lshl_add_u64 v[202:203], s[66:67], 0, v[114:115]
	s_mov_b32 m0, s70
	v_lshl_add_u64 v[216:217], s[20:21], 0, v[156:157]
	global_load_lds_dwordx4 v[202:203], off
	v_lshl_add_u64 v[202:203], s[66:67], 0, v[158:159]
	s_add_i32 m0, s70, 0x2000
	s_nop 0
	global_load_lds_dwordx4 v[202:203], off
	v_lshl_add_u64 v[202:203], s[20:21], 0, v[112:113]
	s_mov_b32 m0, s26
	s_nop 0
	global_load_lds_dwordx4 v[202:203], off
	s_mov_b32 m0, s27
	s_nop 0
	global_load_lds_dwordx4 v[216:217], off
	s_waitcnt vmcnt(8)
	s_waitcnt lgkmcnt(0)
	s_barrier
; #define PG8_STAGE(bufoff, gbase, voff) do { _Pragma("unroll") for (int _i = 0; _i < 2; ++_i) \
;         __builtin_amdgcn_global_load_lds((const unsigned*)((const char*)(gbase) + (voff)[_i]), (PG8_LAS unsigned*)(lds + (bufoff) + ldsw + _i * 8192), 16, 0, 0); } while (0)
; #define PG8_LDA(dst, b, h) do { _Pragma("unroll") for (int m = 0; m < 4; ++m) _Pragma("unroll") for (int k = 0; k < 2; ++k) dst[m][k] = *(const PG8_LAS bf16x8*)(lds + PG8_SA(b, h) + aoff + m * 2048 + k * 1024); } while (0)
; #define PG8_LDB(dst, b, h) do { _Pragma("unroll") for (int n = 0; n < 2; ++n) _Pragma("unroll") for (int k = 0; k < 2; ++k) dst[n][k] = *(const PG8_LAS bf16x8*)(lds + PG8_SB(b, h) + boff + n * 2048 + k * 1024); } while (0)
; #define PG8_MMA(ai, bj, At, Bt) do { __builtin_amdgcn_s_setprio(1); _Pragma("unroll") for (int m = 0; m < 4; ++m) _Pragma("unroll") for (int n = 0; n < 2; ++n) _Pragma("unroll") for (int k = 0; k < 2; ++k) \
;         acc[ai][bj][m][n] = __builtin_amdgcn_mfma_f32_16x16x32_bf16(Bt[n][k], At[m][k], acc[ai][bj][m][n], 0, 0, 0); __builtin_amdgcn_s_setprio(0); } while (0)
; #define PG8_WAIT_V(n) asm volatile("s_waitcnt vmcnt(" #n ")" ::: "memory")
; #define PG8_WAIT_L(n) asm volatile("s_waitcnt lgkmcnt(" #n ")" ::: "memory")
; #define PG8_BAR __builtin_amdgcn_s_barrier()
; #define PG8_SCHED __builtin_amdgcn_sched_barrier(0)
; template <class Epi, class Sched, bool ALIGN_EPI = false, bool SP2 = false>
; __device__ __forceinline__ void gemm_phase(PG8_LAS unsigned char* lds, const Gemm g, const Sched& S, const Epi& E, const int tid_in) {
;     ...
;             PG8_WAIT_V(8); PG8_WAIT_L(0); PG8_BAR; PG8_MMA(1, 0, At, B0); PG8_MMA(1, 1, At, B1); PG8_BAR; PG8_SCHED;
;             PG8_LDB(B0, 1, 0); PG8_LDB(B1, 1, 1); PG8_SCHED; PG8_LDA(At, 1, 0); PG8_STAGE(PG8_SA(0, 1), a2 + hstepA, voffA);
;             PG8_WAIT_V(8); PG8_WAIT_L(0); PG8_BAR; PG8_MMA(0, 0, At, B0); PG8_MMA(0, 1, At, B1); PG8_BAR; PG8_SCHED;
	s_setprio 1
	s_waitcnt lgkmcnt(0)
	v_mfma_f32_16x16x32_bf16 v[60:63], v[132:135], v[180:183], v[60:63]
	v_mfma_f32_16x16x32_bf16 v[56:59], v[140:143], v[180:183], v[56:59]
	v_mfma_f32_16x16x32_bf16 v[44:47], v[132:135], v[188:191], v[44:47]
	v_mfma_f32_16x16x32_bf16 v[40:43], v[140:143], v[188:191], v[40:43]
	v_mfma_f32_16x16x32_bf16 v[28:31], v[132:135], v[196:199], v[28:31]
	v_mfma_f32_16x16x32_bf16 v[24:27], v[140:143], v[196:199], v[24:27]
	v_mfma_f32_16x16x32_bf16 v[12:15], v[132:135], v[208:211], v[12:15]
	v_mfma_f32_16x16x32_bf16 v[8:11], v[140:143], v[208:211], v[8:11]
	v_mfma_f32_16x16x32_bf16 v[60:63], v[136:139], v[184:187], v[60:63]
	v_mfma_f32_16x16x32_bf16 v[56:59], v[144:147], v[184:187], v[56:59]
	v_mfma_f32_16x16x32_bf16 v[44:47], v[136:139], v[192:195], v[44:47]
	v_mfma_f32_16x16x32_bf16 v[40:43], v[144:147], v[192:195], v[40:43]
	v_mfma_f32_16x16x32_bf16 v[28:31], v[136:139], v[204:207], v[28:31]
	v_mfma_f32_16x16x32_bf16 v[24:27], v[144:147], v[204:207], v[24:27]
	v_mfma_f32_16x16x32_bf16 v[12:15], v[136:139], v[212:215], v[12:15]
	v_mfma_f32_16x16x32_bf16 v[8:11], v[144:147], v[212:215], v[8:11]
	s_setprio 0
	s_setprio 1
	v_mfma_f32_16x16x32_bf16 v[52:55], v[148:151], v[180:183], v[52:55]
	v_mfma_f32_16x16x32_bf16 v[48:51], v[164:167], v[180:183], v[48:51]
	v_mfma_f32_16x16x32_bf16 v[36:39], v[148:151], v[188:191], v[36:39]
	v_mfma_f32_16x16x32_bf16 v[32:35], v[164:167], v[188:191], v[32:35]
	v_mfma_f32_16x16x32_bf16 v[20:23], v[148:151], v[196:199], v[20:23]
	v_mfma_f32_16x16x32_bf16 v[16:19], v[164:167], v[196:199], v[16:19]
	v_mfma_f32_16x16x32_bf16 v[4:7], v[148:151], v[208:211], v[4:7]
	v_mfma_f32_16x16x32_bf16 v[0:3], v[164:167], v[208:211], v[0:3]
	v_mfma_f32_16x16x32_bf16 v[52:55], v[152:155], v[184:187], v[52:55]
	v_mfma_f32_16x16x32_bf16 v[48:51], v[168:171], v[184:187], v[48:51]
	v_mfma_f32_16x16x32_bf16 v[36:39], v[152:155], v[192:195], v[36:39]
	v_mfma_f32_16x16x32_bf16 v[32:35], v[168:171], v[192:195], v[32:35]
	v_mfma_f32_16x16x32_bf16 v[20:23], v[152:155], v[204:207], v[20:23]
	v_mfma_f32_16x16x32_bf16 v[16:19], v[168:171], v[204:207], v[16:19]
	v_mfma_f32_16x16x32_bf16 v[4:7], v[152:155], v[212:215], v[4:7]
	v_mfma_f32_16x16x32_bf16 v[0:3], v[168:171], v[212:215], v[0:3]
	s_setprio 0
	s_barrier
	s_add_i32 s66, 0, 0x18000
	s_add_i32 s67, 0, 0x1c000
	v_add_u32_e32 v144, s66, v176
	v_add_u32_e32 v168, s67, v176
	ds_read_b128 v[132:135], v144
	ds_read_b128 v[136:139], v144 offset:1024
	ds_read_b128 v[140:143], v144 offset:2048
	ds_read_b128 v[144:147], v144 offset:3072
	ds_read_b128 v[148:151], v168
	ds_read_b128 v[152:155], v168 offset:1024
	ds_read_b128 v[164:167], v168 offset:2048
	ds_read_b128 v[168:171], v168 offset:3072
	s_add_u32 s20, s20, 0x40000
	s_addc_u32 s21, s21, 0
	s_mov_b32 m0, s28
	v_lshl_add_u64 v[218:219], s[20:21], 0, v[112:113]
	ds_read_b128 v[180:183], v179 offset:32768
	ds_read_b128 v[184:187], v179 offset:33792
	ds_read_b128 v[188:191], v179 offset:34816
	ds_read_b128 v[192:195], v179 offset:35840
	ds_read_b128 v[196:199], v179 offset:36864
	ds_read_b128 v[204:207], v179 offset:37888
	ds_read_b128 v[208:211], v179 offset:38912
	ds_read_b128 v[212:215], v179 offset:39936
	global_load_lds_dwordx4 v[218:219], off
	v_lshl_add_u64 v[218:219], s[20:21], 0, v[156:157]
	s_mov_b32 m0, s29
	s_nop 0
	global_load_lds_dwordx4 v[218:219], off
	s_waitcnt vmcnt(8)
	s_waitcnt lgkmcnt(0)
	s_barrier
	s_setprio 1
	s_waitcnt lgkmcnt(0)
	v_mfma_f32_16x16x32_bf16 v[128:131], v[132:135], v[180:183], v[128:131]
	v_mfma_f32_16x16x32_bf16 v[124:127], v[140:143], v[180:183], v[124:127]
	v_mfma_f32_16x16x32_bf16 v[108:111], v[132:135], v[188:191], v[108:111]
	v_mfma_f32_16x16x32_bf16 v[104:107], v[140:143], v[188:191], v[104:107]
	v_mfma_f32_16x16x32_bf16 v[92:95], v[132:135], v[196:199], v[92:95]
	v_mfma_f32_16x16x32_bf16 v[88:91], v[140:143], v[196:199], v[88:91]
	v_mfma_f32_16x16x32_bf16 v[76:79], v[132:135], v[208:211], v[76:79]
	v_mfma_f32_16x16x32_bf16 v[72:75], v[140:143], v[208:211], v[72:75]
	v_mfma_f32_16x16x32_bf16 v[128:131], v[136:139], v[184:187], v[128:131]
	v_mfma_f32_16x16x32_bf16 v[124:127], v[144:147], v[184:187], v[124:127]
	v_mfma_f32_16x16x32_bf16 v[108:111], v[136:139], v[192:195], v[108:111]
	v_mfma_f32_16x16x32_bf16 v[104:107], v[144:147], v[192:195], v[104:107]
	v_mfma_f32_16x16x32_bf16 v[92:95], v[136:139], v[204:207], v[92:95]
	v_mfma_f32_16x16x32_bf16 v[88:91], v[144:147], v[204:207], v[88:91]
	v_mfma_f32_16x16x32_bf16 v[76:79], v[136:139], v[212:215], v[76:79]
	v_mfma_f32_16x16x32_bf16 v[72:75], v[144:147], v[212:215], v[72:75]
	s_setprio 0
	s_setprio 1
	v_mfma_f32_16x16x32_bf16 v[120:123], v[148:151], v[180:183], v[120:123]
	v_mfma_f32_16x16x32_bf16 v[116:119], v[164:167], v[180:183], v[116:119]
	v_mfma_f32_16x16x32_bf16 v[100:103], v[148:151], v[188:191], v[100:103]
	v_mfma_f32_16x16x32_bf16 v[96:99], v[164:167], v[188:191], v[96:99]
	v_mfma_f32_16x16x32_bf16 v[84:87], v[148:151], v[196:199], v[84:87]
	v_mfma_f32_16x16x32_bf16 v[80:83], v[164:167], v[196:199], v[80:83]
	v_mfma_f32_16x16x32_bf16 v[68:71], v[148:151], v[208:211], v[68:71]
	v_mfma_f32_16x16x32_bf16 v[64:67], v[164:167], v[208:211], v[64:67]
	v_mfma_f32_16x16x32_bf16 v[120:123], v[152:155], v[184:187], v[120:123]
	v_mfma_f32_16x16x32_bf16 v[116:119], v[168:171], v[184:187], v[116:119]
	v_mfma_f32_16x16x32_bf16 v[100:103], v[152:155], v[192:195], v[100:103]
	v_mfma_f32_16x16x32_bf16 v[96:99], v[168:171], v[192:195], v[96:99]
	v_mfma_f32_16x16x32_bf16 v[84:87], v[152:155], v[204:207], v[84:87]
	v_mfma_f32_16x16x32_bf16 v[80:83], v[168:171], v[204:207], v[80:83]
	v_mfma_f32_16x16x32_bf16 v[68:71], v[152:155], v[212:215], v[68:71]
	v_mfma_f32_16x16x32_bf16 v[64:67], v[168:171], v[212:215], v[64:67]
	s_setprio 0
	s_barrier
; #define PG8_STAGE(bufoff, gbase, voff) do { _Pragma("unroll") for (int _i = 0; _i < 2; ++_i) \
;         __builtin_amdgcn_global_load_lds((const unsigned*)((const char*)(gbase) + (voff)[_i]), (PG8_LAS unsigned*)(lds + (bufoff) + ldsw + _i * 8192), 16, 0, 0); } while (0)
; #define PG8_LDA(dst, b, h) do { _Pragma("unroll") for (int m = 0; m < 4; ++m) _Pragma("unroll") for (int k = 0; k < 2; ++k) dst[m][k] = *(const PG8_LAS bf16x8*)(lds + PG8_SA(b, h) + aoff + m * 2048 + k * 1024); } while (0)
; #define PG8_MMA(ai, bj, At, Bt) do { __builtin_amdgcn_s_setprio(1); _Pragma("unroll") for (int m = 0; m < 4; ++m) _Pragma("unroll") for (int n = 0; n < 2; ++n) _Pragma("unroll") for (int k = 0; k < 2; ++k) \
;         acc[ai][bj][m][n] = __builtin_amdgcn_mfma_f32_16x16x32_bf16(Bt[n][k], At[m][k], acc[ai][bj][m][n], 0, 0, 0); __builtin_amdgcn_s_setprio(0); } while (0)
; #define PG8_WAIT_V(n) asm volatile("s_waitcnt vmcnt(" #n ")" ::: "memory")
; #define PG8_WAIT_L(n) asm volatile("s_waitcnt lgkmcnt(" #n ")" ::: "memory")
; #define PG8_BAR __builtin_amdgcn_s_barrier()
; #define PG8_SCHED __builtin_amdgcn_sched_barrier(0)
; template <class Epi, class Sched, bool ALIGN_EPI = false, bool SP2 = false>
; __device__ __forceinline__ void gemm_phase(PG8_LAS unsigned char* lds, const Gemm g, const Sched& S, const Epi& E, const int tid_in) {
;     ...
;             PG8_LDA(At, 1, 1); PG8_STAGE(PG8_SB(1, 0), b3, voffB); PG8_STAGE(PG8_SB(1, 1), b3 + hstepB, voffB); PG8_STAGE(PG8_SA(1, 0), a3, voffA);
;             PG8_WAIT_V(8); PG8_WAIT_L(0); PG8_BAR; PG8_MMA(1, 0, At, B0); PG8_MMA(1, 1, At, B1); PG8_BAR; PG8_SCHED;
	s_add_i32 s20, s66, s13
	v_lshl_add_u64 v[174:175], v[174:175], 0, s[10:11]
	s_mov_b32 m0, s20
	ds_read_b128 v[180:183], v179 offset:49152
	ds_read_b128 v[184:187], v179 offset:50176
	ds_read_b128 v[188:191], v179 offset:51200
	ds_read_b128 v[192:195], v179 offset:52224
	ds_read_b128 v[196:199], v179 offset:53248
	ds_read_b128 v[204:207], v179 offset:54272
	ds_read_b128 v[208:211], v179 offset:55296
	ds_read_b128 v[212:215], v179 offset:56320
	global_load_lds_dwordx4 v[174:175], off
	s_add_i32 m0, s20, 0x2000
	s_add_u32 s4, s4, 0x40080
	v_lshl_add_u64 v[174:175], v[200:201], 0, s[10:11]
	s_addc_u32 s5, s5, 0
	s_add_i32 s20, s67, s13
	global_load_lds_dwordx4 v[174:175], off
	v_lshl_add_u64 v[174:175], s[4:5], 0, v[114:115]
	s_mov_b32 m0, s20
	s_nop 0
	global_load_lds_dwordx4 v[174:175], off
	v_lshl_add_u64 v[174:175], s[4:5], 0, v[158:159]
	s_add_i32 m0, s20, 0x2000
	s_nop 0
	global_load_lds_dwordx4 v[174:175], off
	v_lshl_add_u64 v[174:175], v[202:203], 0, s[10:11]
	s_mov_b32 m0, s58
	s_nop 0
	global_load_lds_dwordx4 v[174:175], off
	v_lshl_add_u64 v[174:175], v[216:217], 0, s[10:11]
	s_mov_b32 m0, s59
	s_nop 0
	global_load_lds_dwordx4 v[174:175], off
	s_waitcnt vmcnt(8)
	s_waitcnt lgkmcnt(0)
	s_barrier
	s_setprio 1
	s_waitcnt lgkmcnt(0)
	v_mfma_f32_16x16x32_bf16 v[60:63], v[132:135], v[180:183], v[60:63]
	v_mfma_f32_16x16x32_bf16 v[56:59], v[140:143], v[180:183], v[56:59]
	v_mfma_f32_16x16x32_bf16 v[44:47], v[132:135], v[188:191], v[44:47]
	v_mfma_f32_16x16x32_bf16 v[40:43], v[140:143], v[188:191], v[40:43]
	v_mfma_f32_16x16x32_bf16 v[28:31], v[132:135], v[196:199], v[28:31]
	v_mfma_f32_16x16x32_bf16 v[24:27], v[140:143], v[196:199], v[24:27]
	v_mfma_f32_16x16x32_bf16 v[12:15], v[132:135], v[208:211], v[12:15]
	v_mfma_f32_16x16x32_bf16 v[8:11], v[140:143], v[208:211], v[8:11]
	v_mfma_f32_16x16x32_bf16 v[60:63], v[136:139], v[184:187], v[60:63]
	v_mfma_f32_16x16x32_bf16 v[56:59], v[144:147], v[184:187], v[56:59]
	v_mfma_f32_16x16x32_bf16 v[44:47], v[136:139], v[192:195], v[44:47]
	v_mfma_f32_16x16x32_bf16 v[40:43], v[144:147], v[192:195], v[40:43]
	v_mfma_f32_16x16x32_bf16 v[28:31], v[136:139], v[204:207], v[28:31]
	v_mfma_f32_16x16x32_bf16 v[24:27], v[144:147], v[204:207], v[24:27]
	v_mfma_f32_16x16x32_bf16 v[12:15], v[136:139], v[212:215], v[12:15]
	v_mfma_f32_16x16x32_bf16 v[8:11], v[144:147], v[212:215], v[8:11]
	s_setprio 0
	s_setprio 1
	v_mfma_f32_16x16x32_bf16 v[52:55], v[148:151], v[180:183], v[52:55]
	v_mfma_f32_16x16x32_bf16 v[48:51], v[164:167], v[180:183], v[48:51]
	v_mfma_f32_16x16x32_bf16 v[36:39], v[148:151], v[188:191], v[36:39]
	v_mfma_f32_16x16x32_bf16 v[32:35], v[164:167], v[188:191], v[32:35]
	v_mfma_f32_16x16x32_bf16 v[20:23], v[148:151], v[196:199], v[20:23]
	v_mfma_f32_16x16x32_bf16 v[16:19], v[164:167], v[196:199], v[16:19]
	v_mfma_f32_16x16x32_bf16 v[4:7], v[148:151], v[208:211], v[4:7]
	v_mfma_f32_16x16x32_bf16 v[0:3], v[164:167], v[208:211], v[0:3]
	v_mfma_f32_16x16x32_bf16 v[52:55], v[152:155], v[184:187], v[52:55]
	v_mfma_f32_16x16x32_bf16 v[48:51], v[168:171], v[184:187], v[48:51]
	v_mfma_f32_16x16x32_bf16 v[36:39], v[152:155], v[192:195], v[36:39]
	v_mfma_f32_16x16x32_bf16 v[32:35], v[168:171], v[192:195], v[32:35]
	v_mfma_f32_16x16x32_bf16 v[20:23], v[152:155], v[204:207], v[20:23]
	v_mfma_f32_16x16x32_bf16 v[16:19], v[168:171], v[204:207], v[16:19]
	v_mfma_f32_16x16x32_bf16 v[4:7], v[152:155], v[212:215], v[4:7]
	v_mfma_f32_16x16x32_bf16 v[0:3], v[168:171], v[212:215], v[0:3]
	s_setprio 0
	s_add_i32 s65, s65, 2
	s_add_u32 s0, s0, 0x100
	s_addc_u32 s1, s1, 0
	s_add_u32 s63, s63, 0x100
	s_addc_u32 s64, s64, 0
	s_cmp_gt_u32 s65, 13
	s_barrier
	s_cbranch_scc0 .LBB0_613
	s_and_b64 vcc, exec, s[18:19]
	s_cbranch_vccz .LBB0_616
	s_barrier

; #define LAS __attribute__((address_space(3)))
; __device__ __forceinline__ unsigned pk2(float lo, float hi) { return f2bf(lo) | (f2bf(hi) << 16); }
; #define ws KWS(F)
; __device__ __forceinline__ void spatial_phase(const Frame& F, bf16* Z, const float* stats, const float* lng, const float* lnb, const float* ws, const float* bs, bool do_store = true) {
;     ...
;     LAS unsigned char* Wl = F.lds; LAS unsigned char* Vt = F.lds + 128 * LST; LAS float* st = (LAS float*)(F.lds + 128 * LST + 256 * LST);
;     const int tid = F.tid, lane = F.lane, w = F.wave, fr = lane & 15, fq = lane >> 4;
;     int staged_g = -1;
;     for (int unit = F.vcu; unit < (M / 128) * 8; unit += F.G) {
;         const int g = unit & 7, chunk = 16 * ((unit >> 5) & 7) + ((unit & 31) >> 3) + 4 * (unit >> 8); const size_t row0 = (size_t)chunk * 128;
;         f32x4 sq[16];
;         if (tid < 128) { const f32x4* sp = (const f32x4*)(stats + (row0 + tid) * 64);
; #pragma unroll
;             for (int i = 0; i < 16; ++i) sq[i] = sp[i]; }
;         const bf16* va = Z + (row0 + 2 * lane) * 4096 + 2048 + 256 * g + 32 * w;
;         v4u rawA[4], rawB[4];
; #pragma unroll
;         for (int it = 0; it < 4; ++it) { rawA[it] = *(const v4u*)(va + 8 * it); rawB[it] = *(const v4u*)(va + 4096 + 8 * it); }
;         v2u uu[8][2];
; #pragma unroll
;         for (int m = 0; m < 8; ++m)
; #pragma unroll
;             for (int n = 0; n < 2; ++n) uu[m][n] = *(const v2u*)(Z + (row0 + 16 * m + fr) * 4096 + 256 * g + 32 * w + 16 * n + 4 * fq);
;         if (tid < 128) { float s1 = 0.f, s2 = 0.f;
; #pragma unroll
;             for (int i = 0; i < 16; ++i) { const f32x4 q = sq[i]; s1 += q.x + q.z; s2 += q.y + q.w; }
;             const float mean = s1 * (1.0f / GE); const float var = fmaxf(s2 * (1.0f / GE) - mean * mean, 0.f);
;             st[2 * tid] = mean; st[2 * tid + 1] = 1.0f / sqrtf(var + LN_EPS); }
;         if (g != staged_g) { staged_g = g; const float* wg = ws + (size_t)g * 128 * 128;
; #pragma unroll
;             for (int i = 0; i < 8; ++i) { const int p = tid + 512 * i, t = p >> 5, s4 = (p & 31) * 4; f32x4 x = *(const f32x4*)(wg + t * 128 + s4);
;                 if (s4 + 0 > t) x.x = 0.f; if (s4 + 1 > t) x.y = 0.f; if (s4 + 2 > t) x.z = 0.f; if (s4 + 3 > t) x.w = 0.f;
;                 *(LAS v2u*)(Wl + t * LST + s4 * 2) = (v2u){pk2(x.x, x.y), pk2(x.z, x.w)}; } }
.LBB0_713:
	s_andn2_b64 vcc, exec, s[0:1]
	s_cbranch_vccnz .LBB0_781
	s_mov_b32 s0, -1
	v_writelane_b32 v255, s86, 9
	v_readlane_b32 s4, v253, 4
	v_readlane_b32 s5, v253, 5
	v_writelane_b32 v255, s94, 10
	s_mov_b32 s47, s96
	s_andn2_b64 vcc, exec, s[4:5]
	v_writelane_b32 v255, s95, 11
	s_cbranch_vccnz .LBB0_725
	v_readlane_b32 s6, v255, 10
	v_readlane_b32 s7, v255, 11
	s_load_dwordx2 s[4:5], s[6:7], 0x88
	s_load_dwordx8 s[88:95], s[6:7], 0x10
	s_waitcnt vmcnt(0)
	v_mbcnt_lo_u32_b32 v0, s0, 0
	v_readlane_b32 s6, v255, 9
	v_mbcnt_hi_u32_b32 v2, s0, v0
	s_waitcnt lgkmcnt(0)
	s_add_u32 s26, s4, 0x9400000
	s_addc_u32 s27, s5, 0
	s_add_u32 s28, s4, 0x100000
	v_readlane_b32 s0, v255, 4
	s_addc_u32 s29, s5, 0
	s_lshl_b32 s48, s6, 11
	v_add_u32_e32 v112, s0, v2
	s_lshl_b64 s[0:1], s[48:49], 2
	s_add_u32 s4, s88, s0
	s_addc_u32 s5, s89, s1
	s_add_u32 s8, s90, s0
	s_addc_u32 s9, s91, s1
	s_lshl_b32 s48, s6, 10
	s_lshl_b64 s[0:1], s[48:49], 2
	s_add_u32 s22, s94, s0
	v_readlane_b32 s12, v254, 20
	s_addc_u32 s23, s95, s1
	s_movk_i32 s0, 0x80
	s_lshl_b32 s18, s12, 1
	v_lshrrev_b32_e32 v0, 2, v2
	v_cmp_gt_i32_e64 s[38:39], s0, v112
	s_add_u32 s0, s26, s18
	v_and_b32_e32 v3, 28, v0
	s_addc_u32 s1, s27, 0
	v_lshlrev_b32_e32 v0, 1, v3
	v_mov_b32_e32 v1, v115
	v_lshl_add_u64 v[134:135], s[0:1], 0, v[0:1]
	v_lshlrev_b32_e32 v0, 2, v2
	v_readlane_b32 s0, v255, 1
	v_and_b32_e32 v132, 15, v2
	v_lshlrev_b32_e32 v114, 1, v2
	v_and_b32_e32 v5, 0x7c, v0
	v_lshl_add_u32 v133, v2, 4, s0
	v_add_u32_e32 v137, 0, v0
	v_and_b32_e32 v0, 0x70, v2
	v_ashrrev_i32_e32 v2, 5, v112
	v_cmp_gt_i32_e64 s[0:1], v5, v2
	v_or_b32_e32 v64, 2, v5
	v_or_b32_e32 v65, 3, v5
	v_writelane_b32 v255, s0, 12
	s_movk_i32 s14, 0x110
	v_lshlrev_b32_e32 v146, 7, v2
	v_writelane_b32 v255, s1, 13
	v_cmp_gt_i32_e64 s[0:1], v64, v2
	v_cmp_lt_i32_e64 s[42:43], v5, v2
	v_mul_lo_u32 v8, v2, s14
	v_writelane_b32 v255, s0, 14
	s_lshl_b32 s48, s6, 17
	v_readlane_b32 s13, v254, 21
	v_writelane_b32 v255, s1, 15
	v_cmp_gt_i32_e64 s[0:1], v65, v2
	v_add_u32_e32 v2, 0x200, v112
	v_ashrrev_i32_e32 v2, 5, v2
	v_lshlrev_b32_e32 v148, 7, v2
	v_cmp_gt_i32_e64 s[24:25], v5, v2
	v_cmp_lt_i32_e64 s[50:51], v5, v2
	v_cmp_gt_i32_e64 s[52:53], v64, v2
	v_cmp_gt_i32_e64 s[54:55], v65, v2
	v_mul_lo_u32 v9, v2, s14
	v_add_u32_e32 v2, 0x400, v112
	v_ashrrev_i32_e32 v2, 5, v2
	v_lshlrev_b32_e32 v150, 7, v2
	v_cmp_gt_i32_e64 s[56:57], v5, v2
	v_cmp_lt_i32_e64 s[58:59], v5, v2
	v_cmp_gt_i32_e64 s[60:61], v64, v2
	v_cmp_gt_i32_e64 s[62:63], v65, v2
	v_mul_lo_u32 v10, v2, s14
	v_add_u32_e32 v2, 0x600, v112
	v_ashrrev_i32_e32 v2, 5, v2
	v_lshlrev_b32_e32 v152, 7, v2
	v_cmp_gt_i32_e64 s[64:65], v5, v2
	v_cmp_lt_i32_e64 s[66:67], v5, v2
	v_cmp_gt_i32_e64 s[40:41], v64, v2
	v_cmp_gt_i32_e64 s[70:71], v65, v2
	v_mul_lo_u32 v11, v2, s14
	v_add_u32_e32 v2, 0x800, v112
	v_ashrrev_i32_e32 v2, 5, v2
	v_writelane_b32 v255, s0, 16
	v_lshlrev_b32_e32 v154, 7, v2
	v_cmp_gt_i32_e64 s[72:73], v5, v2
	v_cmp_lt_i32_e64 s[74:75], v5, v2
	v_cmp_gt_i32_e64 s[76:77], v64, v2
	v_cmp_gt_i32_e64 s[78:79], v65, v2
	v_mul_lo_u32 v12, v2, s14
	v_add_u32_e32 v2, 0xa00, v112
	v_writelane_b32 v255, s1, 17
	v_ashrrev_i32_e32 v2, 5, v2
	s_lshl_b64 s[0:1], s[48:49], 2
	v_lshlrev_b32_e32 v156, 7, v2
	v_cmp_gt_i32_e64 s[80:81], v5, v2
	v_cmp_lt_i32_e64 s[82:83], v5, v2
	v_cmp_gt_i32_e64 s[84:85], v64, v2
	v_cmp_gt_i32_e64 s[86:87], v65, v2
	v_mul_lo_u32 v13, v2, s14
	v_add_u32_e32 v2, 0xc00, v112
	s_add_u32 s6, s92, s0
	v_ashrrev_i32_e32 v2, 5, v2
	s_addc_u32 s7, s93, s1
	s_lshl_b64 s[0:1], s[12:13], 2
	v_lshlrev_b32_e32 v158, 7, v2
	v_cmp_gt_i32_e64 s[88:89], v5, v2
	v_cmp_lt_i32_e64 s[90:91], v5, v2
	v_cmp_gt_i32_e64 s[92:93], v64, v2
	v_cmp_gt_i32_e64 s[94:95], v65, v2
	v_mul_lo_u32 v14, v2, s14
	v_add_u32_e32 v2, 0xe00, v112
	s_add_u32 s20, s4, s0
	v_lshlrev_b32_e32 v4, 3, v112
	v_or_b32_e32 v1, s12, v132
	v_add_u32_e32 v7, 0, v0
	v_add_u32_e32 v0, s12, v3
	v_ashrrev_i32_e32 v66, 5, v2
	s_addc_u32 s21, s5, s1
	v_lshlrev_b32_e32 v2, 2, v5
	v_mov_b32_e32 v3, v115
	v_lshl_add_u32 v6, v5, 1, 0
	v_lshlrev_b32_e32 v160, 7, v66
	s_add_u32 s0, s8, s0
	v_mul_lo_u32 v15, v66, s14
	v_mul_lo_u32 v16, v1, s14
	v_mul_u32_u24_e32 v17, 0x110, v132
	v_ashrrev_i32_e32 v1, 31, v0
	v_lshl_add_u64 v[162:163], s[6:7], 0, v[2:3]
	v_add_u32_e32 v2, 0, v4
	v_ashrrev_i32_e32 v113, 31, v112
	v_or_b32_e32 v136, 48, v132
	v_or_b32_e32 v230, 64, v132
	v_or_b32_e32 v232, 0x50, v132
	v_or_b32_e32 v250, 0x60, v132
	v_or_b32_e32 v202, 0x70, v132
	v_ashrrev_i32_e32 v147, 31, v146
	v_ashrrev_i32_e32 v149, 31, v148
	v_ashrrev_i32_e32 v151, 31, v150
	v_ashrrev_i32_e32 v153, 31, v152
	v_ashrrev_i32_e32 v155, 31, v154
	v_ashrrev_i32_e32 v157, 31, v156
	v_ashrrev_i32_e32 v159, 31, v158
	v_ashrrev_i32_e32 v161, 31, v160
	s_addc_u32 s1, s9, s1
	v_cmp_gt_i32_e64 s[96:97], v5, v66
	v_cmp_lt_i32_e64 s[4:5], v5, v66
	s_mov_b32 s46, -1
	v_add_u32_e32 v231, 0x19800, v2
	v_add_u32_e32 v234, v6, v8
	v_add_u32_e32 v203, v6, v9
	v_add_u32_e32 v235, v6, v10
	v_add_u32_e32 v196, v6, v11
	v_add_u32_e32 v197, v6, v12
	v_add_u32_e32 v198, v6, v13
	v_add_u32_e32 v199, v6, v14
	v_add_u32_e32 v200, v6, v15
	v_add_u32_e32 v201, v7, v16
	v_add_u32_e32 v222, v7, v17
	v_lshlrev_b64 v[164:165], 1, v[0:1]
	v_mbcnt_lo_u32_b32 v0, -1, 0
	v_mbcnt_hi_u32_b32 v0, -1, v0
	v_lshrrev_b32_e32 v0, 4, v0
	v_lshlrev_b32_e32 v0, 3, v0
	v_mov_b32_e32 v1, 0
	v_lshl_add_u64 v[164:165], v[164:165], 0, v[0:1]
	s_mov_b32 s44, s47
	v_cmp_gt_i32_e64 s[6:7], v64, v66
	v_cmp_gt_i32_e64 s[8:9], v65, v66
	s_branch .LBB0_717

; #define LAS __attribute__((address_space(3)))
; __device__ __forceinline__ unsigned pk2(float lo, float hi) { return f2bf(lo) | (f2bf(hi) << 16); }
; __device__ __forceinline__ float bflo(unsigned w) { return __uint_as_float(w << 16); }
; __device__ __forceinline__ float bfhi(unsigned w) { return __uint_as_float(w & 0xffff0000u); }
; __device__ __forceinline__ void spatial_phase(const Frame& F, bf16* Z, const float* stats, const float* lng, const float* lnb, const float* ws, const float* bs, bool do_store = true) {
;     ...
;         {
;             const float meanA = st[4 * lane], rstdA = st[4 * lane + 1], meanB = st[4 * lane + 2], rstdB = st[4 * lane + 3];
; #pragma unroll
;             for (int it = 0; it < 4; ++it) { const int c0 = 32 * w + 8 * it;
;                 const f32x4 ga = *(const f32x4*)(lng + 256 * g + c0), gb = *(const f32x4*)(lng + 256 * g + c0 + 4), ba = *(const f32x4*)(lnb + 256 * g + c0), bb = *(const f32x4*)(lnb + 256 * g + c0 + 4);
;                 const float lg[8] = {ga.x, ga.y, ga.z, ga.w, gb.x, gb.y, gb.z, gb.w}, lb[8] = {ba.x, ba.y, ba.z, ba.w, bb.x, bb.y, bb.z, bb.w};
; #pragma unroll
;                 for (int e = 0; e < 8; ++e) { const unsigned wa = rawA[it][e >> 1], wb = rawB[it][e >> 1]; const float xa = (e & 1) ? bfhi(wa) : bflo(wa), xb = (e & 1) ? bfhi(wb) : bflo(wb);
;                     const float ya = (xa - meanA) * rstdA * lg[e] + lb[e], yb = (xb - meanB) * rstdB * lg[e] + lb[e];
;                     *(LAS unsigned*)(Vt + (c0 + e) * LST + 4 * lane) = pk2(ya, yb); } } }
.LBB0_723:
	s_lshl_b32 s12, s45, 8
	s_lshl_b32 s13, s12, 2
	v_mov_b32_e32 v223, s13
	s_waitcnt lgkmcnt(0)
	s_barrier
	ds_read_b128 v[96:99], v133
	global_load_dwordx4 v[104:107], v223, s[20:21] offset:48
	global_load_dwordx4 v[116:119], v223, s[20:21] offset:32
	global_load_dwordx4 v[124:127], v223, s[20:21] offset:16
	global_load_dwordx4 v[128:131], v223, s[20:21]
	global_load_dwordx4 v[100:103], v223, s[0:1] offset:48
	global_load_dwordx4 v[108:111], v223, s[0:1] offset:32
	global_load_dwordx4 v[120:123], v223, s[0:1] offset:16
	global_load_dwordx4 v[224:227], v223, s[0:1]
	s_waitcnt vmcnt(29)
	v_lshlrev_b32_e32 v138, 16, v88
	s_waitcnt vmcnt(28)
	v_lshlrev_b32_e32 v139, 16, v92
	v_and_b32_e32 v88, 0xffff0000, v88
	s_waitcnt lgkmcnt(0)
	v_sub_f32_e32 v138, v138, v96
	v_mul_f32_e32 v138, v97, v138
	v_sub_f32_e32 v139, v139, v98
	v_and_b32_e32 v92, 0xffff0000, v92
	v_sub_f32_e32 v88, v88, v96
	v_mul_f32_e32 v139, v99, v139
	v_mul_f32_e32 v88, v97, v88
	v_sub_f32_e32 v92, v92, v98
	v_mul_f32_e32 v92, v99, v92
	v_readlane_b32 s13, v254, 22
	v_readlane_b32 s14, v254, 16
	v_readlane_b32 s15, v254, 17
	s_andn2_b64 vcc, exec, s[14:15]
	s_waitcnt vmcnt(0)
	v_fma_f32 v138, v138, v128, v224
	v_fma_f32 v128, v139, v128, v224
	v_bfe_u32 v139, v138, 16, 1
	v_fma_f32 v88, v88, v129, v225
	v_add3_u32 v138, v138, v139, s37
	v_bfe_u32 v139, v128, 16, 1
	v_fma_f32 v92, v92, v129, v225
	v_bfe_u32 v129, v88, 16, 1
	v_lshrrev_b32_e32 v138, 16, v138
	v_add3_u32 v128, v128, v139, s37
	v_add3_u32 v88, v88, v129, s37
	v_bfe_u32 v129, v92, 16, 1
	v_and_or_b32 v138, v128, s68, v138
	v_add_u32_e32 v128, s13, v137
	v_lshrrev_b32_e32 v88, 16, v88
	v_add3_u32 v92, v92, v129, s37
	v_and_or_b32 v88, v92, s68, v88
	v_add_u32_e32 v92, 0x8800, v128
	ds_write2_b32 v92, v138, v88 offset1:68
	v_lshlrev_b32_e32 v88, 16, v89
	v_and_b32_e32 v89, 0xffff0000, v89
	v_lshlrev_b32_e32 v129, 16, v93
	v_sub_f32_e32 v88, v88, v96
	v_and_b32_e32 v93, 0xffff0000, v93
	v_sub_f32_e32 v89, v89, v96
	v_mul_f32_e32 v88, v97, v88
	v_sub_f32_e32 v129, v129, v98
	v_mul_f32_e32 v89, v97, v89
	v_sub_f32_e32 v93, v93, v98
	v_fma_f32 v88, v88, v130, v226
	v_mul_f32_e32 v129, v99, v129
	v_fma_f32 v89, v89, v131, v227
	v_mul_f32_e32 v93, v99, v93
	v_fma_f32 v129, v129, v130, v226
	v_bfe_u32 v130, v88, 16, 1
	v_fmac_f32_e32 v227, v93, v131
	v_bfe_u32 v93, v89, 16, 1
	v_add3_u32 v88, v88, v130, s37
	v_bfe_u32 v130, v129, 16, 1
	v_add3_u32 v89, v89, v93, s37
	v_bfe_u32 v93, v227, 16, 1
	v_lshrrev_b32_e32 v88, 16, v88
	v_add3_u32 v129, v129, v130, s37
	v_lshrrev_b32_e32 v89, 16, v89
	v_add3_u32 v93, v227, v93, s37
	v_and_or_b32 v88, v129, s68, v88
	v_and_or_b32 v89, v93, s68, v89
	ds_write2_b32 v92, v88, v89 offset0:136 offset1:204
	v_lshlrev_b32_e32 v88, 16, v90
	v_lshlrev_b32_e32 v89, 16, v94
	v_sub_f32_e32 v88, v88, v96
	v_mul_f32_e32 v88, v97, v88
	v_sub_f32_e32 v89, v89, v98
	v_fma_f32 v88, v88, v124, v120
	v_mul_f32_e32 v89, v99, v89
	v_fma_f32 v89, v89, v124, v120
	v_bfe_u32 v92, v88, 16, 1
	v_add3_u32 v88, v88, v92, s37
	v_bfe_u32 v92, v89, 16, 1
	v_lshrrev_b32_e32 v88, 16, v88
	v_add3_u32 v89, v89, v92, s37
	v_and_or_b32 v88, v89, s68, v88
	v_and_b32_e32 v89, 0xffff0000, v90
	v_and_b32_e32 v90, 0xffff0000, v94
	v_sub_f32_e32 v89, v89, v96
	v_mul_f32_e32 v89, v97, v89
	v_sub_f32_e32 v90, v90, v98
	v_fma_f32 v89, v89, v125, v121
	v_mul_f32_e32 v90, v99, v90
	v_fma_f32 v90, v90, v125, v121
	v_bfe_u32 v92, v89, 16, 1
	v_add3_u32 v89, v89, v92, s37
	v_bfe_u32 v92, v90, 16, 1
	v_lshrrev_b32_e32 v89, 16, v89
	v_add3_u32 v90, v90, v92, s37
	v_and_or_b32 v89, v90, s68, v89
	v_add_u32_e32 v90, 0x8c00, v128
	ds_write2_b32 v90, v88, v89 offset0:16 offset1:84
	v_lshlrev_b32_e32 v88, 16, v91
	v_lshlrev_b32_e32 v89, 16, v95
	v_sub_f32_e32 v88, v88, v96
	v_mul_f32_e32 v88, v97, v88
	v_sub_f32_e32 v89, v89, v98
	v_fma_f32 v88, v88, v126, v122
	v_mul_f32_e32 v89, v99, v89
	v_fma_f32 v89, v89, v126, v122
	v_bfe_u32 v92, v88, 16, 1
	v_add3_u32 v88, v88, v92, s37
	v_bfe_u32 v92, v89, 16, 1
	v_lshrrev_b32_e32 v88, 16, v88
	v_add3_u32 v89, v89, v92, s37
	v_and_or_b32 v88, v89, s68, v88
	v_and_b32_e32 v89, 0xffff0000, v91
	v_and_b32_e32 v91, 0xffff0000, v95
	v_sub_f32_e32 v89, v89, v96
	v_mul_f32_e32 v89, v97, v89
	v_sub_f32_e32 v91, v91, v98
	v_fma_f32 v89, v89, v127, v123
	v_mul_f32_e32 v91, v99, v91
	v_fmac_f32_e32 v123, v91, v127
	v_bfe_u32 v91, v89, 16, 1
	v_add3_u32 v89, v89, v91, s37
	v_bfe_u32 v91, v123, 16, 1
	v_lshrrev_b32_e32 v89, 16, v89
	v_add3_u32 v91, v123, v91, s37
	v_and_or_b32 v89, v91, s68, v89
	ds_write2_b32 v90, v88, v89 offset0:152 offset1:220
	v_lshlrev_b32_e32 v88, 16, v80
	v_lshlrev_b32_e32 v89, 16, v84
	v_sub_f32_e32 v88, v88, v96
	v_mul_f32_e32 v88, v97, v88
	v_sub_f32_e32 v89, v89, v98
	v_fma_f32 v88, v88, v116, v108
	v_mul_f32_e32 v89, v99, v89
	v_fma_f32 v89, v89, v116, v108
	v_bfe_u32 v90, v88, 16, 1
	v_and_b32_e32 v80, 0xffff0000, v80
	v_add3_u32 v88, v88, v90, s37
	v_bfe_u32 v90, v89, 16, 1
	v_and_b32_e32 v84, 0xffff0000, v84
	v_sub_f32_e32 v80, v80, v96
	v_lshrrev_b32_e32 v88, 16, v88
	v_add3_u32 v89, v89, v90, s37
	v_readlane_b32 s13, v254, 23
	v_mul_f32_e32 v80, v97, v80
	v_sub_f32_e32 v84, v84, v98
	v_and_or_b32 v88, v89, s68, v88
	v_add_u32_e32 v120, s13, v137
	v_fma_f32 v80, v80, v117, v109
	v_mul_f32_e32 v84, v99, v84
	ds_write_b32 v120, v88 offset:34816
	v_fma_f32 v84, v84, v117, v109
	v_bfe_u32 v88, v80, 16, 1
	v_add3_u32 v80, v80, v88, s37
	v_bfe_u32 v88, v84, 16, 1
	v_lshrrev_b32_e32 v80, 16, v80
	v_add3_u32 v84, v84, v88, s37
	v_and_or_b32 v80, v84, s68, v80
	v_lshlrev_b32_e32 v84, 16, v81
	v_lshlrev_b32_e32 v88, 16, v85
	v_sub_f32_e32 v84, v84, v96
	v_mul_f32_e32 v84, v97, v84
; #define LAS __attribute__((address_space(3)))
; __device__ __forceinline__ unsigned pk2(float lo, float hi) { return f2bf(lo) | (f2bf(hi) << 16); }
; __device__ __forceinline__ float bflo(unsigned w) { return __uint_as_float(w << 16); }
; __device__ __forceinline__ float bfhi(unsigned w) { return __uint_as_float(w & 0xffff0000u); }
; __device__ __forceinline__ void spatial_phase(const Frame& F, bf16* Z, const float* stats, const float* lng, const float* lnb, const float* ws, const float* bs, bool do_store = true) {
;     ...
;         {
;             const float meanA = st[4 * lane], rstdA = st[4 * lane + 1], meanB = st[4 * lane + 2], rstdB = st[4 * lane + 3];
; #pragma unroll
;             for (int it = 0; it < 4; ++it) { const int c0 = 32 * w + 8 * it;
;                 const f32x4 ga = *(const f32x4*)(lng + 256 * g + c0), gb = *(const f32x4*)(lng + 256 * g + c0 + 4), ba = *(const f32x4*)(lnb + 256 * g + c0), bb = *(const f32x4*)(lnb + 256 * g + c0 + 4);
;                 const float lg[8] = {ga.x, ga.y, ga.z, ga.w, gb.x, gb.y, gb.z, gb.w}, lb[8] = {ba.x, ba.y, ba.z, ba.w, bb.x, bb.y, bb.z, bb.w};
; #pragma unroll
;                 for (int e = 0; e < 8; ++e) { const unsigned wa = rawA[it][e >> 1], wb = rawB[it][e >> 1]; const float xa = (e & 1) ? bfhi(wa) : bflo(wa), xb = (e & 1) ? bfhi(wb) : bflo(wb);
;                     const float ya = (xa - meanA) * rstdA * lg[e] + lb[e], yb = (xb - meanB) * rstdB * lg[e] + lb[e];
;                     *(LAS unsigned*)(Vt + (c0 + e) * LST + 4 * lane) = pk2(ya, yb); } } }
	v_sub_f32_e32 v88, v88, v98
	v_fma_f32 v84, v84, v118, v110
	v_mul_f32_e32 v88, v99, v88
	v_fma_f32 v88, v88, v118, v110
	v_bfe_u32 v89, v84, 16, 1
	v_add3_u32 v84, v84, v89, s37
	v_bfe_u32 v89, v88, 16, 1
	v_lshrrev_b32_e32 v84, 16, v84
	v_add3_u32 v88, v88, v89, s37
	v_and_or_b32 v84, v88, s68, v84
	v_add_u32_e32 v88, 0x9000, v128
	ds_write2_b32 v88, v80, v84 offset0:100 offset1:168
	v_and_b32_e32 v80, 0xffff0000, v81
	v_and_b32_e32 v81, 0xffff0000, v85
	v_sub_f32_e32 v80, v80, v96
	v_mul_f32_e32 v80, v97, v80
	v_sub_f32_e32 v81, v81, v98
	v_fma_f32 v80, v80, v119, v111
	v_mul_f32_e32 v81, v99, v81
	v_fmac_f32_e32 v111, v81, v119
	v_bfe_u32 v81, v80, 16, 1
	v_add3_u32 v80, v80, v81, s37
	v_bfe_u32 v81, v111, 16, 1
	v_lshrrev_b32_e32 v80, 16, v80
	v_add3_u32 v81, v111, v81, s37
	v_and_or_b32 v80, v81, s68, v80
	v_lshlrev_b32_e32 v81, 16, v82
	v_lshlrev_b32_e32 v84, 16, v86
	v_sub_f32_e32 v81, v81, v96
	v_mul_f32_e32 v81, v97, v81
	v_sub_f32_e32 v84, v84, v98
	v_fma_f32 v81, v81, v104, v100
	v_mul_f32_e32 v84, v99, v84
	v_fma_f32 v84, v84, v104, v100
	v_bfe_u32 v85, v81, 16, 1
	v_add3_u32 v81, v81, v85, s37
	v_bfe_u32 v85, v84, 16, 1
	v_lshrrev_b32_e32 v81, 16, v81
	v_add3_u32 v84, v84, v85, s37
	v_and_or_b32 v81, v84, s68, v81
	v_add_u32_e32 v84, 0x9200, v128
	ds_write2_b32 v84, v80, v81 offset0:108 offset1:176
	v_and_b32_e32 v80, 0xffff0000, v82
	v_and_b32_e32 v81, 0xffff0000, v86
	v_sub_f32_e32 v80, v80, v96
	v_mul_f32_e32 v80, v97, v80
	v_sub_f32_e32 v81, v81, v98
	v_fma_f32 v80, v80, v105, v101
	v_mul_f32_e32 v81, v99, v81
	v_fma_f32 v81, v81, v105, v101
	v_bfe_u32 v82, v80, 16, 1
	v_add3_u32 v80, v80, v82, s37
	v_bfe_u32 v82, v81, 16, 1
	v_lshrrev_b32_e32 v80, 16, v80
	v_add3_u32 v81, v81, v82, s37
	v_and_or_b32 v80, v81, s68, v80
	v_lshlrev_b32_e32 v81, 16, v83
	v_lshlrev_b32_e32 v82, 16, v87
	v_sub_f32_e32 v81, v81, v96
	v_mul_f32_e32 v81, v97, v81
	v_sub_f32_e32 v82, v82, v98
	v_fma_f32 v81, v81, v106, v102
	v_mul_f32_e32 v82, v99, v82
	v_fma_f32 v82, v82, v106, v102
	v_bfe_u32 v84, v81, 16, 1
	v_add3_u32 v81, v81, v84, s37
	v_bfe_u32 v84, v82, 16, 1
	v_lshrrev_b32_e32 v81, 16, v81
	v_add3_u32 v82, v82, v84, s37
	v_and_or_b32 v81, v82, s68, v81
	v_add_u32_e32 v82, 0x9400, v128
	ds_write2_b32 v82, v80, v81 offset0:116 offset1:184
	v_and_b32_e32 v80, 0xffff0000, v83
	v_and_b32_e32 v81, 0xffff0000, v87
	v_sub_f32_e32 v80, v80, v96
	v_mul_f32_e32 v80, v97, v80
	v_sub_f32_e32 v81, v81, v98
	v_fma_f32 v80, v80, v107, v103
	v_mul_f32_e32 v81, v99, v81
	v_fmac_f32_e32 v103, v81, v107
	v_bfe_u32 v81, v80, 16, 1
	v_add3_u32 v80, v80, v81, s37
	v_bfe_u32 v81, v103, 16, 1
	v_lshrrev_b32_e32 v80, 16, v80
	v_add3_u32 v81, v103, v81, s37
	v_and_or_b32 v121, v81, s68, v80
	global_load_dwordx4 v[80:83], v223, s[20:21] offset:112
	global_load_dwordx4 v[84:87], v223, s[20:21] offset:96
	global_load_dwordx4 v[88:91], v223, s[20:21] offset:80
	global_load_dwordx4 v[108:111], v223, s[20:21] offset:64
	global_load_dwordx4 v[92:95], v223, s[0:1] offset:112
	global_load_dwordx4 v[100:103], v223, s[0:1] offset:96
	global_load_dwordx4 v[104:107], v223, s[0:1] offset:80
	global_load_dwordx4 v[116:119], v223, s[0:1] offset:64
	v_lshlrev_b32_e32 v122, 16, v72
	v_lshlrev_b32_e32 v123, 16, v76
	v_sub_f32_e32 v122, v122, v96
	v_mul_f32_e32 v122, v97, v122
	v_sub_f32_e32 v123, v123, v98
	v_mul_f32_e32 v123, v99, v123
	v_and_b32_e32 v72, 0xffff0000, v72
	v_and_b32_e32 v76, 0xffff0000, v76
	v_sub_f32_e32 v72, v72, v96
	v_mul_f32_e32 v72, v97, v72
	v_sub_f32_e32 v76, v76, v98
	v_mul_f32_e32 v76, v99, v76
	s_waitcnt vmcnt(0)
	v_fma_f32 v122, v122, v108, v116
	v_fma_f32 v108, v123, v108, v116
	v_bfe_u32 v116, v122, 16, 1
	v_add3_u32 v116, v122, v116, s37
	v_bfe_u32 v122, v108, 16, 1
	v_lshrrev_b32_e32 v116, 16, v116
	v_add3_u32 v108, v108, v122, s37
	v_and_or_b32 v108, v108, s68, v116
	v_fma_f32 v72, v72, v109, v117
	ds_write_b32 v120, v108 offset:36992
	v_fma_f32 v76, v76, v109, v117
	v_bfe_u32 v108, v72, 16, 1
	v_add3_u32 v72, v72, v108, s37
	v_bfe_u32 v108, v76, 16, 1
	v_lshrrev_b32_e32 v72, 16, v72
	v_add3_u32 v76, v76, v108, s37
	v_and_or_b32 v72, v76, s68, v72
	v_add_u32_e32 v76, 0x9700, v128
	ds_write2_b32 v76, v121, v72 offset0:60 offset1:196
	v_lshlrev_b32_e32 v72, 16, v73
	v_lshlrev_b32_e32 v76, 16, v77
	v_sub_f32_e32 v72, v72, v96
	v_mul_f32_e32 v72, v97, v72
	v_sub_f32_e32 v76, v76, v98
	v_fma_f32 v72, v72, v110, v118
	v_mul_f32_e32 v76, v99, v76
	v_fma_f32 v76, v76, v110, v118
	v_bfe_u32 v108, v72, 16, 1
	v_add3_u32 v72, v72, v108, s37
	v_bfe_u32 v108, v76, 16, 1
	v_lshrrev_b32_e32 v72, 16, v72
	v_add3_u32 v76, v76, v108, s37
	v_and_b32_e32 v73, 0xffff0000, v73
	v_and_or_b32 v72, v76, s68, v72
	v_and_b32_e32 v76, 0xffff0000, v77
	v_sub_f32_e32 v73, v73, v96
	v_mul_f32_e32 v73, v97, v73
	v_sub_f32_e32 v76, v76, v98
	v_fma_f32 v73, v73, v111, v119
	v_mul_f32_e32 v76, v99, v76
	v_fmac_f32_e32 v119, v76, v111
	v_bfe_u32 v76, v73, 16, 1
	v_add3_u32 v73, v73, v76, s37
	v_bfe_u32 v76, v119, 16, 1
	v_lshrrev_b32_e32 v73, 16, v73
	v_add3_u32 v76, v119, v76, s37
	v_and_or_b32 v73, v76, s68, v73
	v_add_u32_e32 v76, 0x9a00, v128
	ds_write2_b32 v76, v72, v73 offset0:72 offset1:140
	v_lshlrev_b32_e32 v72, 16, v74
	v_lshlrev_b32_e32 v73, 16, v78
	v_sub_f32_e32 v72, v72, v96
	v_mul_f32_e32 v72, v97, v72
	v_sub_f32_e32 v73, v73, v98
	v_fma_f32 v72, v72, v88, v104
	v_mul_f32_e32 v73, v99, v73
	v_fma_f32 v73, v73, v88, v104
	v_bfe_u32 v76, v72, 16, 1
	v_add3_u32 v72, v72, v76, s37
	v_bfe_u32 v76, v73, 16, 1
	v_lshrrev_b32_e32 v72, 16, v72
	v_add3_u32 v73, v73, v76, s37
	v_and_or_b32 v72, v73, s68, v72
	v_and_b32_e32 v73, 0xffff0000, v74
	v_and_b32_e32 v74, 0xffff0000, v78
; #define LAS __attribute__((address_space(3)))
; __device__ __forceinline__ unsigned pk2(float lo, float hi) { return f2bf(lo) | (f2bf(hi) << 16); }
; __device__ __forceinline__ float bflo(unsigned w) { return __uint_as_float(w << 16); }
; __device__ __forceinline__ float bfhi(unsigned w) { return __uint_as_float(w & 0xffff0000u); }
; __device__ __forceinline__ void spatial_phase(const Frame& F, bf16* Z, const float* stats, const float* lng, const float* lnb, const float* ws, const float* bs, bool do_store = true) {
;     ...
;         {
;             const float meanA = st[4 * lane], rstdA = st[4 * lane + 1], meanB = st[4 * lane + 2], rstdB = st[4 * lane + 3];
; #pragma unroll
;             for (int it = 0; it < 4; ++it) { const int c0 = 32 * w + 8 * it;
;                 const f32x4 ga = *(const f32x4*)(lng + 256 * g + c0), gb = *(const f32x4*)(lng + 256 * g + c0 + 4), ba = *(const f32x4*)(lnb + 256 * g + c0), bb = *(const f32x4*)(lnb + 256 * g + c0 + 4);
;                 const float lg[8] = {ga.x, ga.y, ga.z, ga.w, gb.x, gb.y, gb.z, gb.w}, lb[8] = {ba.x, ba.y, ba.z, ba.w, bb.x, bb.y, bb.z, bb.w};
; #pragma unroll
;                 for (int e = 0; e < 8; ++e) { const unsigned wa = rawA[it][e >> 1], wb = rawB[it][e >> 1]; const float xa = (e & 1) ? bfhi(wa) : bflo(wa), xb = (e & 1) ? bfhi(wb) : bflo(wb);
;                     const float ya = (xa - meanA) * rstdA * lg[e] + lb[e], yb = (xb - meanB) * rstdB * lg[e] + lb[e];
;                     *(LAS unsigned*)(Vt + (c0 + e) * LST + 4 * lane) = pk2(ya, yb); } } }
;         __syncthreads();
	v_sub_f32_e32 v73, v73, v96
	v_mul_f32_e32 v73, v97, v73
	v_sub_f32_e32 v74, v74, v98
	v_fma_f32 v73, v73, v89, v105
	v_mul_f32_e32 v74, v99, v74
	v_fma_f32 v74, v74, v89, v105
	v_bfe_u32 v76, v73, 16, 1
	v_add3_u32 v73, v73, v76, s37
	v_bfe_u32 v76, v74, 16, 1
	v_lshrrev_b32_e32 v73, 16, v73
	v_add3_u32 v74, v74, v76, s37
	v_and_or_b32 v73, v74, s68, v73
	v_add_u32_e32 v74, 0x9c00, v128
	ds_write2_b32 v74, v72, v73 offset0:80 offset1:148
	v_lshlrev_b32_e32 v72, 16, v75
	v_lshlrev_b32_e32 v73, 16, v79
	v_sub_f32_e32 v72, v72, v96
	v_mul_f32_e32 v72, v97, v72
	v_sub_f32_e32 v73, v73, v98
	v_fma_f32 v72, v72, v90, v106
	v_mul_f32_e32 v73, v99, v73
	v_fma_f32 v73, v73, v90, v106
	v_bfe_u32 v74, v72, 16, 1
	v_add3_u32 v72, v72, v74, s37
	v_bfe_u32 v74, v73, 16, 1
	v_lshrrev_b32_e32 v72, 16, v72
	v_add3_u32 v73, v73, v74, s37
	v_and_or_b32 v72, v73, s68, v72
	v_and_b32_e32 v73, 0xffff0000, v75
	v_and_b32_e32 v74, 0xffff0000, v79
	v_sub_f32_e32 v73, v73, v96
	v_mul_f32_e32 v73, v97, v73
	v_sub_f32_e32 v74, v74, v98
	v_fma_f32 v73, v73, v91, v107
	v_mul_f32_e32 v74, v99, v74
	v_fmac_f32_e32 v107, v74, v91
	v_bfe_u32 v74, v73, 16, 1
	v_add3_u32 v73, v73, v74, s37
	v_bfe_u32 v74, v107, 16, 1
	v_lshrrev_b32_e32 v73, 16, v73
	v_add3_u32 v74, v107, v74, s37
	v_and_or_b32 v73, v74, s68, v73
	v_add_u32_e32 v74, 0x9e00, v128
	ds_write2_b32 v74, v72, v73 offset0:88 offset1:156
	v_lshlrev_b32_e32 v72, 16, v68
	v_lshlrev_b32_e32 v73, 16, v64
	v_sub_f32_e32 v72, v72, v96
	v_mul_f32_e32 v72, v97, v72
	v_sub_f32_e32 v73, v73, v98
	v_fma_f32 v72, v72, v84, v100
	v_mul_f32_e32 v73, v99, v73
	v_fma_f32 v73, v73, v84, v100
	v_bfe_u32 v74, v72, 16, 1
	v_and_b32_e32 v68, 0xffff0000, v68
	v_add3_u32 v72, v72, v74, s37
	v_bfe_u32 v74, v73, 16, 1
	v_and_b32_e32 v64, 0xffff0000, v64
	v_sub_f32_e32 v68, v68, v96
	v_lshrrev_b32_e32 v72, 16, v72
	v_add3_u32 v73, v73, v74, s37
	v_mul_f32_e32 v68, v97, v68
	v_sub_f32_e32 v64, v64, v98
	v_and_or_b32 v72, v73, s68, v72
	v_fma_f32 v68, v68, v85, v101
	v_mul_f32_e32 v64, v99, v64
	ds_write_b32 v120, v72 offset:39168
	v_fma_f32 v64, v64, v85, v101
	v_bfe_u32 v72, v68, 16, 1
	v_add3_u32 v68, v68, v72, s37
	v_bfe_u32 v72, v64, 16, 1
	v_lshrrev_b32_e32 v68, 16, v68
	v_add3_u32 v64, v64, v72, s37
	v_and_or_b32 v64, v64, s68, v68
	v_lshlrev_b32_e32 v68, 16, v69
	v_lshlrev_b32_e32 v72, 16, v65
	v_sub_f32_e32 v68, v68, v96
	v_mul_f32_e32 v68, v97, v68
	v_sub_f32_e32 v72, v72, v98
	v_fma_f32 v68, v68, v86, v102
	v_mul_f32_e32 v72, v99, v72
	v_fma_f32 v72, v72, v86, v102
	v_bfe_u32 v73, v68, 16, 1
	v_add3_u32 v68, v68, v73, s37
	v_bfe_u32 v73, v72, 16, 1
	v_lshrrev_b32_e32 v68, 16, v68
	v_add3_u32 v72, v72, v73, s37
	v_and_or_b32 v68, v72, s68, v68
	v_add_u32_e32 v72, 0xa000, v128
	ds_write2_b32 v72, v64, v68 offset0:164 offset1:232
	v_and_b32_e32 v64, 0xffff0000, v69
	v_and_b32_e32 v65, 0xffff0000, v65
	v_sub_f32_e32 v64, v64, v96
	v_mul_f32_e32 v64, v97, v64
	v_sub_f32_e32 v65, v65, v98
	v_fma_f32 v64, v64, v87, v103
	v_mul_f32_e32 v65, v99, v65
	v_fmac_f32_e32 v103, v65, v87
	v_bfe_u32 v65, v64, 16, 1
	v_add3_u32 v64, v64, v65, s37
	v_bfe_u32 v65, v103, 16, 1
	v_lshrrev_b32_e32 v64, 16, v64
	v_add3_u32 v65, v103, v65, s37
	v_and_or_b32 v64, v65, s68, v64
	v_lshlrev_b32_e32 v65, 16, v70
	v_lshlrev_b32_e32 v68, 16, v66
	v_sub_f32_e32 v65, v65, v96
	v_mul_f32_e32 v65, v97, v65
	v_sub_f32_e32 v68, v68, v98
	v_fma_f32 v65, v65, v80, v92
	v_mul_f32_e32 v68, v99, v68
	v_fma_f32 v68, v68, v80, v92
	v_bfe_u32 v69, v65, 16, 1
	v_add3_u32 v65, v65, v69, s37
	v_bfe_u32 v69, v68, 16, 1
	v_lshrrev_b32_e32 v65, 16, v65
	v_add3_u32 v68, v68, v69, s37
	v_and_or_b32 v65, v68, s68, v65
	v_add_u32_e32 v68, 0xa400, v128
	ds_write2_b32 v68, v64, v65 offset0:44 offset1:112
	v_and_b32_e32 v64, 0xffff0000, v70
	v_and_b32_e32 v65, 0xffff0000, v66
	v_sub_f32_e32 v64, v64, v96
	v_mul_f32_e32 v64, v97, v64
	v_sub_f32_e32 v65, v65, v98
	v_fma_f32 v64, v64, v81, v93
	v_mul_f32_e32 v65, v99, v65
	v_fma_f32 v65, v65, v81, v93
	v_bfe_u32 v66, v64, 16, 1
	v_add3_u32 v64, v64, v66, s37
	v_bfe_u32 v66, v65, 16, 1
	v_lshrrev_b32_e32 v64, 16, v64
	v_add3_u32 v65, v65, v66, s37
	v_and_or_b32 v64, v65, s68, v64
	v_lshlrev_b32_e32 v65, 16, v71
	v_lshlrev_b32_e32 v66, 16, v67
	v_sub_f32_e32 v65, v65, v96
	v_mul_f32_e32 v65, v97, v65
	v_sub_f32_e32 v66, v66, v98
	v_fma_f32 v65, v65, v82, v94
	v_mul_f32_e32 v66, v99, v66
	v_fma_f32 v66, v66, v82, v94
	v_bfe_u32 v69, v65, 16, 1
	v_add3_u32 v65, v65, v69, s37
	v_bfe_u32 v69, v66, 16, 1
	v_lshrrev_b32_e32 v65, 16, v65
	v_add3_u32 v66, v66, v69, s37
	v_and_or_b32 v65, v66, s68, v65
	ds_write2_b32 v68, v64, v65 offset0:180 offset1:248
	v_and_b32_e32 v64, 0xffff0000, v71
	v_and_b32_e32 v65, 0xffff0000, v67
	v_sub_f32_e32 v64, v64, v96
	v_mul_f32_e32 v64, v97, v64
	v_sub_f32_e32 v65, v65, v98
	v_fma_f32 v64, v64, v83, v95
	v_mul_f32_e32 v65, v99, v65
	v_fmac_f32_e32 v95, v65, v83
	v_bfe_u32 v65, v64, 16, 1
	v_add3_u32 v64, v64, v65, s37
	v_bfe_u32 v65, v95, 16, 1
	v_lshrrev_b32_e32 v64, 16, v64
	v_add3_u32 v65, v95, v65, s37
	v_and_or_b32 v64, v65, s68, v64
	ds_write_b32 v128, v64 offset:43248
	s_waitcnt lgkmcnt(0)
	s_barrier
; #define LAS __attribute__((address_space(3)))
; __device__ __forceinline__ void spatial_phase(const Frame& F, bf16* Z, const float* stats, const float* lng, const float* lnb, const float* ws, const float* bs, bool do_store = true) {
;     ...
;         f32x4 acc[8][2];
; #pragma unroll
;         for (int m = 0; m < 8; ++m) { acc[m][0] = (f32x4){0.f, 0.f, 0.f, 0.f}; acc[m][1] = (f32x4){0.f, 0.f, 0.f, 0.f}; }
; #pragma unroll
;         for (int ks = 0; ks < 4; ++ks) { bf16x8 Bf[2];
; #pragma unroll
;             for (int n = 0; n < 2; ++n) Bf[n] = *(const LAS bf16x8*)(Vt + (32 * w + 16 * n + fr) * LST + (ks * 32 + fq * 8) * 2);
; #pragma unroll
;             for (int m = 0; m < 8; ++m) if (32 * ks <= 16 * m + 15) { const bf16x8 Af = *(const LAS bf16x8*)(Wl + (16 * m + fr) * LST + (ks * 32 + fq * 8) * 2);
; #pragma unroll
;                 for (int n = 0; n < 2; ++n) acc[m][n] = __builtin_amdgcn_mfma_f32_16x16x32_bf16(Bf[n], Af, acc[m][n], 0, 0, 0); } }
;     ...
;         for (int m = 0; m < 8; ++m) { const int t = 16 * m + fr; const float b = bs[g * 128 + t];
	v_lshlrev_b32_e32 v8, 2, v132
	v_lshl_or_b32 v8, s45, 9, v8
	global_load_dword v0, v8, s[22:23]
	global_load_dword v1, v8, s[22:23] offset:64
	global_load_dword v2, v8, s[22:23] offset:128
	global_load_dword v3, v8, s[22:23] offset:192
	global_load_dword v4, v8, s[22:23] offset:256
	global_load_dword v5, v8, s[22:23] offset:320
	global_load_dword v6, v8, s[22:23] offset:384
	global_load_dword v7, v8, s[22:23] offset:448
	ds_read_b128 v[64:67], v201 offset:34816
	ds_read_b128 v[68:71], v201 offset:39168
	ds_read_b128 v[72:75], v222
	ds_read_b128 v[96:99], v222 offset:21760
	s_waitcnt lgkmcnt(1)
	v_mfma_f32_16x16x32_bf16 v[128:131], v[64:67], v[72:75], 0
	ds_read_b128 v[80:83], v222 offset:13056
	ds_read_b128 v[88:91], v222 offset:17408
	v_mfma_f32_16x16x32_bf16 v[124:127], v[68:71], v[72:75], 0
	ds_read_b128 v[72:75], v222 offset:4352
	s_waitcnt lgkmcnt(3)
	v_mfma_f32_16x16x32_bf16 v[224:227], v[64:67], v[96:99], 0
	v_mfma_f32_16x16x32_bf16 v[238:241], v[68:71], v[96:99], 0
	ds_read_b128 v[96:99], v222 offset:26112
	s_waitcnt lgkmcnt(1)
	v_mfma_f32_16x16x32_bf16 v[108:111], v[64:67], v[72:75], 0
	v_mfma_f32_16x16x32_bf16 v[104:107], v[68:71], v[72:75], 0
	ds_read_b128 v[72:75], v222 offset:8704
	s_waitcnt lgkmcnt(1)
	v_mfma_f32_16x16x32_bf16 v[242:245], v[64:67], v[96:99], 0
	v_mfma_f32_16x16x32_bf16 v[246:249], v[68:71], v[96:99], 0
	ds_read_b128 v[96:99], v222 offset:30464
	s_waitcnt lgkmcnt(1)
	v_mfma_f32_16x16x32_bf16 v[76:79], v[64:67], v[72:75], 0
	v_mfma_f32_16x16x32_bf16 v[72:75], v[68:71], v[72:75], 0
	v_mfma_f32_16x16x32_bf16 v[84:87], v[64:67], v[80:83], 0
	v_mfma_f32_16x16x32_bf16 v[80:83], v[68:71], v[80:83], 0
	v_mfma_f32_16x16x32_bf16 v[92:95], v[64:67], v[88:91], 0
	v_mfma_f32_16x16x32_bf16 v[88:91], v[68:71], v[88:91], 0
	s_waitcnt lgkmcnt(0)
	v_mfma_f32_16x16x32_bf16 v[64:67], v[64:67], v[96:99], 0
	v_mfma_f32_16x16x32_bf16 v[68:71], v[68:71], v[96:99], 0
	ds_read_b128 v[138:141], v201 offset:34880
	ds_read_b128 v[142:145], v201 offset:39232
	ds_read_b128 v[96:99], v222 offset:8768
	s_waitcnt lgkmcnt(0)
	v_mfma_f32_16x16x32_bf16 v[116:119], v[142:145], v[96:99], v[72:75]
	s_nop 2
	ds_read_b128 v[72:75], v222 offset:13120
	v_mfma_f32_16x16x32_bf16 v[120:123], v[138:141], v[96:99], v[76:79]
	s_waitcnt lgkmcnt(0)
	v_mfma_f32_16x16x32_bf16 v[100:103], v[138:141], v[72:75], v[84:87]
	v_mfma_f32_16x16x32_bf16 v[96:99], v[142:145], v[72:75], v[80:83]
	ds_read_b128 v[72:75], v222 offset:17472
	s_nop 1
	ds_read_b128 v[80:83], v222 offset:21824
	s_waitcnt lgkmcnt(1)
	v_mfma_f32_16x16x32_bf16 v[76:79], v[138:141], v[72:75], v[92:95]
	v_mfma_f32_16x16x32_bf16 v[72:75], v[142:145], v[72:75], v[88:91]
	s_nop 2
	ds_read_b128 v[88:91], v222 offset:26176
	s_waitcnt lgkmcnt(1)
	v_mfma_f32_16x16x32_bf16 v[84:87], v[138:141], v[80:83], v[224:227]
	v_mfma_f32_16x16x32_bf16 v[80:83], v[142:145], v[80:83], v[238:241]
	s_waitcnt lgkmcnt(0)
	v_mfma_f32_16x16x32_bf16 v[224:227], v[138:141], v[88:91], v[242:245]
	v_mfma_f32_16x16x32_bf16 v[238:241], v[142:145], v[88:91], v[246:249]
	ds_read_b128 v[88:91], v222 offset:30528
	s_waitcnt lgkmcnt(0)
	v_mfma_f32_16x16x32_bf16 v[64:67], v[138:141], v[88:91], v[64:67]
	v_mfma_f32_16x16x32_bf16 v[68:71], v[142:145], v[88:91], v[68:71]
	ds_read_b128 v[138:141], v201 offset:34944
	ds_read_b128 v[142:145], v201 offset:39296
	ds_read_b128 v[88:91], v222 offset:17536
	s_waitcnt lgkmcnt(0)
	v_mfma_f32_16x16x32_bf16 v[92:95], v[138:141], v[88:91], v[76:79]
	v_mfma_f32_16x16x32_bf16 v[88:91], v[142:145], v[88:91], v[72:75]
	s_nop 2
	ds_read_b128 v[72:75], v222 offset:21888
	s_waitcnt lgkmcnt(0)
	v_mfma_f32_16x16x32_bf16 v[84:87], v[138:141], v[72:75], v[84:87]
	v_mfma_f32_16x16x32_bf16 v[80:83], v[142:145], v[72:75], v[80:83]
	ds_read_b128 v[72:75], v222 offset:26240
	s_waitcnt lgkmcnt(0)
	v_mfma_f32_16x16x32_bf16 v[76:79], v[138:141], v[72:75], v[224:227]
	s_nop 2
	ds_read_b128 v[224:227], v222 offset:30592
	v_mfma_f32_16x16x32_bf16 v[72:75], v[142:145], v[72:75], v[238:241]
	s_waitcnt lgkmcnt(0)
	v_mfma_f32_16x16x32_bf16 v[64:67], v[138:141], v[224:227], v[64:67]
	v_mfma_f32_16x16x32_bf16 v[138:141], v[142:145], v[224:227], v[68:71]
	s_nop 2
	ds_read_b128 v[68:71], v201 offset:35008
	ds_read_b128 v[142:145], v201 offset:39360
	ds_read_b128 v[224:227], v222 offset:26304
	s_waitcnt lgkmcnt(0)
	v_mfma_f32_16x16x32_bf16 v[76:79], v[68:71], v[224:227], v[76:79]
	v_mfma_f32_16x16x32_bf16 v[72:75], v[142:145], v[224:227], v[72:75]
	ds_read_b128 v[224:227], v222 offset:30656
	s_waitcnt lgkmcnt(0)
	v_mfma_f32_16x16x32_bf16 v[68:71], v[68:71], v[224:227], v[64:67]
	v_mfma_f32_16x16x32_bf16 v[64:67], v[142:145], v[224:227], v[138:141]
	s_cbranch_vccnz .LBB0_716
; __device__ __forceinline__ unsigned pk2(float lo, float hi) { return f2bf(lo) | (f2bf(hi) << 16); }
; __device__ __forceinline__ float bflo(unsigned w) { return __uint_as_float(w << 16); }
; __device__ __forceinline__ float bfhi(unsigned w) { return __uint_as_float(w & 0xffff0000u); }
; __device__ __forceinline__ void spatial_phase(const Frame& F, bf16* Z, const float* stats, const float* lng, const float* lnb, const float* ws, const float* bs, bool do_store = true) {
;     ...
;         for (int m = 0; m < 8; ++m) { const int t = 16 * m + fr; const float b = bs[g * 128 + t];
; #pragma unroll
;             for (int n = 0; n < 2; ++n) { const int c = 32 * w + 16 * n + 4 * fq; v2u* p = (v2u*)(Z + (row0 + t) * 4096 + 256 * g + c); const v2u u2 = uu[m][n];
;                 const float o0 = bflo(u2.x) * (acc[m][n][0] + b), o1 = bfhi(u2.x) * (acc[m][n][1] + b), o2 = bflo(u2.y) * (acc[m][n][2] + b), o3 = bfhi(u2.y) * (acc[m][n][3] + b);
;                 if (do_store) *p = (v2u){pk2(o0, o1), pk2(o2, o3)}; } }
	s_nop 1
	s_lshl_b32 s12, s12, 1
	v_mov_b32_e32 v144, v129
	v_mov_b32_e32 v145, v131
	s_add_u32 s12, s26, s12
	v_and_b32_e32 v141, 0xffff0000, v221
	v_and_b32_e32 v140, 0xffff0000, v220
	v_lshlrev_b32_e32 v143, 16, v221
	v_lshlrev_b32_e32 v142, 16, v220
	v_mov_b32_e32 v129, v130
	v_mov_b32_e32 v220, v125
	v_mov_b32_e32 v221, v127
	v_mov_b32_e32 v125, v126
	s_addc_u32 s13, s27, 0
	v_and_b32_e32 v131, 0xffff0000, v219
	v_and_b32_e32 v130, 0xffff0000, v218
	v_lshlrev_b32_e32 v219, 16, v219
	v_lshlrev_b32_e32 v218, 16, v218
	v_lshl_add_u64 v[126:127], s[12:13], 0, v[216:217]
	v_lshl_add_u64 v[126:127], v[126:127], 0, v[164:165]
	s_waitcnt vmcnt(0)
	v_mov_b32_e32 v138, v0
	v_pk_add_f32 v[144:145], v[144:145], v[138:139] op_sel_hi:[1,0]
	v_pk_add_f32 v[128:129], v[128:129], v[138:139] op_sel_hi:[1,0]
	v_pk_add_f32 v[216:217], v[220:221], v[138:139] op_sel_hi:[1,0]
	v_pk_add_f32 v[124:125], v[124:125], v[138:139] op_sel_hi:[1,0]
	v_pk_mul_f32 v[138:139], v[144:145], v[140:141]
	v_pk_mul_f32 v[128:129], v[128:129], v[142:143]
	v_pk_mul_f32 v[130:131], v[216:217], v[130:131]
	v_pk_mul_f32 v[124:125], v[124:125], v[218:219]
	v_and_b32_sdwa v142, v139, v233 dst_sel:DWORD dst_unused:UNUSED_PAD src0_sel:WORD_1 src1_sel:DWORD
	v_and_b32_sdwa v143, v138, v233 dst_sel:DWORD dst_unused:UNUSED_PAD src0_sel:WORD_1 src1_sel:DWORD
	v_and_b32_sdwa v140, v129, v233 dst_sel:DWORD dst_unused:UNUSED_PAD src0_sel:WORD_1 src1_sel:DWORD
	v_and_b32_sdwa v141, v128, v233 dst_sel:DWORD dst_unused:UNUSED_PAD src0_sel:WORD_1 src1_sel:DWORD
	v_and_b32_sdwa v144, v125, v233 dst_sel:DWORD dst_unused:UNUSED_PAD src0_sel:WORD_1 src1_sel:DWORD
	v_and_b32_sdwa v145, v124, v233 dst_sel:DWORD dst_unused:UNUSED_PAD src0_sel:WORD_1 src1_sel:DWORD
	v_and_b32_sdwa v216, v131, v233 dst_sel:DWORD dst_unused:UNUSED_PAD src0_sel:WORD_1 src1_sel:DWORD
	v_and_b32_sdwa v217, v130, v233 dst_sel:DWORD dst_unused:UNUSED_PAD src0_sel:WORD_1 src1_sel:DWORD
	v_add3_u32 v139, v139, v142, s37
	v_add3_u32 v138, v138, v143, s37
	v_add3_u32 v128, v128, v141, s37
	v_add3_u32 v129, v129, v140, s37
	v_add3_u32 v140, v124, v145, s37
	v_add3_u32 v141, v125, v144, s37
	v_add3_u32 v124, v131, v216, s37
	v_add3_u32 v125, v130, v217, s37
	v_and_b32_e32 v130, 0xffff0000, v139
	v_and_b32_e32 v131, 0xffff0000, v138
	v_and_b32_e32 v138, 0xffff0000, v124
	v_and_b32_e32 v139, 0xffff0000, v125
	v_or_b32_sdwa v125, v130, v129 dst_sel:DWORD dst_unused:UNUSED_PAD src0_sel:DWORD src1_sel:WORD_1
	v_or_b32_sdwa v124, v131, v128 dst_sel:DWORD dst_unused:UNUSED_PAD src0_sel:DWORD src1_sel:WORD_1
	v_or_b32_sdwa v129, v138, v141 dst_sel:DWORD dst_unused:UNUSED_PAD src0_sel:DWORD src1_sel:WORD_1
	v_or_b32_sdwa v128, v139, v140 dst_sel:DWORD dst_unused:UNUSED_PAD src0_sel:DWORD src1_sel:WORD_1
	s_nop 1
	v_permlane32_swap_b32_e32 v124, v128
	v_permlane32_swap_b32_e32 v125, v129
	s_nop 1
	v_permlane16_swap_b32_e32 v124, v128
	v_permlane16_swap_b32_e32 v125, v129
	v_mov_b32_e32 v142, v124
	v_mov_b32_e32 v143, v125
	v_mov_b32_e32 v144, v128
	v_mov_b32_e32 v145, v129
	global_store_dwordx4 v[126:127], v[142:145], off
	v_mov_b32_e32 v124, v1
	v_mov_b32_e32 v130, v109
	v_mov_b32_e32 v131, v111
	v_and_b32_e32 v127, 0xffff0000, v215
	v_and_b32_e32 v126, 0xffff0000, v214
	v_mov_b32_e32 v109, v110
	v_mov_b32_e32 v140, v105
	v_mov_b32_e32 v141, v107
	v_mov_b32_e32 v105, v106
	v_lshlrev_b32_e32 v129, 16, v215
	v_lshlrev_b32_e32 v128, 16, v214
	v_and_b32_e32 v111, 0xffff0000, v213
	v_and_b32_e32 v110, 0xffff0000, v212
	v_lshlrev_b32_e32 v139, 16, v213
	v_lshlrev_b32_e32 v138, 16, v212
	v_lshl_add_u64 v[106:107], s[12:13], 0, v[210:211]
	v_lshl_add_u64 v[106:107], v[106:107], 0, v[164:165]
	v_pk_add_f32 v[130:131], v[130:131], v[124:125] op_sel_hi:[1,0]
	v_pk_add_f32 v[108:109], v[108:109], v[124:125] op_sel_hi:[1,0]
	v_pk_add_f32 v[140:141], v[140:141], v[124:125] op_sel_hi:[1,0]
	v_pk_add_f32 v[104:105], v[104:105], v[124:125] op_sel_hi:[1,0]
	v_pk_mul_f32 v[124:125], v[130:131], v[126:127]
	v_pk_mul_f32 v[108:109], v[108:109], v[128:129]
	v_pk_mul_f32 v[110:111], v[140:141], v[110:111]
	v_pk_mul_f32 v[104:105], v[104:105], v[138:139]
	v_and_b32_sdwa v128, v125, v233 dst_sel:DWORD dst_unused:UNUSED_PAD src0_sel:WORD_1 src1_sel:DWORD
	v_and_b32_sdwa v129, v124, v233 dst_sel:DWORD dst_unused:UNUSED_PAD src0_sel:WORD_1 src1_sel:DWORD
	v_and_b32_sdwa v126, v109, v233 dst_sel:DWORD dst_unused:UNUSED_PAD src0_sel:WORD_1 src1_sel:DWORD
	v_and_b32_sdwa v127, v108, v233 dst_sel:DWORD dst_unused:UNUSED_PAD src0_sel:WORD_1 src1_sel:DWORD
	v_and_b32_sdwa v130, v105, v233 dst_sel:DWORD dst_unused:UNUSED_PAD src0_sel:WORD_1 src1_sel:DWORD
	v_and_b32_sdwa v131, v104, v233 dst_sel:DWORD dst_unused:UNUSED_PAD src0_sel:WORD_1 src1_sel:DWORD
	v_and_b32_sdwa v138, v111, v233 dst_sel:DWORD dst_unused:UNUSED_PAD src0_sel:WORD_1 src1_sel:DWORD
	v_and_b32_sdwa v139, v110, v233 dst_sel:DWORD dst_unused:UNUSED_PAD src0_sel:WORD_1 src1_sel:DWORD
	v_add3_u32 v125, v125, v128, s37
	v_add3_u32 v124, v124, v129, s37
	v_add3_u32 v108, v108, v127, s37
	v_add3_u32 v109, v109, v126, s37
	v_add3_u32 v126, v104, v131, s37
	v_add3_u32 v127, v105, v130, s37
	v_add3_u32 v104, v111, v138, s37
	v_add3_u32 v105, v110, v139, s37
	v_and_b32_e32 v110, 0xffff0000, v125
	v_and_b32_e32 v111, 0xffff0000, v124
	v_and_b32_e32 v124, 0xffff0000, v104
	v_and_b32_e32 v125, 0xffff0000, v105
	v_or_b32_sdwa v105, v110, v109 dst_sel:DWORD dst_unused:UNUSED_PAD src0_sel:DWORD src1_sel:WORD_1
	v_or_b32_sdwa v104, v111, v108 dst_sel:DWORD dst_unused:UNUSED_PAD src0_sel:DWORD src1_sel:WORD_1
	v_or_b32_sdwa v109, v124, v127 dst_sel:DWORD dst_unused:UNUSED_PAD src0_sel:DWORD src1_sel:WORD_1
; __device__ __forceinline__ unsigned pk2(float lo, float hi) { return f2bf(lo) | (f2bf(hi) << 16); }
; __device__ __forceinline__ float bflo(unsigned w) { return __uint_as_float(w << 16); }
; __device__ __forceinline__ float bfhi(unsigned w) { return __uint_as_float(w & 0xffff0000u); }
; __device__ __forceinline__ void spatial_phase(const Frame& F, bf16* Z, const float* stats, const float* lng, const float* lnb, const float* ws, const float* bs, bool do_store = true) {
;     ...
;         for (int m = 0; m < 8; ++m) { const int t = 16 * m + fr; const float b = bs[g * 128 + t];
; #pragma unroll
;             for (int n = 0; n < 2; ++n) { const int c = 32 * w + 16 * n + 4 * fq; v2u* p = (v2u*)(Z + (row0 + t) * 4096 + 256 * g + c); const v2u u2 = uu[m][n];
;                 const float o0 = bflo(u2.x) * (acc[m][n][0] + b), o1 = bfhi(u2.x) * (acc[m][n][1] + b), o2 = bflo(u2.y) * (acc[m][n][2] + b), o3 = bfhi(u2.y) * (acc[m][n][3] + b);
;                 if (do_store) *p = (v2u){pk2(o0, o1), pk2(o2, o3)}; } }
	v_or_b32_sdwa v108, v125, v126 dst_sel:DWORD dst_unused:UNUSED_PAD src0_sel:DWORD src1_sel:WORD_1
	s_nop 1
	v_permlane32_swap_b32_e32 v104, v108
	v_permlane32_swap_b32_e32 v105, v109
	s_nop 1
	v_permlane16_swap_b32_e32 v104, v108
	v_permlane16_swap_b32_e32 v105, v109
	v_mov_b32_e32 v142, v104
	v_mov_b32_e32 v143, v105
	v_mov_b32_e32 v144, v108
	v_mov_b32_e32 v145, v109
	global_store_dwordx4 v[106:107], v[142:145], off
	v_mov_b32_e32 v104, v2
	v_mov_b32_e32 v110, v121
	v_mov_b32_e32 v111, v123
	v_and_b32_e32 v107, 0xffff0000, v209
	v_and_b32_e32 v106, 0xffff0000, v208
	v_mov_b32_e32 v121, v122
	v_mov_b32_e32 v126, v117
	v_mov_b32_e32 v127, v119
	v_mov_b32_e32 v117, v118
	v_lshlrev_b32_e32 v109, 16, v209
	v_lshlrev_b32_e32 v108, 16, v208
	v_and_b32_e32 v123, 0xffff0000, v207
	v_and_b32_e32 v122, 0xffff0000, v206
	v_lshlrev_b32_e32 v125, 16, v207
	v_lshlrev_b32_e32 v124, 16, v206
	v_lshl_add_u64 v[118:119], s[12:13], 0, v[204:205]
	v_lshl_add_u64 v[118:119], v[118:119], 0, v[164:165]
	v_pk_add_f32 v[110:111], v[110:111], v[104:105] op_sel_hi:[1,0]
	v_pk_add_f32 v[120:121], v[120:121], v[104:105] op_sel_hi:[1,0]
	v_pk_add_f32 v[126:127], v[126:127], v[104:105] op_sel_hi:[1,0]
	v_pk_add_f32 v[104:105], v[116:117], v[104:105] op_sel_hi:[1,0]
	v_pk_mul_f32 v[106:107], v[110:111], v[106:107]
	v_pk_mul_f32 v[108:109], v[120:121], v[108:109]
	v_pk_mul_f32 v[110:111], v[126:127], v[122:123]
	v_pk_mul_f32 v[104:105], v[104:105], v[124:125]
	v_and_b32_sdwa v120, v107, v233 dst_sel:DWORD dst_unused:UNUSED_PAD src0_sel:WORD_1 src1_sel:DWORD
	v_and_b32_sdwa v121, v106, v233 dst_sel:DWORD dst_unused:UNUSED_PAD src0_sel:WORD_1 src1_sel:DWORD
	v_and_b32_sdwa v116, v109, v233 dst_sel:DWORD dst_unused:UNUSED_PAD src0_sel:WORD_1 src1_sel:DWORD
	v_and_b32_sdwa v117, v108, v233 dst_sel:DWORD dst_unused:UNUSED_PAD src0_sel:WORD_1 src1_sel:DWORD
	v_and_b32_sdwa v122, v105, v233 dst_sel:DWORD dst_unused:UNUSED_PAD src0_sel:WORD_1 src1_sel:DWORD
	v_and_b32_sdwa v123, v104, v233 dst_sel:DWORD dst_unused:UNUSED_PAD src0_sel:WORD_1 src1_sel:DWORD
	v_and_b32_sdwa v124, v111, v233 dst_sel:DWORD dst_unused:UNUSED_PAD src0_sel:WORD_1 src1_sel:DWORD
	v_and_b32_sdwa v125, v110, v233 dst_sel:DWORD dst_unused:UNUSED_PAD src0_sel:WORD_1 src1_sel:DWORD
	v_add3_u32 v107, v107, v120, s37
	v_add3_u32 v106, v106, v121, s37
	v_add3_u32 v108, v108, v117, s37
	v_add3_u32 v109, v109, v116, s37
	v_add3_u32 v116, v104, v123, s37
	v_add3_u32 v117, v105, v122, s37
	v_add3_u32 v104, v111, v124, s37
	v_add3_u32 v105, v110, v125, s37
	v_and_b32_e32 v107, 0xffff0000, v107
	v_and_b32_e32 v106, 0xffff0000, v106
	v_and_b32_e32 v110, 0xffff0000, v104
	v_and_b32_e32 v111, 0xffff0000, v105
	v_or_b32_sdwa v105, v107, v109 dst_sel:DWORD dst_unused:UNUSED_PAD src0_sel:DWORD src1_sel:WORD_1
	v_or_b32_sdwa v104, v106, v108 dst_sel:DWORD dst_unused:UNUSED_PAD src0_sel:DWORD src1_sel:WORD_1
	v_or_b32_sdwa v107, v110, v117 dst_sel:DWORD dst_unused:UNUSED_PAD src0_sel:DWORD src1_sel:WORD_1
	v_or_b32_sdwa v106, v111, v116 dst_sel:DWORD dst_unused:UNUSED_PAD src0_sel:DWORD src1_sel:WORD_1
	s_nop 1
	v_permlane32_swap_b32_e32 v104, v106
	v_permlane32_swap_b32_e32 v105, v107
	s_nop 1
	v_permlane16_swap_b32_e32 v104, v106
	v_permlane16_swap_b32_e32 v105, v107
	v_mov_b32_e32 v142, v104
	v_mov_b32_e32 v143, v105
	v_mov_b32_e32 v144, v106
	v_mov_b32_e32 v145, v107
	global_store_dwordx4 v[118:119], v[142:145], off
	v_mov_b32_e32 v104, v3
	v_mov_b32_e32 v110, v101
	v_mov_b32_e32 v111, v103
	v_and_b32_e32 v107, 0xffff0000, v195
	v_and_b32_e32 v106, 0xffff0000, v194
	v_mov_b32_e32 v101, v102
	v_mov_b32_e32 v118, v97
	v_mov_b32_e32 v119, v99
	v_mov_b32_e32 v97, v98
	v_lshlrev_b32_e32 v109, 16, v195
	v_lshlrev_b32_e32 v108, 16, v194
	v_and_b32_e32 v103, 0xffff0000, v193
	v_and_b32_e32 v102, 0xffff0000, v192
	v_lshlrev_b32_e32 v117, 16, v193
	v_lshlrev_b32_e32 v116, 16, v192
	v_lshl_add_u64 v[98:99], s[12:13], 0, v[190:191]
	v_lshl_add_u64 v[98:99], v[98:99], 0, v[164:165]
	v_pk_add_f32 v[110:111], v[110:111], v[104:105] op_sel_hi:[1,0]
	v_pk_add_f32 v[100:101], v[100:101], v[104:105] op_sel_hi:[1,0]
	v_pk_add_f32 v[118:119], v[118:119], v[104:105] op_sel_hi:[1,0]
	v_pk_add_f32 v[96:97], v[96:97], v[104:105] op_sel_hi:[1,0]
	v_pk_mul_f32 v[104:105], v[110:111], v[106:107]
	v_pk_mul_f32 v[100:101], v[100:101], v[108:109]
	v_pk_mul_f32 v[102:103], v[118:119], v[102:103]
	v_pk_mul_f32 v[96:97], v[96:97], v[116:117]
	v_and_b32_sdwa v108, v105, v233 dst_sel:DWORD dst_unused:UNUSED_PAD src0_sel:WORD_1 src1_sel:DWORD
	v_and_b32_sdwa v109, v104, v233 dst_sel:DWORD dst_unused:UNUSED_PAD src0_sel:WORD_1 src1_sel:DWORD
	v_and_b32_sdwa v106, v101, v233 dst_sel:DWORD dst_unused:UNUSED_PAD src0_sel:WORD_1 src1_sel:DWORD
	v_and_b32_sdwa v107, v100, v233 dst_sel:DWORD dst_unused:UNUSED_PAD src0_sel:WORD_1 src1_sel:DWORD
	v_and_b32_sdwa v110, v97, v233 dst_sel:DWORD dst_unused:UNUSED_PAD src0_sel:WORD_1 src1_sel:DWORD
	v_and_b32_sdwa v111, v96, v233 dst_sel:DWORD dst_unused:UNUSED_PAD src0_sel:WORD_1 src1_sel:DWORD
	v_and_b32_sdwa v116, v103, v233 dst_sel:DWORD dst_unused:UNUSED_PAD src0_sel:WORD_1 src1_sel:DWORD
	v_and_b32_sdwa v117, v102, v233 dst_sel:DWORD dst_unused:UNUSED_PAD src0_sel:WORD_1 src1_sel:DWORD
	v_add3_u32 v105, v105, v108, s37
	v_add3_u32 v104, v104, v109, s37
	v_add3_u32 v100, v100, v107, s37
	v_add3_u32 v101, v101, v106, s37
	v_add3_u32 v106, v96, v111, s37
	v_add3_u32 v107, v97, v110, s37
	v_add3_u32 v96, v103, v116, s37
	v_add3_u32 v97, v102, v117, s37
	v_and_b32_e32 v102, 0xffff0000, v105
	v_and_b32_e32 v103, 0xffff0000, v104
	v_and_b32_e32 v104, 0xffff0000, v96
	v_and_b32_e32 v105, 0xffff0000, v97
; __device__ __forceinline__ unsigned pk2(float lo, float hi) { return f2bf(lo) | (f2bf(hi) << 16); }
; __device__ __forceinline__ float bflo(unsigned w) { return __uint_as_float(w << 16); }
; __device__ __forceinline__ float bfhi(unsigned w) { return __uint_as_float(w & 0xffff0000u); }
; __device__ __forceinline__ void spatial_phase(const Frame& F, bf16* Z, const float* stats, const float* lng, const float* lnb, const float* ws, const float* bs, bool do_store = true) {
;     ...
;         for (int m = 0; m < 8; ++m) { const int t = 16 * m + fr; const float b = bs[g * 128 + t];
; #pragma unroll
;             for (int n = 0; n < 2; ++n) { const int c = 32 * w + 16 * n + 4 * fq; v2u* p = (v2u*)(Z + (row0 + t) * 4096 + 256 * g + c); const v2u u2 = uu[m][n];
;                 const float o0 = bflo(u2.x) * (acc[m][n][0] + b), o1 = bfhi(u2.x) * (acc[m][n][1] + b), o2 = bflo(u2.y) * (acc[m][n][2] + b), o3 = bfhi(u2.y) * (acc[m][n][3] + b);
;                 if (do_store) *p = (v2u){pk2(o0, o1), pk2(o2, o3)}; } }
	v_or_b32_sdwa v97, v102, v101 dst_sel:DWORD dst_unused:UNUSED_PAD src0_sel:DWORD src1_sel:WORD_1
	v_or_b32_sdwa v96, v103, v100 dst_sel:DWORD dst_unused:UNUSED_PAD src0_sel:DWORD src1_sel:WORD_1
	v_or_b32_sdwa v101, v104, v107 dst_sel:DWORD dst_unused:UNUSED_PAD src0_sel:DWORD src1_sel:WORD_1
	v_or_b32_sdwa v100, v105, v106 dst_sel:DWORD dst_unused:UNUSED_PAD src0_sel:DWORD src1_sel:WORD_1
	s_nop 1
	v_permlane32_swap_b32_e32 v96, v100
	v_permlane32_swap_b32_e32 v97, v101
	s_nop 1
	v_permlane16_swap_b32_e32 v96, v100
	v_permlane16_swap_b32_e32 v97, v101
	v_mov_b32_e32 v142, v96
	v_mov_b32_e32 v143, v97
	v_mov_b32_e32 v144, v100
	v_mov_b32_e32 v145, v101
	global_store_dwordx4 v[98:99], v[142:145], off
	v_mov_b32_e32 v96, v4
	v_mov_b32_e32 v102, v93
	v_mov_b32_e32 v103, v95
	v_and_b32_e32 v99, 0xffff0000, v189
	v_and_b32_e32 v98, 0xffff0000, v188
	v_mov_b32_e32 v93, v94
	v_mov_b32_e32 v106, v89
	v_mov_b32_e32 v107, v91
	v_mov_b32_e32 v89, v90
	v_lshlrev_b32_e32 v101, 16, v189
	v_lshlrev_b32_e32 v100, 16, v188
	v_and_b32_e32 v95, 0xffff0000, v187
	v_and_b32_e32 v94, 0xffff0000, v186
	v_lshlrev_b32_e32 v105, 16, v187
	v_lshlrev_b32_e32 v104, 16, v186
	v_lshl_add_u64 v[90:91], s[12:13], 0, v[184:185]
	v_lshl_add_u64 v[90:91], v[90:91], 0, v[164:165]
	v_pk_add_f32 v[102:103], v[102:103], v[96:97] op_sel_hi:[1,0]
	v_pk_add_f32 v[92:93], v[92:93], v[96:97] op_sel_hi:[1,0]
	v_pk_add_f32 v[106:107], v[106:107], v[96:97] op_sel_hi:[1,0]
	v_pk_add_f32 v[88:89], v[88:89], v[96:97] op_sel_hi:[1,0]
	v_pk_mul_f32 v[96:97], v[102:103], v[98:99]
	v_pk_mul_f32 v[92:93], v[92:93], v[100:101]
	v_pk_mul_f32 v[94:95], v[106:107], v[94:95]
	v_pk_mul_f32 v[88:89], v[88:89], v[104:105]
	v_and_b32_sdwa v100, v97, v233 dst_sel:DWORD dst_unused:UNUSED_PAD src0_sel:WORD_1 src1_sel:DWORD
	v_and_b32_sdwa v101, v96, v233 dst_sel:DWORD dst_unused:UNUSED_PAD src0_sel:WORD_1 src1_sel:DWORD
	v_and_b32_sdwa v98, v93, v233 dst_sel:DWORD dst_unused:UNUSED_PAD src0_sel:WORD_1 src1_sel:DWORD
	v_and_b32_sdwa v99, v92, v233 dst_sel:DWORD dst_unused:UNUSED_PAD src0_sel:WORD_1 src1_sel:DWORD
	v_and_b32_sdwa v102, v89, v233 dst_sel:DWORD dst_unused:UNUSED_PAD src0_sel:WORD_1 src1_sel:DWORD
	v_and_b32_sdwa v103, v88, v233 dst_sel:DWORD dst_unused:UNUSED_PAD src0_sel:WORD_1 src1_sel:DWORD
	v_and_b32_sdwa v104, v95, v233 dst_sel:DWORD dst_unused:UNUSED_PAD src0_sel:WORD_1 src1_sel:DWORD
	v_and_b32_sdwa v105, v94, v233 dst_sel:DWORD dst_unused:UNUSED_PAD src0_sel:WORD_1 src1_sel:DWORD
	v_add3_u32 v97, v97, v100, s37
	v_add3_u32 v96, v96, v101, s37
	v_add3_u32 v92, v92, v99, s37
	v_add3_u32 v93, v93, v98, s37
	v_add3_u32 v98, v88, v103, s37
	v_add3_u32 v99, v89, v102, s37
	v_add3_u32 v88, v95, v104, s37
	v_add3_u32 v89, v94, v105, s37
	v_and_b32_e32 v94, 0xffff0000, v97
	v_and_b32_e32 v95, 0xffff0000, v96
	v_and_b32_e32 v96, 0xffff0000, v88
	v_and_b32_e32 v97, 0xffff0000, v89
	v_or_b32_sdwa v89, v94, v93 dst_sel:DWORD dst_unused:UNUSED_PAD src0_sel:DWORD src1_sel:WORD_1
	v_or_b32_sdwa v88, v95, v92 dst_sel:DWORD dst_unused:UNUSED_PAD src0_sel:DWORD src1_sel:WORD_1
	v_or_b32_sdwa v93, v96, v99 dst_sel:DWORD dst_unused:UNUSED_PAD src0_sel:DWORD src1_sel:WORD_1
	v_or_b32_sdwa v92, v97, v98 dst_sel:DWORD dst_unused:UNUSED_PAD src0_sel:DWORD src1_sel:WORD_1
	s_nop 1
	v_permlane32_swap_b32_e32 v88, v92
	v_permlane32_swap_b32_e32 v89, v93
	s_nop 1
	v_permlane16_swap_b32_e32 v88, v92
	v_permlane16_swap_b32_e32 v89, v93
	v_mov_b32_e32 v142, v88
	v_mov_b32_e32 v143, v89
	v_mov_b32_e32 v144, v92
	v_mov_b32_e32 v145, v93
	global_store_dwordx4 v[90:91], v[142:145], off
	v_mov_b32_e32 v88, v5
	v_mov_b32_e32 v94, v85
	v_mov_b32_e32 v95, v87
	v_and_b32_e32 v91, 0xffff0000, v183
	v_and_b32_e32 v90, 0xffff0000, v182
	v_mov_b32_e32 v85, v86
	v_mov_b32_e32 v98, v81
	v_mov_b32_e32 v99, v83
	v_mov_b32_e32 v81, v82
	v_lshlrev_b32_e32 v93, 16, v183
	v_lshlrev_b32_e32 v92, 16, v182
	v_and_b32_e32 v87, 0xffff0000, v181
	v_and_b32_e32 v86, 0xffff0000, v180
	v_lshlrev_b32_e32 v97, 16, v181
	v_lshlrev_b32_e32 v96, 16, v180
	v_lshl_add_u64 v[82:83], s[12:13], 0, v[178:179]
	v_lshl_add_u64 v[82:83], v[82:83], 0, v[164:165]
	v_pk_add_f32 v[94:95], v[94:95], v[88:89] op_sel_hi:[1,0]
	v_pk_add_f32 v[84:85], v[84:85], v[88:89] op_sel_hi:[1,0]
	v_pk_add_f32 v[98:99], v[98:99], v[88:89] op_sel_hi:[1,0]
	v_pk_add_f32 v[80:81], v[80:81], v[88:89] op_sel_hi:[1,0]
	v_pk_mul_f32 v[88:89], v[94:95], v[90:91]
	v_pk_mul_f32 v[84:85], v[84:85], v[92:93]
	v_pk_mul_f32 v[86:87], v[98:99], v[86:87]
	v_pk_mul_f32 v[80:81], v[80:81], v[96:97]
	v_and_b32_sdwa v92, v89, v233 dst_sel:DWORD dst_unused:UNUSED_PAD src0_sel:WORD_1 src1_sel:DWORD
	v_and_b32_sdwa v93, v88, v233 dst_sel:DWORD dst_unused:UNUSED_PAD src0_sel:WORD_1 src1_sel:DWORD
	v_and_b32_sdwa v90, v85, v233 dst_sel:DWORD dst_unused:UNUSED_PAD src0_sel:WORD_1 src1_sel:DWORD
	v_and_b32_sdwa v91, v84, v233 dst_sel:DWORD dst_unused:UNUSED_PAD src0_sel:WORD_1 src1_sel:DWORD
	v_and_b32_sdwa v94, v81, v233 dst_sel:DWORD dst_unused:UNUSED_PAD src0_sel:WORD_1 src1_sel:DWORD
	v_and_b32_sdwa v95, v80, v233 dst_sel:DWORD dst_unused:UNUSED_PAD src0_sel:WORD_1 src1_sel:DWORD
	v_and_b32_sdwa v96, v87, v233 dst_sel:DWORD dst_unused:UNUSED_PAD src0_sel:WORD_1 src1_sel:DWORD
	v_and_b32_sdwa v97, v86, v233 dst_sel:DWORD dst_unused:UNUSED_PAD src0_sel:WORD_1 src1_sel:DWORD
	v_add3_u32 v89, v89, v92, s37
	v_add3_u32 v88, v88, v93, s37
	v_add3_u32 v84, v84, v91, s37
	v_add3_u32 v85, v85, v90, s37
	v_add3_u32 v90, v80, v95, s37
	v_add3_u32 v91, v81, v94, s37
	v_add3_u32 v80, v87, v96, s37
	v_add3_u32 v81, v86, v97, s37
	v_and_b32_e32 v86, 0xffff0000, v89
	v_and_b32_e32 v87, 0xffff0000, v88
; __device__ __forceinline__ unsigned pk2(float lo, float hi) { return f2bf(lo) | (f2bf(hi) << 16); }
; __device__ __forceinline__ float bflo(unsigned w) { return __uint_as_float(w << 16); }
; __device__ __forceinline__ float bfhi(unsigned w) { return __uint_as_float(w & 0xffff0000u); }
; __device__ __forceinline__ void spatial_phase(const Frame& F, bf16* Z, const float* stats, const float* lng, const float* lnb, const float* ws, const float* bs, bool do_store = true) {
;     ...
;         for (int m = 0; m < 8; ++m) { const int t = 16 * m + fr; const float b = bs[g * 128 + t];
; #pragma unroll
;             for (int n = 0; n < 2; ++n) { const int c = 32 * w + 16 * n + 4 * fq; v2u* p = (v2u*)(Z + (row0 + t) * 4096 + 256 * g + c); const v2u u2 = uu[m][n];
;                 const float o0 = bflo(u2.x) * (acc[m][n][0] + b), o1 = bfhi(u2.x) * (acc[m][n][1] + b), o2 = bflo(u2.y) * (acc[m][n][2] + b), o3 = bfhi(u2.y) * (acc[m][n][3] + b);
;                 if (do_store) *p = (v2u){pk2(o0, o1), pk2(o2, o3)}; } }
	v_and_b32_e32 v88, 0xffff0000, v80
	v_and_b32_e32 v89, 0xffff0000, v81
	v_or_b32_sdwa v81, v86, v85 dst_sel:DWORD dst_unused:UNUSED_PAD src0_sel:DWORD src1_sel:WORD_1
	v_or_b32_sdwa v80, v87, v84 dst_sel:DWORD dst_unused:UNUSED_PAD src0_sel:DWORD src1_sel:WORD_1
	v_or_b32_sdwa v85, v88, v91 dst_sel:DWORD dst_unused:UNUSED_PAD src0_sel:DWORD src1_sel:WORD_1
	v_or_b32_sdwa v84, v89, v90 dst_sel:DWORD dst_unused:UNUSED_PAD src0_sel:DWORD src1_sel:WORD_1
	s_nop 1
	v_permlane32_swap_b32_e32 v80, v84
	v_permlane32_swap_b32_e32 v81, v85
	s_nop 1
	v_permlane16_swap_b32_e32 v80, v84
	v_permlane16_swap_b32_e32 v81, v85
	v_mov_b32_e32 v142, v80
	v_mov_b32_e32 v143, v81
	v_mov_b32_e32 v144, v84
	v_mov_b32_e32 v145, v85
	global_store_dwordx4 v[82:83], v[142:145], off
	v_mov_b32_e32 v80, v6
	v_mov_b32_e32 v86, v77
	v_mov_b32_e32 v87, v79
	v_and_b32_e32 v83, 0xffff0000, v177
	v_and_b32_e32 v82, 0xffff0000, v176
	v_mov_b32_e32 v77, v78
	v_mov_b32_e32 v90, v73
	v_mov_b32_e32 v91, v75
	v_mov_b32_e32 v73, v74
	v_lshlrev_b32_e32 v85, 16, v177
	v_lshlrev_b32_e32 v84, 16, v176
	v_and_b32_e32 v79, 0xffff0000, v175
	v_and_b32_e32 v78, 0xffff0000, v174
	v_lshlrev_b32_e32 v89, 16, v175
	v_lshlrev_b32_e32 v88, 16, v174
	v_lshl_add_u64 v[74:75], s[12:13], 0, v[172:173]
	v_lshl_add_u64 v[74:75], v[74:75], 0, v[164:165]
	v_pk_add_f32 v[86:87], v[86:87], v[80:81] op_sel_hi:[1,0]
	v_pk_add_f32 v[76:77], v[76:77], v[80:81] op_sel_hi:[1,0]
	v_pk_add_f32 v[90:91], v[90:91], v[80:81] op_sel_hi:[1,0]
	v_pk_add_f32 v[72:73], v[72:73], v[80:81] op_sel_hi:[1,0]
	v_pk_mul_f32 v[80:81], v[86:87], v[82:83]
	v_pk_mul_f32 v[76:77], v[76:77], v[84:85]
	v_pk_mul_f32 v[78:79], v[90:91], v[78:79]
	v_pk_mul_f32 v[72:73], v[72:73], v[88:89]
	v_and_b32_sdwa v84, v81, v233 dst_sel:DWORD dst_unused:UNUSED_PAD src0_sel:WORD_1 src1_sel:DWORD
	v_and_b32_sdwa v85, v80, v233 dst_sel:DWORD dst_unused:UNUSED_PAD src0_sel:WORD_1 src1_sel:DWORD
	v_and_b32_sdwa v82, v77, v233 dst_sel:DWORD dst_unused:UNUSED_PAD src0_sel:WORD_1 src1_sel:DWORD
	v_and_b32_sdwa v83, v76, v233 dst_sel:DWORD dst_unused:UNUSED_PAD src0_sel:WORD_1 src1_sel:DWORD
	v_and_b32_sdwa v86, v73, v233 dst_sel:DWORD dst_unused:UNUSED_PAD src0_sel:WORD_1 src1_sel:DWORD
	v_and_b32_sdwa v87, v72, v233 dst_sel:DWORD dst_unused:UNUSED_PAD src0_sel:WORD_1 src1_sel:DWORD
	v_and_b32_sdwa v88, v79, v233 dst_sel:DWORD dst_unused:UNUSED_PAD src0_sel:WORD_1 src1_sel:DWORD
	v_and_b32_sdwa v89, v78, v233 dst_sel:DWORD dst_unused:UNUSED_PAD src0_sel:WORD_1 src1_sel:DWORD
	v_add3_u32 v81, v81, v84, s37
	v_add3_u32 v80, v80, v85, s37
	v_add3_u32 v76, v76, v83, s37
	v_add3_u32 v77, v77, v82, s37
	v_add3_u32 v82, v72, v87, s37
	v_add3_u32 v83, v73, v86, s37
	v_add3_u32 v72, v79, v88, s37
	v_add3_u32 v73, v78, v89, s37
	v_and_b32_e32 v78, 0xffff0000, v81
	v_and_b32_e32 v79, 0xffff0000, v80
	v_and_b32_e32 v80, 0xffff0000, v72
	v_and_b32_e32 v81, 0xffff0000, v73
	v_or_b32_sdwa v73, v78, v77 dst_sel:DWORD dst_unused:UNUSED_PAD src0_sel:DWORD src1_sel:WORD_1
	v_or_b32_sdwa v72, v79, v76 dst_sel:DWORD dst_unused:UNUSED_PAD src0_sel:DWORD src1_sel:WORD_1
	v_or_b32_sdwa v77, v80, v83 dst_sel:DWORD dst_unused:UNUSED_PAD src0_sel:DWORD src1_sel:WORD_1
	v_or_b32_sdwa v76, v81, v82 dst_sel:DWORD dst_unused:UNUSED_PAD src0_sel:DWORD src1_sel:WORD_1
	s_nop 1
	v_permlane32_swap_b32_e32 v72, v76
	v_permlane32_swap_b32_e32 v73, v77
	s_nop 1
	v_permlane16_swap_b32_e32 v72, v76
	v_permlane16_swap_b32_e32 v73, v77
	v_mov_b32_e32 v142, v72
	v_mov_b32_e32 v143, v73
	v_mov_b32_e32 v144, v76
	v_mov_b32_e32 v145, v77
	global_store_dwordx4 v[74:75], v[142:145], off
	v_mov_b32_e32 v72, v7
	v_mov_b32_e32 v78, v69
	v_mov_b32_e32 v79, v71
	v_and_b32_e32 v75, 0xffff0000, v171
	v_and_b32_e32 v74, 0xffff0000, v170
	v_mov_b32_e32 v69, v70
	v_mov_b32_e32 v82, v65
	v_mov_b32_e32 v83, v67
	v_mov_b32_e32 v65, v66
	v_lshlrev_b32_e32 v77, 16, v171
	v_lshlrev_b32_e32 v76, 16, v170
	v_and_b32_e32 v71, 0xffff0000, v169
	v_and_b32_e32 v70, 0xffff0000, v168
	v_lshlrev_b32_e32 v81, 16, v169
	v_lshlrev_b32_e32 v80, 16, v168
	v_lshl_add_u64 v[66:67], s[12:13], 0, v[166:167]
	v_lshl_add_u64 v[66:67], v[66:67], 0, v[164:165]
	v_pk_add_f32 v[78:79], v[78:79], v[72:73] op_sel_hi:[1,0]
	v_pk_add_f32 v[68:69], v[68:69], v[72:73] op_sel_hi:[1,0]
	v_pk_add_f32 v[82:83], v[82:83], v[72:73] op_sel_hi:[1,0]
	v_pk_add_f32 v[64:65], v[64:65], v[72:73] op_sel_hi:[1,0]
	v_pk_mul_f32 v[72:73], v[78:79], v[74:75]
	v_pk_mul_f32 v[68:69], v[68:69], v[76:77]
	v_pk_mul_f32 v[70:71], v[82:83], v[70:71]
	v_pk_mul_f32 v[64:65], v[64:65], v[80:81]
	v_and_b32_sdwa v76, v73, v233 dst_sel:DWORD dst_unused:UNUSED_PAD src0_sel:WORD_1 src1_sel:DWORD
	v_and_b32_sdwa v77, v72, v233 dst_sel:DWORD dst_unused:UNUSED_PAD src0_sel:WORD_1 src1_sel:DWORD
	v_and_b32_sdwa v74, v69, v233 dst_sel:DWORD dst_unused:UNUSED_PAD src0_sel:WORD_1 src1_sel:DWORD
	v_and_b32_sdwa v75, v68, v233 dst_sel:DWORD dst_unused:UNUSED_PAD src0_sel:WORD_1 src1_sel:DWORD
	v_and_b32_sdwa v78, v65, v233 dst_sel:DWORD dst_unused:UNUSED_PAD src0_sel:WORD_1 src1_sel:DWORD
	v_and_b32_sdwa v79, v64, v233 dst_sel:DWORD dst_unused:UNUSED_PAD src0_sel:WORD_1 src1_sel:DWORD
	v_and_b32_sdwa v80, v71, v233 dst_sel:DWORD dst_unused:UNUSED_PAD src0_sel:WORD_1 src1_sel:DWORD
	v_and_b32_sdwa v81, v70, v233 dst_sel:DWORD dst_unused:UNUSED_PAD src0_sel:WORD_1 src1_sel:DWORD
	v_add3_u32 v73, v73, v76, s37
	v_add3_u32 v72, v72, v77, s37
	v_add3_u32 v68, v68, v75, s37
	v_add3_u32 v69, v69, v74, s37
	v_add3_u32 v74, v64, v79, s37
	v_add3_u32 v75, v65, v78, s37
	v_add3_u32 v64, v71, v80, s37
	v_add3_u32 v65, v70, v81, s37
	v_and_b32_e32 v70, 0xffff0000, v73
	v_and_b32_e32 v71, 0xffff0000, v72
	v_and_b32_e32 v72, 0xffff0000, v64
	v_and_b32_e32 v73, 0xffff0000, v65
	v_or_b32_sdwa v65, v70, v69 dst_sel:DWORD dst_unused:UNUSED_PAD src0_sel:DWORD src1_sel:WORD_1
	v_or_b32_sdwa v64, v71, v68 dst_sel:DWORD dst_unused:UNUSED_PAD src0_sel:DWORD src1_sel:WORD_1
	v_or_b32_sdwa v69, v72, v75 dst_sel:DWORD dst_unused:UNUSED_PAD src0_sel:DWORD src1_sel:WORD_1
	v_or_b32_sdwa v68, v73, v74 dst_sel:DWORD dst_unused:UNUSED_PAD src0_sel:DWORD src1_sel:WORD_1
	s_nop 1
	v_permlane32_swap_b32_e32 v64, v68
	v_permlane32_swap_b32_e32 v65, v69
	s_nop 1
	v_permlane16_swap_b32_e32 v64, v68
	v_permlane16_swap_b32_e32 v65, v69
	v_mov_b32_e32 v142, v64
	v_mov_b32_e32 v143, v65
	v_mov_b32_e32 v144, v68
	v_mov_b32_e32 v145, v69
	global_store_dwordx4 v[66:67], v[142:145], off
	s_branch .LBB0_716

; #define PG8_STAGE(bufoff, gbase, voff) do { _Pragma("unroll") for (int _i = 0; _i < 2; ++_i) \
;         __builtin_amdgcn_global_load_lds((const unsigned*)((const char*)(gbase) + (voff)[_i]), (PG8_LAS unsigned*)(lds + (bufoff) + ldsw + _i * 8192), 16, 0, 0); } while (0)
; #define PG8_LDA(dst, b, h) do { _Pragma("unroll") for (int m = 0; m < 4; ++m) _Pragma("unroll") for (int k = 0; k < 2; ++k) dst[m][k] = *(const PG8_LAS bf16x8*)(lds + PG8_SA(b, h) + aoff + m * 2048 + k * 1024); } while (0)
; #define PG8_MMA(ai, bj, At, Bt) do { __builtin_amdgcn_s_setprio(1); _Pragma("unroll") for (int m = 0; m < 4; ++m) _Pragma("unroll") for (int n = 0; n < 2; ++n) _Pragma("unroll") for (int k = 0; k < 2; ++k) \
;         acc[ai][bj][m][n] = __builtin_amdgcn_mfma_f32_16x16x32_bf16(Bt[n][k], At[m][k], acc[ai][bj][m][n], 0, 0, 0); __builtin_amdgcn_s_setprio(0); } while (0)
; #define PG8_WAIT_V(n) asm volatile("s_waitcnt vmcnt(" #n ")" ::: "memory")
; #define PG8_WAIT_L(n) asm volatile("s_waitcnt lgkmcnt(" #n ")" ::: "memory")
; #define PG8_BAR __builtin_amdgcn_s_barrier()
; #define PG8_SCHED __builtin_amdgcn_sched_barrier(0)
; template <class Epi, class Sched, bool ALIGN_EPI = false, bool SP2 = false>
; __device__ __forceinline__ void gemm_phase(PG8_LAS unsigned char* lds, const Gemm g, const Sched& S, const Epi& E, const int tid_in) {
;     ...
;             PG8_WAIT_V(8); PG8_WAIT_L(0); PG8_BAR; PG8_MMA(0, 0, At, B0); PG8_MMA(0, 1, At, B1); PG8_BAR; PG8_SCHED;
;             PG8_LDA(At, 1, 1); PG8_STAGE(PG8_SB(1, 0), b3, voffB); PG8_STAGE(PG8_SB(1, 1), b3 + hstepB, voffB); PG8_STAGE(PG8_SA(1, 0), a3, voffA);
;             PG8_WAIT_V(8); PG8_WAIT_L(0); PG8_BAR; PG8_MMA(1, 0, At, B0); PG8_MMA(1, 1, At, B1); PG8_BAR; PG8_SCHED;
.Ltl_gout_15_j:
	s_waitcnt vmcnt(8)
	s_waitcnt lgkmcnt(0)
	s_barrier
	s_setprio 1
	s_waitcnt lgkmcnt(0)
	v_mfma_f32_16x16x32_bf16 v[64:67], v[152:155], v[184:187], v[64:67]
	v_mfma_f32_16x16x32_bf16 v[68:71], v[160:163], v[184:187], v[68:71]
	v_mfma_f32_16x16x32_bf16 v[80:83], v[152:155], v[192:195], v[80:83]
	v_mfma_f32_16x16x32_bf16 v[84:87], v[160:163], v[192:195], v[84:87]
	v_mfma_f32_16x16x32_bf16 v[96:99], v[152:155], v[200:203], v[96:99]
	v_mfma_f32_16x16x32_bf16 v[100:103], v[160:163], v[200:203], v[100:103]
	v_mfma_f32_16x16x32_bf16 v[116:119], v[152:155], v[208:211], v[116:119]
	v_mfma_f32_16x16x32_bf16 v[120:123], v[160:163], v[208:211], v[120:123]
	v_mfma_f32_16x16x32_bf16 v[64:67], v[156:159], v[188:191], v[64:67]
	v_mfma_f32_16x16x32_bf16 v[68:71], v[164:167], v[188:191], v[68:71]
	v_mfma_f32_16x16x32_bf16 v[80:83], v[156:159], v[196:199], v[80:83]
	v_mfma_f32_16x16x32_bf16 v[84:87], v[164:167], v[196:199], v[84:87]
	v_mfma_f32_16x16x32_bf16 v[96:99], v[156:159], v[204:207], v[96:99]
	v_mfma_f32_16x16x32_bf16 v[100:103], v[164:167], v[204:207], v[100:103]
	v_mfma_f32_16x16x32_bf16 v[116:119], v[156:159], v[212:215], v[116:119]
	v_mfma_f32_16x16x32_bf16 v[120:123], v[164:167], v[212:215], v[120:123]
	s_setprio 0
	s_setprio 1
	v_mfma_f32_16x16x32_bf16 v[72:75], v[168:171], v[184:187], v[72:75]
	v_mfma_f32_16x16x32_bf16 v[76:79], v[176:179], v[184:187], v[76:79]
	v_mfma_f32_16x16x32_bf16 v[88:91], v[168:171], v[192:195], v[88:91]
	v_mfma_f32_16x16x32_bf16 v[92:95], v[176:179], v[192:195], v[92:95]
	v_mfma_f32_16x16x32_bf16 v[104:107], v[168:171], v[200:203], v[104:107]
	v_mfma_f32_16x16x32_bf16 v[108:111], v[176:179], v[200:203], v[108:111]
	v_mfma_f32_16x16x32_bf16 v[124:127], v[168:171], v[208:211], v[124:127]
	v_mfma_f32_16x16x32_bf16 v[128:131], v[176:179], v[208:211], v[128:131]
	v_mfma_f32_16x16x32_bf16 v[72:75], v[172:175], v[188:191], v[72:75]
	v_mfma_f32_16x16x32_bf16 v[76:79], v[180:183], v[188:191], v[76:79]
	v_mfma_f32_16x16x32_bf16 v[88:91], v[172:175], v[196:199], v[88:91]
	v_mfma_f32_16x16x32_bf16 v[92:95], v[180:183], v[196:199], v[92:95]
	v_mfma_f32_16x16x32_bf16 v[104:107], v[172:175], v[204:207], v[104:107]
	v_mfma_f32_16x16x32_bf16 v[108:111], v[180:183], v[204:207], v[108:111]
	v_mfma_f32_16x16x32_bf16 v[124:127], v[172:175], v[212:215], v[124:127]
	v_mfma_f32_16x16x32_bf16 v[128:131], v[180:183], v[212:215], v[128:131]
	s_setprio 0
	s_add_i32 s45, s45, 2
	s_add_u32 s46, s46, 0x100
	s_addc_u32 s47, s47, 0
	s_cmp_gt_u32 s45, 29
	s_barrier
	s_cbranch_scc0 .LBB0_794
	s_and_b64 vcc, exec, s[22:23]
	s_cbranch_vccz .LBB0_797
	s_barrier

; #define PG8_STAGE(bufoff, gbase, voff) do { _Pragma("unroll") for (int _i = 0; _i < 2; ++_i) \
;         __builtin_amdgcn_global_load_lds((const unsigned*)((const char*)(gbase) + (voff)[_i]), (PG8_LAS unsigned*)(lds + (bufoff) + ldsw + _i * 8192), 16, 0, 0); } while (0)
; #define PG8_LDA(dst, b, h) do { _Pragma("unroll") for (int m = 0; m < 4; ++m) _Pragma("unroll") for (int k = 0; k < 2; ++k) dst[m][k] = *(const PG8_LAS bf16x8*)(lds + PG8_SA(b, h) + aoff + m * 2048 + k * 1024); } while (0)
; #define PG8_LDB(dst, b, h) do { _Pragma("unroll") for (int n = 0; n < 2; ++n) _Pragma("unroll") for (int k = 0; k < 2; ++k) dst[n][k] = *(const PG8_LAS bf16x8*)(lds + PG8_SB(b, h) + boff + n * 2048 + k * 1024); } while (0)
; #define PG8_MMA(ai, bj, At, Bt) do { __builtin_amdgcn_s_setprio(1); _Pragma("unroll") for (int m = 0; m < 4; ++m) _Pragma("unroll") for (int n = 0; n < 2; ++n) _Pragma("unroll") for (int k = 0; k < 2; ++k) \
;         acc[ai][bj][m][n] = __builtin_amdgcn_mfma_f32_16x16x32_bf16(Bt[n][k], At[m][k], acc[ai][bj][m][n], 0, 0, 0); __builtin_amdgcn_s_setprio(0); } while (0)
; #define PG8_WAIT_V(n) asm volatile("s_waitcnt vmcnt(" #n ")" ::: "memory")
; #define PG8_WAIT_L(n) asm volatile("s_waitcnt lgkmcnt(" #n ")" ::: "memory")
; template <class Epi, class Sched, bool ALIGN_EPI = false, bool SP2 = false>
; __device__ __forceinline__ void gemm_phase(PG8_LAS unsigned char* lds, const Gemm g, const Sched& S, const Epi& E, const int tid_in) {
;     ...
;             const bool last = (t == nt - 2);
;             const char* a1 = cA + (size_t)(t + 1) * kstep;
;             const char* a2 = last ? nA : cA + (size_t)(t + 2) * kstep; const char* b2 = last ? nB : cB + (size_t)(t + 2) * kstep;
;             const char* a3 = a2 + kstep; const char* b3 = b2 + kstep;
;             if (last && has_next) S.a_ready(nxt);
;             if constexpr (SP2) {
;             PG8_LDB(B0, 0, 0); PG8_LDB(B1, 0, 1); PG8_SCHED; PG8_LDA(At, 0, 0); PG8_STAGE(PG8_SA(1, 1), a1 + hstepA, voffA);
;             PG8_WAIT_V(8); PG8_WAIT_L(0); PG8_BAR; PG8_MMA(0, 0, At, B0); PG8_MMA(0, 1, At, B1); PG8_BAR; PG8_SCHED;
;             PG8_LDA(At, 0, 1); PG8_STAGE(PG8_SB(0, 0), b2, voffB); PG8_STAGE(PG8_SB(0, 1), b2 + hstepB, voffB); PG8_STAGE(PG8_SA(0, 0), a2, voffA);
;             PG8_WAIT_V(8); PG8_WAIT_L(0); PG8_BAR; PG8_MMA(1, 0, At, B0); PG8_MMA(1, 1, At, B1); PG8_BAR; PG8_SCHED;
.LBB0_856:
	s_add_u32 s38, s6, 0xfffc0080
	s_addc_u32 s39, s7, -1
	s_add_i32 s61, 0, 0x10000
	s_cmp_eq_u32 s60, 12
	s_cselect_b32 s41, s14, s39
	s_cselect_b32 s40, s15, s38
	s_cselect_b32 s39, s23, s59
	s_cselect_b32 s38, s25, s58
	s_add_i32 s64, 0, 0x14000
	v_add_u32_e32 v144, s61, v184
	v_add_u32_e32 v168, s64, v184
	ds_read_b128 v[132:135], v144
	ds_read_b128 v[136:139], v144 offset:1024
	ds_read_b128 v[140:143], v144 offset:2048
	ds_read_b128 v[144:147], v144 offset:3072
	ds_read_b128 v[148:151], v168
	ds_read_b128 v[152:155], v168 offset:1024
	ds_read_b128 v[164:167], v168 offset:2048
	ds_read_b128 v[168:171], v168 offset:3072
	v_lshl_add_u64 v[180:181], s[6:7], 0, v[160:161]
	s_add_i32 m0, s47, 0xc000
	ds_read_b128 v[172:175], v187
	ds_read_b128 v[176:179], v187 offset:1024
	ds_read_b128 v[188:191], v187 offset:2048
	ds_read_b128 v[192:195], v187 offset:3072
	ds_read_b128 v[196:199], v187 offset:4096
	ds_read_b128 v[200:203], v187 offset:5120
	ds_read_b128 v[204:207], v187 offset:6144
	ds_read_b128 v[208:211], v187 offset:7168
	global_load_lds_dwordx4 v[180:181], off
	v_lshl_add_u64 v[180:181], s[6:7], 0, v[162:163]
	s_add_i32 m0, s47, 0xe000
	s_nop 0
	global_load_lds_dwordx4 v[180:181], off
	s_waitcnt vmcnt(8)
	s_waitcnt lgkmcnt(0)
	s_barrier
	s_setprio 1
	s_waitcnt lgkmcnt(0)
	v_mfma_f32_16x16x32_bf16 v[128:131], v[132:135], v[172:175], v[128:131]
	v_mfma_f32_16x16x32_bf16 v[124:127], v[140:143], v[172:175], v[124:127]
	v_mfma_f32_16x16x32_bf16 v[108:111], v[132:135], v[188:191], v[108:111]
	v_mfma_f32_16x16x32_bf16 v[104:107], v[140:143], v[188:191], v[104:107]
	v_mfma_f32_16x16x32_bf16 v[92:95], v[132:135], v[196:199], v[92:95]
	v_mfma_f32_16x16x32_bf16 v[88:91], v[140:143], v[196:199], v[88:91]
	v_mfma_f32_16x16x32_bf16 v[76:79], v[132:135], v[204:207], v[76:79]
	v_mfma_f32_16x16x32_bf16 v[72:75], v[140:143], v[204:207], v[72:75]
	v_mfma_f32_16x16x32_bf16 v[128:131], v[136:139], v[176:179], v[128:131]
	v_mfma_f32_16x16x32_bf16 v[124:127], v[144:147], v[176:179], v[124:127]
	v_mfma_f32_16x16x32_bf16 v[108:111], v[136:139], v[192:195], v[108:111]
	v_mfma_f32_16x16x32_bf16 v[104:107], v[144:147], v[192:195], v[104:107]
	v_mfma_f32_16x16x32_bf16 v[92:95], v[136:139], v[200:203], v[92:95]
	v_mfma_f32_16x16x32_bf16 v[88:91], v[144:147], v[200:203], v[88:91]
	v_mfma_f32_16x16x32_bf16 v[76:79], v[136:139], v[208:211], v[76:79]
	v_mfma_f32_16x16x32_bf16 v[72:75], v[144:147], v[208:211], v[72:75]
	s_setprio 0
	s_setprio 1
	v_mfma_f32_16x16x32_bf16 v[120:123], v[148:151], v[172:175], v[120:123]
	v_mfma_f32_16x16x32_bf16 v[116:119], v[164:167], v[172:175], v[116:119]
	v_mfma_f32_16x16x32_bf16 v[100:103], v[148:151], v[188:191], v[100:103]
	v_mfma_f32_16x16x32_bf16 v[96:99], v[164:167], v[188:191], v[96:99]
	v_mfma_f32_16x16x32_bf16 v[84:87], v[148:151], v[196:199], v[84:87]
	v_mfma_f32_16x16x32_bf16 v[80:83], v[164:167], v[196:199], v[80:83]
	v_mfma_f32_16x16x32_bf16 v[68:71], v[148:151], v[204:207], v[68:71]
	v_mfma_f32_16x16x32_bf16 v[64:67], v[164:167], v[204:207], v[64:67]
	v_mfma_f32_16x16x32_bf16 v[120:123], v[152:155], v[176:179], v[120:123]
	v_mfma_f32_16x16x32_bf16 v[116:119], v[168:171], v[176:179], v[116:119]
	v_mfma_f32_16x16x32_bf16 v[100:103], v[152:155], v[192:195], v[100:103]
	v_mfma_f32_16x16x32_bf16 v[96:99], v[168:171], v[192:195], v[96:99]
	v_mfma_f32_16x16x32_bf16 v[84:87], v[152:155], v[200:203], v[84:87]
	v_mfma_f32_16x16x32_bf16 v[80:83], v[168:171], v[200:203], v[80:83]
	v_mfma_f32_16x16x32_bf16 v[68:71], v[152:155], v[208:211], v[68:71]
	v_mfma_f32_16x16x32_bf16 v[64:67], v[168:171], v[208:211], v[64:67]
	s_setprio 0
	s_barrier
	s_add_i32 s61, s61, s42
	v_lshl_add_u64 v[180:181], s[38:39], 0, v[114:115]
	s_mov_b32 m0, s61
	ds_read_b128 v[172:175], v187 offset:16384
	ds_read_b128 v[176:179], v187 offset:17408
	ds_read_b128 v[188:191], v187 offset:18432
	ds_read_b128 v[192:195], v187 offset:19456
	ds_read_b128 v[196:199], v187 offset:20480
	ds_read_b128 v[200:203], v187 offset:21504
	ds_read_b128 v[204:207], v187 offset:22528
	ds_read_b128 v[208:211], v187 offset:23552
	global_load_lds_dwordx4 v[180:181], off
	s_add_i32 m0, s61, 0x2000
	s_add_u32 s62, s38, 0x40000
	v_lshl_add_u64 v[212:213], s[38:39], 0, v[158:159]
	s_addc_u32 s63, s39, 0
	s_add_i32 s61, s64, s42
	global_load_lds_dwordx4 v[212:213], off
	v_lshl_add_u64 v[214:215], s[62:63], 0, v[114:115]
	s_mov_b32 m0, s61
	v_lshl_add_u64 v[216:217], s[40:41], 0, v[156:157]
	global_load_lds_dwordx4 v[214:215], off
	v_lshl_add_u64 v[214:215], s[62:63], 0, v[158:159]
	s_add_i32 m0, s61, 0x2000
	s_nop 0
	global_load_lds_dwordx4 v[214:215], off
	v_lshl_add_u64 v[214:215], s[40:41], 0, v[112:113]
	s_mov_b32 m0, s47
	s_nop 0
	global_load_lds_dwordx4 v[214:215], off
	s_mov_b32 m0, s50
	s_nop 0
	global_load_lds_dwordx4 v[216:217], off
	s_waitcnt vmcnt(8)
	s_waitcnt lgkmcnt(0)
	s_barrier
; #define PG8_STAGE(bufoff, gbase, voff) do { _Pragma("unroll") for (int _i = 0; _i < 2; ++_i) \
;         __builtin_amdgcn_global_load_lds((const unsigned*)((const char*)(gbase) + (voff)[_i]), (PG8_LAS unsigned*)(lds + (bufoff) + ldsw + _i * 8192), 16, 0, 0); } while (0)
; #define PG8_LDA(dst, b, h) do { _Pragma("unroll") for (int m = 0; m < 4; ++m) _Pragma("unroll") for (int k = 0; k < 2; ++k) dst[m][k] = *(const PG8_LAS bf16x8*)(lds + PG8_SA(b, h) + aoff + m * 2048 + k * 1024); } while (0)
; #define PG8_LDB(dst, b, h) do { _Pragma("unroll") for (int n = 0; n < 2; ++n) _Pragma("unroll") for (int k = 0; k < 2; ++k) dst[n][k] = *(const PG8_LAS bf16x8*)(lds + PG8_SB(b, h) + boff + n * 2048 + k * 1024); } while (0)
; #define PG8_MMA(ai, bj, At, Bt) do { __builtin_amdgcn_s_setprio(1); _Pragma("unroll") for (int m = 0; m < 4; ++m) _Pragma("unroll") for (int n = 0; n < 2; ++n) _Pragma("unroll") for (int k = 0; k < 2; ++k) \
;         acc[ai][bj][m][n] = __builtin_amdgcn_mfma_f32_16x16x32_bf16(Bt[n][k], At[m][k], acc[ai][bj][m][n], 0, 0, 0); __builtin_amdgcn_s_setprio(0); } while (0)
; #define PG8_WAIT_V(n) asm volatile("s_waitcnt vmcnt(" #n ")" ::: "memory")
; #define PG8_WAIT_L(n) asm volatile("s_waitcnt lgkmcnt(" #n ")" ::: "memory")
; #define PG8_BAR __builtin_amdgcn_s_barrier()
; #define PG8_SCHED __builtin_amdgcn_sched_barrier(0)
; template <class Epi, class Sched, bool ALIGN_EPI = false, bool SP2 = false>
; __device__ __forceinline__ void gemm_phase(PG8_LAS unsigned char* lds, const Gemm g, const Sched& S, const Epi& E, const int tid_in) {
;     ...
;             PG8_WAIT_V(8); PG8_WAIT_L(0); PG8_BAR; PG8_MMA(1, 0, At, B0); PG8_MMA(1, 1, At, B1); PG8_BAR; PG8_SCHED;
;             PG8_LDB(B0, 1, 0); PG8_LDB(B1, 1, 1); PG8_SCHED; PG8_LDA(At, 1, 0); PG8_STAGE(PG8_SA(0, 1), a2 + hstepA, voffA);
;             PG8_WAIT_V(8); PG8_WAIT_L(0); PG8_BAR; PG8_MMA(0, 0, At, B0); PG8_MMA(0, 1, At, B1); PG8_BAR; PG8_SCHED;
	s_setprio 1
	s_waitcnt lgkmcnt(0)
	v_mfma_f32_16x16x32_bf16 v[60:63], v[132:135], v[172:175], v[60:63]
	v_mfma_f32_16x16x32_bf16 v[56:59], v[140:143], v[172:175], v[56:59]
	v_mfma_f32_16x16x32_bf16 v[44:47], v[132:135], v[188:191], v[44:47]
	v_mfma_f32_16x16x32_bf16 v[40:43], v[140:143], v[188:191], v[40:43]
	v_mfma_f32_16x16x32_bf16 v[28:31], v[132:135], v[196:199], v[28:31]
	v_mfma_f32_16x16x32_bf16 v[24:27], v[140:143], v[196:199], v[24:27]
	v_mfma_f32_16x16x32_bf16 v[12:15], v[132:135], v[204:207], v[12:15]
	v_mfma_f32_16x16x32_bf16 v[8:11], v[140:143], v[204:207], v[8:11]
	v_mfma_f32_16x16x32_bf16 v[60:63], v[136:139], v[176:179], v[60:63]
	v_mfma_f32_16x16x32_bf16 v[56:59], v[144:147], v[176:179], v[56:59]
	v_mfma_f32_16x16x32_bf16 v[44:47], v[136:139], v[192:195], v[44:47]
	v_mfma_f32_16x16x32_bf16 v[40:43], v[144:147], v[192:195], v[40:43]
	v_mfma_f32_16x16x32_bf16 v[28:31], v[136:139], v[200:203], v[28:31]
	v_mfma_f32_16x16x32_bf16 v[24:27], v[144:147], v[200:203], v[24:27]
	v_mfma_f32_16x16x32_bf16 v[12:15], v[136:139], v[208:211], v[12:15]
	v_mfma_f32_16x16x32_bf16 v[8:11], v[144:147], v[208:211], v[8:11]
	s_setprio 0
	s_setprio 1
	v_mfma_f32_16x16x32_bf16 v[52:55], v[148:151], v[172:175], v[52:55]
	v_mfma_f32_16x16x32_bf16 v[48:51], v[164:167], v[172:175], v[48:51]
	v_mfma_f32_16x16x32_bf16 v[36:39], v[148:151], v[188:191], v[36:39]
	v_mfma_f32_16x16x32_bf16 v[32:35], v[164:167], v[188:191], v[32:35]
	v_mfma_f32_16x16x32_bf16 v[20:23], v[148:151], v[196:199], v[20:23]
	v_mfma_f32_16x16x32_bf16 v[16:19], v[164:167], v[196:199], v[16:19]
	v_mfma_f32_16x16x32_bf16 v[4:7], v[148:151], v[204:207], v[4:7]
	v_mfma_f32_16x16x32_bf16 v[0:3], v[164:167], v[204:207], v[0:3]
	v_mfma_f32_16x16x32_bf16 v[52:55], v[152:155], v[176:179], v[52:55]
	v_mfma_f32_16x16x32_bf16 v[48:51], v[168:171], v[176:179], v[48:51]
	v_mfma_f32_16x16x32_bf16 v[36:39], v[152:155], v[192:195], v[36:39]
	v_mfma_f32_16x16x32_bf16 v[32:35], v[168:171], v[192:195], v[32:35]
	v_mfma_f32_16x16x32_bf16 v[20:23], v[152:155], v[200:203], v[20:23]
	v_mfma_f32_16x16x32_bf16 v[16:19], v[168:171], v[200:203], v[16:19]
	v_mfma_f32_16x16x32_bf16 v[4:7], v[152:155], v[208:211], v[4:7]
	v_mfma_f32_16x16x32_bf16 v[0:3], v[168:171], v[208:211], v[0:3]
	s_setprio 0
	s_barrier
	s_add_i32 s61, 0, 0x18000
	s_add_i32 s62, 0, 0x1c000
	v_add_u32_e32 v144, s61, v184
	v_add_u32_e32 v168, s62, v184
	ds_read_b128 v[132:135], v144
	ds_read_b128 v[136:139], v144 offset:1024
	ds_read_b128 v[140:143], v144 offset:2048
	ds_read_b128 v[144:147], v144 offset:3072
	ds_read_b128 v[148:151], v168
	ds_read_b128 v[152:155], v168 offset:1024
	ds_read_b128 v[164:167], v168 offset:2048
	ds_read_b128 v[168:171], v168 offset:3072
	s_add_u32 s40, s40, 0x40000
	s_addc_u32 s41, s41, 0
	s_mov_b32 m0, s51
	v_lshl_add_u64 v[218:219], s[40:41], 0, v[112:113]
	ds_read_b128 v[172:175], v187 offset:32768
	ds_read_b128 v[176:179], v187 offset:33792
	ds_read_b128 v[188:191], v187 offset:34816
	ds_read_b128 v[192:195], v187 offset:35840
	ds_read_b128 v[196:199], v187 offset:36864
	ds_read_b128 v[200:203], v187 offset:37888
	ds_read_b128 v[204:207], v187 offset:38912
	ds_read_b128 v[208:211], v187 offset:39936
	global_load_lds_dwordx4 v[218:219], off
	v_lshl_add_u64 v[218:219], s[40:41], 0, v[156:157]
	s_mov_b32 m0, s52
	s_nop 0
	global_load_lds_dwordx4 v[218:219], off
	s_waitcnt vmcnt(8)
	s_waitcnt lgkmcnt(0)
	s_barrier
	s_setprio 1
	s_waitcnt lgkmcnt(0)
	v_mfma_f32_16x16x32_bf16 v[128:131], v[132:135], v[172:175], v[128:131]
	v_mfma_f32_16x16x32_bf16 v[124:127], v[140:143], v[172:175], v[124:127]
	v_mfma_f32_16x16x32_bf16 v[108:111], v[132:135], v[188:191], v[108:111]
	v_mfma_f32_16x16x32_bf16 v[104:107], v[140:143], v[188:191], v[104:107]
	v_mfma_f32_16x16x32_bf16 v[92:95], v[132:135], v[196:199], v[92:95]
	v_mfma_f32_16x16x32_bf16 v[88:91], v[140:143], v[196:199], v[88:91]
	v_mfma_f32_16x16x32_bf16 v[76:79], v[132:135], v[204:207], v[76:79]
	v_mfma_f32_16x16x32_bf16 v[72:75], v[140:143], v[204:207], v[72:75]
	v_mfma_f32_16x16x32_bf16 v[128:131], v[136:139], v[176:179], v[128:131]
	v_mfma_f32_16x16x32_bf16 v[124:127], v[144:147], v[176:179], v[124:127]
	v_mfma_f32_16x16x32_bf16 v[108:111], v[136:139], v[192:195], v[108:111]
	v_mfma_f32_16x16x32_bf16 v[104:107], v[144:147], v[192:195], v[104:107]
	v_mfma_f32_16x16x32_bf16 v[92:95], v[136:139], v[200:203], v[92:95]
	v_mfma_f32_16x16x32_bf16 v[88:91], v[144:147], v[200:203], v[88:91]
	v_mfma_f32_16x16x32_bf16 v[76:79], v[136:139], v[208:211], v[76:79]
	v_mfma_f32_16x16x32_bf16 v[72:75], v[144:147], v[208:211], v[72:75]
	s_setprio 0
	s_setprio 1
	v_mfma_f32_16x16x32_bf16 v[120:123], v[148:151], v[172:175], v[120:123]
	v_mfma_f32_16x16x32_bf16 v[116:119], v[164:167], v[172:175], v[116:119]
	v_mfma_f32_16x16x32_bf16 v[100:103], v[148:151], v[188:191], v[100:103]
	v_mfma_f32_16x16x32_bf16 v[96:99], v[164:167], v[188:191], v[96:99]
	v_mfma_f32_16x16x32_bf16 v[84:87], v[148:151], v[196:199], v[84:87]
	v_mfma_f32_16x16x32_bf16 v[80:83], v[164:167], v[196:199], v[80:83]
	v_mfma_f32_16x16x32_bf16 v[68:71], v[148:151], v[204:207], v[68:71]
	v_mfma_f32_16x16x32_bf16 v[64:67], v[164:167], v[204:207], v[64:67]
	v_mfma_f32_16x16x32_bf16 v[120:123], v[152:155], v[176:179], v[120:123]
	v_mfma_f32_16x16x32_bf16 v[116:119], v[168:171], v[176:179], v[116:119]
	v_mfma_f32_16x16x32_bf16 v[100:103], v[152:155], v[192:195], v[100:103]
	v_mfma_f32_16x16x32_bf16 v[96:99], v[168:171], v[192:195], v[96:99]
	v_mfma_f32_16x16x32_bf16 v[84:87], v[152:155], v[200:203], v[84:87]
	v_mfma_f32_16x16x32_bf16 v[80:83], v[168:171], v[200:203], v[80:83]
	v_mfma_f32_16x16x32_bf16 v[68:71], v[152:155], v[208:211], v[68:71]
	v_mfma_f32_16x16x32_bf16 v[64:67], v[168:171], v[208:211], v[64:67]
	s_setprio 0
	s_barrier
; #define PG8_STAGE(bufoff, gbase, voff) do { _Pragma("unroll") for (int _i = 0; _i < 2; ++_i) \
;         __builtin_amdgcn_global_load_lds((const unsigned*)((const char*)(gbase) + (voff)[_i]), (PG8_LAS unsigned*)(lds + (bufoff) + ldsw + _i * 8192), 16, 0, 0); } while (0)
; #define PG8_LDA(dst, b, h) do { _Pragma("unroll") for (int m = 0; m < 4; ++m) _Pragma("unroll") for (int k = 0; k < 2; ++k) dst[m][k] = *(const PG8_LAS bf16x8*)(lds + PG8_SA(b, h) + aoff + m * 2048 + k * 1024); } while (0)
; #define PG8_MMA(ai, bj, At, Bt) do { __builtin_amdgcn_s_setprio(1); _Pragma("unroll") for (int m = 0; m < 4; ++m) _Pragma("unroll") for (int n = 0; n < 2; ++n) _Pragma("unroll") for (int k = 0; k < 2; ++k) \
;         acc[ai][bj][m][n] = __builtin_amdgcn_mfma_f32_16x16x32_bf16(Bt[n][k], At[m][k], acc[ai][bj][m][n], 0, 0, 0); __builtin_amdgcn_s_setprio(0); } while (0)
; #define PG8_WAIT_V(n) asm volatile("s_waitcnt vmcnt(" #n ")" ::: "memory")
; #define PG8_WAIT_L(n) asm volatile("s_waitcnt lgkmcnt(" #n ")" ::: "memory")
; #define PG8_BAR __builtin_amdgcn_s_barrier()
; #define PG8_SCHED __builtin_amdgcn_sched_barrier(0)
; template <class Epi, class Sched, bool ALIGN_EPI = false, bool SP2 = false>
; __device__ __forceinline__ void gemm_phase(PG8_LAS unsigned char* lds, const Gemm g, const Sched& S, const Epi& E, const int tid_in) {
;     ...
;         for (int t = 0; t < nt; t += 2) {
;     ...
;             PG8_LDA(At, 1, 1); PG8_STAGE(PG8_SB(1, 0), b3, voffB); PG8_STAGE(PG8_SB(1, 1), b3 + hstepB, voffB); PG8_STAGE(PG8_SA(1, 0), a3, voffA);
;             PG8_WAIT_V(8); PG8_WAIT_L(0); PG8_BAR; PG8_MMA(1, 0, At, B0); PG8_MMA(1, 1, At, B1); PG8_BAR; PG8_SCHED;
	s_add_i32 s40, s61, s42
	v_lshl_add_u64 v[180:181], v[180:181], 0, s[10:11]
	s_mov_b32 m0, s40
	ds_read_b128 v[172:175], v187 offset:49152
	ds_read_b128 v[176:179], v187 offset:50176
	ds_read_b128 v[188:191], v187 offset:51200
	ds_read_b128 v[192:195], v187 offset:52224
	ds_read_b128 v[196:199], v187 offset:53248
	ds_read_b128 v[200:203], v187 offset:54272
	ds_read_b128 v[204:207], v187 offset:55296
	ds_read_b128 v[208:211], v187 offset:56320
	global_load_lds_dwordx4 v[180:181], off
	s_add_i32 m0, s40, 0x2000
	s_add_u32 s38, s38, 0x40080
	v_lshl_add_u64 v[180:181], v[212:213], 0, s[10:11]
	s_addc_u32 s39, s39, 0
	s_add_i32 s40, s62, s42
	global_load_lds_dwordx4 v[180:181], off
	v_lshl_add_u64 v[180:181], s[38:39], 0, v[114:115]
	s_mov_b32 m0, s40
	s_nop 0
	global_load_lds_dwordx4 v[180:181], off
	v_lshl_add_u64 v[180:181], s[38:39], 0, v[158:159]
	s_add_i32 m0, s40, 0x2000
	s_nop 0
	global_load_lds_dwordx4 v[180:181], off
	v_lshl_add_u64 v[180:181], v[214:215], 0, s[10:11]
	s_mov_b32 m0, s53
	s_nop 0
	global_load_lds_dwordx4 v[180:181], off
	v_lshl_add_u64 v[180:181], v[216:217], 0, s[10:11]
	s_mov_b32 m0, s54
	s_nop 0
	global_load_lds_dwordx4 v[180:181], off
	s_waitcnt vmcnt(8)
	s_waitcnt lgkmcnt(0)
	s_barrier
	s_setprio 1
	s_waitcnt lgkmcnt(0)
	v_mfma_f32_16x16x32_bf16 v[60:63], v[132:135], v[172:175], v[60:63]
	v_mfma_f32_16x16x32_bf16 v[56:59], v[140:143], v[172:175], v[56:59]
	v_mfma_f32_16x16x32_bf16 v[44:47], v[132:135], v[188:191], v[44:47]
	v_mfma_f32_16x16x32_bf16 v[40:43], v[140:143], v[188:191], v[40:43]
	v_mfma_f32_16x16x32_bf16 v[28:31], v[132:135], v[196:199], v[28:31]
	v_mfma_f32_16x16x32_bf16 v[24:27], v[140:143], v[196:199], v[24:27]
	v_mfma_f32_16x16x32_bf16 v[12:15], v[132:135], v[204:207], v[12:15]
	v_mfma_f32_16x16x32_bf16 v[8:11], v[140:143], v[204:207], v[8:11]
	v_mfma_f32_16x16x32_bf16 v[60:63], v[136:139], v[176:179], v[60:63]
	v_mfma_f32_16x16x32_bf16 v[56:59], v[144:147], v[176:179], v[56:59]
	v_mfma_f32_16x16x32_bf16 v[44:47], v[136:139], v[192:195], v[44:47]
	v_mfma_f32_16x16x32_bf16 v[40:43], v[144:147], v[192:195], v[40:43]
	v_mfma_f32_16x16x32_bf16 v[28:31], v[136:139], v[200:203], v[28:31]
	v_mfma_f32_16x16x32_bf16 v[24:27], v[144:147], v[200:203], v[24:27]
	v_mfma_f32_16x16x32_bf16 v[12:15], v[136:139], v[208:211], v[12:15]
	v_mfma_f32_16x16x32_bf16 v[8:11], v[144:147], v[208:211], v[8:11]
	s_setprio 0
	s_setprio 1
	v_mfma_f32_16x16x32_bf16 v[52:55], v[148:151], v[172:175], v[52:55]
	v_mfma_f32_16x16x32_bf16 v[48:51], v[164:167], v[172:175], v[48:51]
	v_mfma_f32_16x16x32_bf16 v[36:39], v[148:151], v[188:191], v[36:39]
	v_mfma_f32_16x16x32_bf16 v[32:35], v[164:167], v[188:191], v[32:35]
	v_mfma_f32_16x16x32_bf16 v[20:23], v[148:151], v[196:199], v[20:23]
	v_mfma_f32_16x16x32_bf16 v[16:19], v[164:167], v[196:199], v[16:19]
	v_mfma_f32_16x16x32_bf16 v[4:7], v[148:151], v[204:207], v[4:7]
	v_mfma_f32_16x16x32_bf16 v[0:3], v[164:167], v[204:207], v[0:3]
	v_mfma_f32_16x16x32_bf16 v[52:55], v[152:155], v[176:179], v[52:55]
	v_mfma_f32_16x16x32_bf16 v[48:51], v[168:171], v[176:179], v[48:51]
	v_mfma_f32_16x16x32_bf16 v[36:39], v[152:155], v[192:195], v[36:39]
	v_mfma_f32_16x16x32_bf16 v[32:35], v[168:171], v[192:195], v[32:35]
	v_mfma_f32_16x16x32_bf16 v[20:23], v[152:155], v[200:203], v[20:23]
	v_mfma_f32_16x16x32_bf16 v[16:19], v[168:171], v[200:203], v[16:19]
	v_mfma_f32_16x16x32_bf16 v[4:7], v[152:155], v[208:211], v[4:7]
	v_mfma_f32_16x16x32_bf16 v[0:3], v[168:171], v[208:211], v[0:3]
	s_setprio 0
	s_add_i32 s60, s60, 2
	s_add_u32 s6, s6, 0x100
	s_addc_u32 s7, s7, 0
	s_add_u32 s58, s58, 0x100
	s_addc_u32 s59, s59, 0
	s_cmp_gt_u32 s60, 13
	s_barrier
	s_cbranch_scc0 .LBB0_856
	s_and_b64 vcc, exec, s[20:21]
	s_cbranch_vccz .LBB0_859
	s_barrier

; #define PG8_MMA(ai, bj, At, Bt) do { __builtin_amdgcn_s_setprio(1); _Pragma("unroll") for (int m = 0; m < 4; ++m) _Pragma("unroll") for (int n = 0; n < 2; ++n) _Pragma("unroll") for (int k = 0; k < 2; ++k) \
;         acc[ai][bj][m][n] = __builtin_amdgcn_mfma_f32_16x16x32_bf16(Bt[n][k], At[m][k], acc[ai][bj][m][n], 0, 0, 0); __builtin_amdgcn_s_setprio(0); } while (0)
; #define PG8_WAIT_V(n) asm volatile("s_waitcnt vmcnt(" #n ")" ::: "memory")
; #define PG8_WAIT_L(n) asm volatile("s_waitcnt lgkmcnt(" #n ")" ::: "memory")
; #define PG8_BAR __builtin_amdgcn_s_barrier()
; #define PG8_SCHED __builtin_amdgcn_sched_barrier(0)
; template <class Epi, class Sched, bool ALIGN_EPI = false, bool SP2 = false>
; __device__ __forceinline__ void gemm_phase(PG8_LAS unsigned char* lds, const Gemm g, const Sched& S, const Epi& E, const int tid_in) {
;     ...
;         for (int t = 0; t < nt; t += 2) {
;     ...
;             PG8_WAIT_V(8); PG8_WAIT_L(0); PG8_BAR; PG8_MMA(1, 0, At, B0); PG8_MMA(1, 1, At, B1); PG8_BAR; PG8_SCHED;
.Ltl_down_15_j:
	s_waitcnt vmcnt(8)
	s_waitcnt lgkmcnt(0)
	s_barrier
	s_setprio 1
	s_waitcnt lgkmcnt(0)
	v_mfma_f32_16x16x32_bf16 v[64:67], v[144:147], v[184:187], v[64:67]
	v_mfma_f32_16x16x32_bf16 v[68:71], v[160:163], v[184:187], v[68:71]
	v_mfma_f32_16x16x32_bf16 v[80:83], v[144:147], v[192:195], v[80:83]
	v_mfma_f32_16x16x32_bf16 v[84:87], v[160:163], v[192:195], v[84:87]
	v_mfma_f32_16x16x32_bf16 v[96:99], v[144:147], v[200:203], v[96:99]
	v_mfma_f32_16x16x32_bf16 v[100:103], v[160:163], v[200:203], v[100:103]
	v_mfma_f32_16x16x32_bf16 v[116:119], v[144:147], v[208:211], v[116:119]
	v_mfma_f32_16x16x32_bf16 v[120:123], v[160:163], v[208:211], v[120:123]
	v_mfma_f32_16x16x32_bf16 v[64:67], v[156:159], v[188:191], v[64:67]
	v_mfma_f32_16x16x32_bf16 v[68:71], v[164:167], v[188:191], v[68:71]
	v_mfma_f32_16x16x32_bf16 v[80:83], v[156:159], v[196:199], v[80:83]
	v_mfma_f32_16x16x32_bf16 v[84:87], v[164:167], v[196:199], v[84:87]
	v_mfma_f32_16x16x32_bf16 v[96:99], v[156:159], v[204:207], v[96:99]
	v_mfma_f32_16x16x32_bf16 v[100:103], v[164:167], v[204:207], v[100:103]
	v_mfma_f32_16x16x32_bf16 v[116:119], v[156:159], v[212:215], v[116:119]
	v_mfma_f32_16x16x32_bf16 v[120:123], v[164:167], v[212:215], v[120:123]
	s_setprio 0
	s_setprio 1
	v_mfma_f32_16x16x32_bf16 v[72:75], v[168:171], v[184:187], v[72:75]
	v_mfma_f32_16x16x32_bf16 v[76:79], v[176:179], v[184:187], v[76:79]
	v_mfma_f32_16x16x32_bf16 v[88:91], v[168:171], v[192:195], v[88:91]
	v_mfma_f32_16x16x32_bf16 v[92:95], v[176:179], v[192:195], v[92:95]
	v_mfma_f32_16x16x32_bf16 v[104:107], v[168:171], v[200:203], v[104:107]
	v_mfma_f32_16x16x32_bf16 v[108:111], v[176:179], v[200:203], v[108:111]
	v_mfma_f32_16x16x32_bf16 v[124:127], v[168:171], v[208:211], v[124:127]
	v_mfma_f32_16x16x32_bf16 v[128:131], v[176:179], v[208:211], v[128:131]
	v_mfma_f32_16x16x32_bf16 v[72:75], v[172:175], v[188:191], v[72:75]
	v_mfma_f32_16x16x32_bf16 v[76:79], v[180:183], v[188:191], v[76:79]
	v_mfma_f32_16x16x32_bf16 v[88:91], v[172:175], v[196:199], v[88:91]
	v_mfma_f32_16x16x32_bf16 v[92:95], v[180:183], v[196:199], v[92:95]
	v_mfma_f32_16x16x32_bf16 v[104:107], v[172:175], v[204:207], v[104:107]
	v_mfma_f32_16x16x32_bf16 v[108:111], v[180:183], v[204:207], v[108:111]
	v_mfma_f32_16x16x32_bf16 v[124:127], v[172:175], v[212:215], v[124:127]
	v_mfma_f32_16x16x32_bf16 v[128:131], v[180:183], v[212:215], v[128:131]
	s_setprio 0
	s_add_i32 s53, s53, 2
	s_add_u32 s40, s40, 0x100
	s_addc_u32 s41, s41, 0
	s_cmp_gt_u32 s53, 61
	s_barrier
	s_cbranch_scc0 .LBB0_974
	s_and_b64 vcc, exec, s[24:25]
	s_cbranch_vccz .LBB0_977
	s_barrier
